# up-GEMM A rows staged in permuted order (token 4*fr+m) so conv neighbours are in-lane; DPP ops per unit 448 to 64
# speedup vs baseline: 1.0146x; 1.0146x over previous
.LBB0_818:
	s_add_u32 s33, s70, 0xa00000
	s_mov_b64 s[2:3], s[82:83]
	s_addc_u32 s82, s71, 0
	s_cmpk_lt_i32 s84, 0x2c0
	s_cselect_b64 s[4:5], -1, 0
	s_ashr_i32 s85, s84, 31
	s_lshr_b32 s0, s85, 29
	s_add_i32 s0, s84, s0
	s_ashr_i32 s1, s0, 3
	s_and_b32 s0, s0, -8
	s_sub_i32 s0, s84, s0
	s_cmp_lt_i32 s0, 0
	v_writelane_b32 v254, s1, 61
	s_cselect_b64 s[6:7], -1, 0
	v_writelane_b32 v254, s6, 62
	s_cmp_gt_i32 s0, -1
	s_mov_b32 s18, s2
	v_writelane_b32 v254, s7, 63
	v_writelane_b32 v254, s0, 51
	s_cselect_b64 s[0:1], -1, 0
	s_ashr_i32 s19, s2, 31
	v_writelane_b32 v255, s0, 0
	s_cmpk_eq_i32 s2, 0x100
	v_cmp_eq_u32_e64 s[2:3], 0, v230
	v_writelane_b32 v255, s1, 1
	s_cselect_b64 s[0:1], -1, 0
	s_cmpk_gt_u32 s84, 0xbf
	s_cselect_b64 s[6:7], -1, 0
	s_and_b64 s[8:9], s[6:7], s[0:1]
	s_lshl_b32 s1, s84, 3
	s_add_i32 s83, s1, 0xfffffa00
	s_cmp_gt_i32 s72, 7
	v_writelane_b32 v254, s2, 59
	s_cselect_b64 s[6:7], -1, 0
	s_cmp_lt_i32 s73, 8
	v_cndmask_b32_e64 v0, 0, 1, s[4:5]
	v_writelane_b32 v254, s3, 60
	s_cselect_b64 s[12:13], -1, 0
	v_cmp_ne_u32_e64 s[2:3], 1, v0
	s_or_b64 s[6:7], s[6:7], s[12:13]
	s_and_b64 vcc, exec, s[6:7]
	v_writelane_b32 v255, s2, 2
	s_nop 1
	v_writelane_b32 v255, s3, 3
	s_cbranch_vccnz .LBB0_899
	v_readlane_b32 s2, v255, 2
	v_mov_b32_e32 v14, v230
	v_readlane_b32 s3, v255, 3
	s_and_b64 vcc, exec, s[2:3]
	v_readfirstlane_b32 s5, v14
	s_cbranch_vccnz .LBB0_834
	v_lshlrev_b32_e32 v0, 4, v14
	s_waitcnt lgkmcnt(0)
	v_add_u32_e32 v1, 0x2000, v0
	v_ashrrev_i32_e32 v2, 31, v1
	v_lshrrev_b32_e32 v2, 22, v2
	v_add_u32_e32 v2, v1, v2
	v_ashrrev_i32_e32 v8, 10, v2
	v_mul_i32_i24_e32 v2, 0x400, v8
	v_sub_u32_e32 v1, v1, v2
	v_lshrrev_b32_e32 v2, 4, v1
	v_bitop3_b32 v1, v2, v1, 32 bitop3:0x6c
	v_ashrrev_i32_e32 v2, 31, v1
	v_lshrrev_b32_e32 v2, 26, v2
	v_add_u32_e32 v2, v1, v2
	v_lshlrev_b32_e32 v3, 3, v8
	v_ashrrev_i32_e32 v9, 6, v2
	v_and_b32_e32 v3, -16, v3
	v_add_u32_e32 v3, v9, v3
	v_and_b32_e32 v4, 3, v9
	s_mov_b32 s4, 0x1fffe0
	v_lshrrev_b32_e32 v5, 2, v3
	v_lshlrev_b32_e32 v6, 1, v3
	v_and_b32_e32 v2, 0xc0, v2
	v_and_or_b32 v4, v3, s4, v4
	v_and_b32_e32 v5, 4, v5
	v_and_b32_e32 v6, 24, v6
	v_sub_u32_e32 v1, v1, v2
	v_mov_b32_e32 v2, 1
	v_or3_b32 v4, v4, v5, v6
	v_lshlrev_b32_e32 v5, 5, v8
	v_ashrrev_i16_sdwa v1, v2, sext(v1) dst_sel:DWORD dst_unused:UNUSED_PAD src0_sel:DWORD src1_sel:BYTE_0
	v_and_b32_e32 v5, 32, v5
	v_bfe_i32 v10, v1, 0, 16
	v_add_lshl_u32 v1, v5, v10, 1
	v_lshl_add_u32 v144, v4, 11, v1
	v_lshl_add_u32 v146, v3, 11, v1
	v_lshrrev_b32_e32 v248, 11, v146
	v_and_b32_e32 v249, 0x7ff, v146
	v_and_b32_e32 v250, 15, v248
	v_lshlrev_b32_e32 v250, 2, v250
	v_bfe_u32 v251, v248, 4, 2
	v_and_or_b32 v248, v248, 64, v250
	v_or_b32_e32 v248, v248, v251
	v_lshl_or_b32 v146, v248, 11, v249
	v_bfe_i32 v1, v14, 27, 1
	v_lshrrev_b32_e32 v1, 22, v1
	v_add_u32_e32 v1, v0, v1
	v_and_b32_e32 v1, 0xfffffc00, v1
	v_sub_u32_e32 v0, v0, v1
	v_lshrrev_b32_e32 v1, 4, v0
	v_ashrrev_i32_e32 v3, 31, v14
	v_bitop3_b32 v0, v1, v0, 32 bitop3:0x6c
	v_lshrrev_b32_e32 v3, 26, v3
	v_ashrrev_i32_e32 v1, 31, v0
	v_add_u32_e32 v3, v14, v3
	s_add_u32 s0, s70, 0x3b00000
	v_lshrrev_b32_e32 v1, 26, v1
	v_ashrrev_i32_e32 v12, 6, v3
	s_addc_u32 s20, s71, 0
	s_ashr_i32 s6, s5, 6
	v_add_u32_e32 v1, v0, v1
	v_lshlrev_b32_e32 v3, 3, v12
	v_readlane_b32 s2, v254, 62
	s_ashr_i32 s7, s5, 8
	s_lshl_b32 s21, s6, 10
	v_ashrrev_i32_e32 v11, 6, v1
	v_and_b32_e32 v3, -16, v3
	v_readlane_b32 s3, v254, 63
	v_add_u32_e32 v3, v11, v3
	v_and_b32_e32 v4, 3, v11
	s_movk_i32 s30, 0x59
	s_and_b64 s[12:13], s[2:3], exec
	v_and_or_b32 v4, v3, s4, v4
	s_cselect_b32 s4, s30, 0x58
	v_readlane_b32 s2, v254, 51
	s_mul_i32 s4, s4, s2
	v_readlane_b32 s2, v254, 61
	s_add_i32 s4, s4, s2
	s_mul_hi_i32 s12, s4, 0x2e8ba2e9
	s_lshr_b32 s13, s12, 31
	s_ashr_i32 s12, s12, 5
	s_add_i32 s12, s12, s13
	s_lshl_b32 s13, s12, 3
	s_mulk_i32 s12, 0xb0
	s_sub_i32 s12, s4, s12
	s_bfe_u32 s4, s12, 0x3001c
	s_add_i32 s14, s12, s4
	s_sext_i32_i16 s4, s14
	s_and_b32 s14, s14, 0xfff8
	s_sub_i32 s12, s12, s14
	s_sext_i32_i16 s12, s12
	v_lshrrev_b32_e32 v5, 2, v3
	v_lshlrev_b32_e32 v6, 1, v3
	v_and_b32_e32 v1, 0xc0, v1
	s_lshr_b32 s4, s4, 3
	s_add_i32 s88, s13, s12
	v_and_b32_e32 v5, 4, v5
	v_and_b32_e32 v6, 24, v6
	v_sub_u32_e32 v0, v0, v1
	s_ashr_i32 s89, s88, 31
	s_bfe_i64 s[14:15], s[4:5], 0x100000
	v_or3_b32 v4, v4, v5, v6
	v_lshlrev_b32_e32 v5, 5, v12
	v_ashrrev_i16_sdwa v0, v2, sext(v0) dst_sel:DWORD dst_unused:UNUSED_PAD src0_sel:DWORD src1_sel:BYTE_0
	s_lshl_b64 s[12:13], s[88:89], 19
	s_lshl_b64 s[14:15], s[14:15], 18
	v_and_b32_e32 v5, 32, v5
	v_bfe_i32 v13, v0, 0, 16
	s_add_u32 s92, s33, s14
	v_add_lshl_u32 v0, v5, v13, 1
	s_addc_u32 s93, s82, s15
	s_add_i32 s31, s21, 0
	v_lshl_add_u32 v148, v4, 11, v0
	s_add_i32 m0, s31, 0x10000
	v_lshl_add_u32 v150, v3, 11, v0
	v_lshrrev_b32_e32 v248, 11, v150
	v_and_b32_e32 v249, 0x7ff, v150
	v_and_b32_e32 v250, 15, v248
	v_lshlrev_b32_e32 v250, 2, v250
	v_bfe_u32 v251, v248, 4, 2
	v_and_or_b32 v248, v248, 64, v250
	v_or_b32_e32 v248, v248, v251
	v_lshl_or_b32 v150, v248, 11, v249
	global_load_lds_dwordx4 v148, s[92:93]
	s_add_i32 m0, s31, 0x12000
	s_add_u32 s14, s92, 0x580000
	global_load_lds_dwordx4 v144, s[92:93]
	s_addc_u32 s15, s93, 0
	s_add_i32 m0, s31, 0x14000
	v_mov_b32_e32 v149, 0
	global_load_lds_dwordx4 v148, s[14:15]
	s_add_i32 m0, s31, 0x16000
	s_add_u32 s90, s0, s12
	s_addc_u32 s91, s20, s13
	s_add_i32 s52, s31, 0x2000
	global_load_lds_dwordx4 v144, s[14:15]
	s_mov_b32 m0, s31
	s_add_u32 s12, s90, 0x40000
	global_load_lds_dwordx4 v150, s[90:91]
	s_mov_b32 m0, s52
	s_addc_u32 s13, s91, 0
	s_add_i32 s53, s31, 0x4000
	global_load_lds_dwordx4 v146, s[90:91]
	s_mov_b32 m0, s53
	s_add_i32 s58, s31, 0x6000
	global_load_lds_dwordx4 v150, s[12:13]
	s_mov_b32 m0, s58
	v_mov_b32_e32 v145, v149
	global_load_lds_dwordx4 v146, s[12:13]
	v_mov_b32_e32 v151, v149
	v_mov_b32_e32 v147, v149
	s_cmp_eq_u32 s7, 1
	s_mov_b32 s59, 0
	v_lshl_add_u64 v[6:7], s[92:93], 0, v[148:149]
	v_lshl_add_u64 v[4:5], s[92:93], 0, v[144:145]
	v_lshl_add_u64 v[0:1], s[90:91], 0, v[150:151]
	s_cselect_b64 s[12:13], -1, 0
	s_cmp_lg_u32 s7, 1
	v_lshl_add_u64 v[2:3], s[90:91], 0, v[146:147]
	s_cbranch_scc1 .LBB0_822
	s_barrier
.LBB0_822:
	v_lshrrev_b32_e32 v16, 1, v14
	v_and_b32_e32 v16, 24, v16
	s_add_u32 s14, s70, 0x3b00000
	v_and_b32_e32 v15, 15, v14
	v_lshlrev_b32_e32 v17, 1, v16
	v_lshlrev_b32_e32 v14, 2, v14
	s_sext_i32_i16 s66, s4
	s_addc_u32 s15, s71, 0
	v_lshl_or_b32 v170, s7, 6, v15
	v_lshl_or_b32 v15, v15, 6, v17
	s_lshl_b32 s4, s7, 13
	v_and_b32_e32 v14, 32, v14
	v_bitop3_b32 v17, v15, s4, v14 bitop3:0xde
	s_lshl_b32 s4, s6, 5
	s_mov_b64 s[16:17], 0x80
	s_and_b32 s4, s4, 0x60
	s_add_i32 m0, s31, 0x18000
	v_lshl_add_u64 v[6:7], v[6:7], 0, s[16:17]
	s_lshl_b32 s6, s4, 7
	s_waitcnt vmcnt(2)
	s_barrier
	global_load_lds_dwordx4 v[6:7], off
	v_lshl_add_u64 v[4:5], v[4:5], 0, s[16:17]
	s_add_i32 m0, s31, 0x1a000
	s_add_i32 s60, s31, 0x8000
	s_add_i32 s61, s31, 0xa000
	v_bitop3_b32 v171, v15, s6, v14 bitop3:0xde
	global_load_lds_dwordx4 v[4:5], off
	v_lshl_add_u64 v[0:1], v[0:1], 0, s[16:17]
	s_mov_b32 m0, s60
	s_add_u32 s6, s92, 0x580080
	global_load_lds_dwordx4 v[0:1], off
	v_lshl_add_u64 v[0:1], v[2:3], 0, s[16:17]
	s_mov_b32 m0, s61
	s_addc_u32 s7, s93, 0
	global_load_lds_dwordx4 v[0:1], off
	s_add_i32 m0, s31, 0x1c000
	v_lshl_add_u64 v[0:1], s[6:7], 0, v[148:149]
	global_load_lds_dwordx4 v[0:1], off
	v_lshl_add_u64 v[0:1], s[6:7], 0, v[144:145]
	s_add_i32 m0, s31, 0x1e000
	s_cmpk_lt_u32 s5, 0x100
	global_load_lds_dwordx4 v[0:1], off
	v_lshlrev_b32_e32 v0, 14, v12
	v_and_b32_e32 v0, 0xffff8000, v0
	v_lshl_add_u32 v0, v11, 11, v0
	v_and_b32_e32 v1, 1, v12
	v_lshl_or_b32 v0, v1, 6, v0
	v_lshl_add_u32 v152, v13, 1, v0
	v_lshrrev_b32_e32 v248, 11, v152
	v_and_b32_e32 v249, 0x7ff, v152
	v_and_b32_e32 v250, 15, v248
	v_lshlrev_b32_e32 v250, 2, v250
	v_bfe_u32 v251, v248, 4, 2
	v_and_or_b32 v248, v248, 64, v250
	v_or_b32_e32 v248, v248, v251
	v_lshl_or_b32 v152, v248, 11, v249
	v_lshlrev_b32_e32 v0, 14, v8
	v_and_b32_e32 v0, 0xffff8000, v0
	s_waitcnt vmcnt(6)
	v_lshl_add_u32 v0, v9, 11, v0
	v_and_b32_e32 v1, 1, v8
	s_cselect_b64 s[34:35], -1, 0
	v_lshl_or_b32 v0, v1, 6, v0
	s_add_i32 s62, 0, 0x10000
	s_add_i32 s63, 0, 0x14000
	v_or_b32_e32 v172, s4, v16
	v_mov_b32_e32 v153, v149
	v_lshl_add_u32 v154, v10, 1, v0
	v_lshrrev_b32_e32 v248, 11, v154
	v_and_b32_e32 v249, 0x7ff, v154
	v_and_b32_e32 v250, 15, v248
	v_lshlrev_b32_e32 v250, 2, v250
	v_bfe_u32 v251, v248, 4, 2
	v_and_or_b32 v248, v248, 64, v250
	v_or_b32_e32 v248, v248, v251
	v_lshl_or_b32 v154, v248, 11, v249
	v_mov_b32_e32 v155, v149
	v_mov_b64_e32 v[156:157], 0x2c0
	v_mov_b64_e32 v[158:159], 0x2bf
	v_add_u32_e32 v173, s62, v171
	v_add_u32_e32 v174, s63, v171
	v_add_u32_e32 v175, 0, v17
	v_mov_b32_e32 v176, 0x358637bd
	s_mov_b32 s64, 0x800000
	s_movk_i32 s65, 0x2c00
	s_barrier
	s_branch .LBB0_825

.LBB0_831:
	s_and_b32 s32, s12, 1
	v_readlane_b32 s92, v254, 49
	v_readlane_b32 s93, v254, 50
	s_nop 0
	s_add_i32 s4, s88, -32
	s_ashr_i32 s4, s4, 2
	s_add_i32 s4, s4, 1
	s_cmp_gt_i32 s88, 31
	s_cselect_b32 s4, s4, 0
	s_mul_hi_i32 s5, s4, 0x5800
	s_mulk_i32 s4, 0x5800
	s_add_u32 s4, s92, s4
	s_addc_u32 s5, s93, s5
	v_and_b32_e32 v237, 15, v170
	v_and_b32_e32 v236, 64, v170
	v_lshl_add_u32 v236, v237, 2, v236
	v_mul_u32_u24_e32 v168, 0x1600, v236
	v_lshl_add_u32 v168, v172, 1, v168
	v_lshl_add_u32 v236, s88, 8, v236
	v_lshlrev_b32_e32 v236, 2, v236
	v_lshl_or_b32 v177, s66, 7, v172
	v_lshlrev_b32_e32 v177, 2, v177
	global_load_dwordx4 v[210:213], v236, s[10:11]
	global_load_dwordx4 v[214:217], v236, s[10:11] offset:512
	global_load_dwordx4 v[202:205], v177, s[4:5]
	global_load_dwordx4 v[206:209], v177, s[4:5] offset:16
	v_add_u32_e32 v226, 0x2c00, v177
	global_load_dwordx4 v[218:221], v226, s[4:5]
	global_load_dwordx4 v[222:225], v226, s[4:5] offset:16
	v_readlane_b32 s2, v254, 5
	v_readlane_b32 s3, v254, 6
	v_readlane_b32 s28, v254, 7
	v_readlane_b32 s29, v254, 8
	s_mul_i32 s76, s88, 0x160000
	s_lshl_b32 s67, s66, 8
	s_add_i32 s76, s76, s67
	s_add_i32 s76, s76, 0x9300000
	s_add_u32 s76, s76, s70
	s_addc_u32 s77, s71, 0
	s_mov_b32 s57, 0x20800
	v_lshl_add_u32 v169, v172, 2, s57
	v_cmp_eq_u32_e64 s[78:79], 0, v237
	v_cmp_eq_u32_e64 s[80:81], 15, v237
	v_and_b32_e32 v231, 8, v237
	v_lshlrev_b32_e32 v231, 9, v231
	s_lshl_b32 s67, s32, 10
	v_add3_u32 v231, v231, v169, s67
	global_load_dwordx4 v[116:119], v177, s[2:3]
	v_add_u32_e32 v229, 0x5800, v177
	global_load_dwordx4 v[124:127], v229, s[2:3]
	v_add_u32_e32 v228, 0xb000, v177
	global_load_dwordx4 v[128:131], v228, s[2:3]
	global_load_dwordx4 v[132:135], v177, s[28:29]
	v_add_u32_e32 v228, 0x2c00, v177
	global_load_dwordx4 v[160:163], v228, s[2:3]
	v_add_u32_e32 v229, 0x8400, v177
	global_load_dwordx4 v[164:167], v229, s[2:3]
	v_add_u32_e32 v228, 0xdc00, v177
	global_load_dwordx4 v[178:181], v228, s[2:3]
	v_add_u32_e32 v229, 0x2c00, v177
	global_load_dwordx4 v[182:185], v229, s[28:29]
	s_waitcnt vmcnt(12)
	v_fmamk_f32 v210, v210, 0x3a800000, v176
	v_fmamk_f32 v211, v211, 0x3a800000, v176
	v_fmamk_f32 v212, v212, 0x3a800000, v176
	v_fmamk_f32 v213, v213, 0x3a800000, v176
	v_fmamk_f32 v214, v214, 0x3a800000, v176
	v_fmamk_f32 v215, v215, 0x3a800000, v176
	v_fmamk_f32 v216, v216, 0x3a800000, v176
	v_fmamk_f32 v217, v217, 0x3a800000, v176
	s_mov_b32 s67, 0x800000
	v_mul_f32_e32 v226, 0x4b800000, v210
	v_mul_f32_e32 v227, 0x4b800000, v211
	v_mul_f32_e32 v228, 0x4b800000, v212
	v_mul_f32_e32 v229, 0x4b800000, v213
	v_mul_f32_e32 v232, 0x4b800000, v214
	v_mul_f32_e32 v233, 0x4b800000, v215
	v_mul_f32_e32 v234, 0x4b800000, v216
	v_mul_f32_e32 v235, 0x4b800000, v217
	v_cmp_gt_f32_e32 vcc, s67, v210
	s_nop 1
	v_cndmask_b32_e32 v210, v210, v226, vcc
	v_rsq_f32_e32 v210, v210
	s_nop 0
	v_mul_f32_e32 v226, 0x45800000, v210
	v_cndmask_b32_e32 v210, v210, v226, vcc
	v_cmp_gt_f32_e32 vcc, s67, v211
	s_nop 1
	v_cndmask_b32_e32 v211, v211, v227, vcc
	v_rsq_f32_e32 v211, v211
	s_nop 0
	v_mul_f32_e32 v227, 0x45800000, v211
	v_cndmask_b32_e32 v211, v211, v227, vcc
	v_cmp_gt_f32_e32 vcc, s67, v212
	s_nop 1
	v_cndmask_b32_e32 v212, v212, v228, vcc
	v_rsq_f32_e32 v212, v212
	s_nop 0
	v_mul_f32_e32 v228, 0x45800000, v212
	v_cndmask_b32_e32 v212, v212, v228, vcc
	v_cmp_gt_f32_e32 vcc, s67, v213
	s_nop 1
	v_cndmask_b32_e32 v213, v213, v229, vcc
	v_rsq_f32_e32 v213, v213
	s_nop 0
	v_mul_f32_e32 v229, 0x45800000, v213
	v_cndmask_b32_e32 v213, v213, v229, vcc
	v_cmp_gt_f32_e32 vcc, s67, v214
	s_nop 1
	v_cndmask_b32_e32 v214, v214, v232, vcc
	v_rsq_f32_e32 v214, v214
	s_nop 0
	v_mul_f32_e32 v232, 0x45800000, v214
	v_cndmask_b32_e32 v214, v214, v232, vcc
	v_cmp_gt_f32_e32 vcc, s67, v215
	s_nop 1
	v_cndmask_b32_e32 v215, v215, v233, vcc
	v_rsq_f32_e32 v215, v215
	s_nop 0
	v_mul_f32_e32 v233, 0x45800000, v215
	v_cndmask_b32_e32 v215, v215, v233, vcc
	v_cmp_gt_f32_e32 vcc, s67, v216
	s_nop 1
	v_cndmask_b32_e32 v216, v216, v234, vcc
	v_rsq_f32_e32 v216, v216
	s_nop 0
	v_mul_f32_e32 v234, 0x45800000, v216
	v_cndmask_b32_e32 v216, v216, v234, vcc
	v_cmp_gt_f32_e32 vcc, s67, v217
	s_nop 1
	v_cndmask_b32_e32 v217, v217, v235, vcc
	v_rsq_f32_e32 v217, v217
	s_nop 0
	v_mul_f32_e32 v235, 0x45800000, v217
	v_cndmask_b32_e32 v217, v217, v235, vcc
	s_waitcnt vmcnt(8)
	v_fma_f32 v140, v140, v210, v202
	v_fma_f32 v141, v141, v210, v203
	v_fma_f32 v142, v142, v210, v204
	v_fma_f32 v143, v143, v210, v205
	v_fma_f32 v136, v136, v210, v206
	v_fma_f32 v137, v137, v210, v207
	v_fma_f32 v138, v138, v210, v208
	v_fma_f32 v139, v139, v210, v209
	v_fma_f32 v120, v120, v210, v218
	v_fma_f32 v121, v121, v210, v219
	v_fma_f32 v122, v122, v210, v220
	v_fma_f32 v123, v123, v210, v221
	v_fma_f32 v112, v112, v210, v222
	v_fma_f32 v113, v113, v210, v223
	v_fma_f32 v114, v114, v210, v224
	v_fma_f32 v115, v115, v210, v225
	v_fma_f32 v108, v108, v211, v202
	v_fma_f32 v109, v109, v211, v203
	v_fma_f32 v110, v110, v211, v204
	v_fma_f32 v111, v111, v211, v205
	v_fma_f32 v104, v104, v211, v206
	v_fma_f32 v105, v105, v211, v207
	v_fma_f32 v106, v106, v211, v208
	v_fma_f32 v107, v107, v211, v209
	v_fma_f32 v100, v100, v211, v218
	v_fma_f32 v101, v101, v211, v219
	v_fma_f32 v102, v102, v211, v220
	v_fma_f32 v103, v103, v211, v221
	v_fma_f32 v96, v96, v211, v222
	v_fma_f32 v97, v97, v211, v223
	v_fma_f32 v98, v98, v211, v224
	v_fma_f32 v99, v99, v211, v225
	v_fma_f32 v92, v92, v212, v202
	v_fma_f32 v93, v93, v212, v203
	v_fma_f32 v94, v94, v212, v204
	v_fma_f32 v95, v95, v212, v205
	v_fma_f32 v88, v88, v212, v206
	v_fma_f32 v89, v89, v212, v207
	v_fma_f32 v90, v90, v212, v208
	v_fma_f32 v91, v91, v212, v209
	v_fma_f32 v84, v84, v212, v218
	v_fma_f32 v85, v85, v212, v219
	v_fma_f32 v86, v86, v212, v220
	v_fma_f32 v87, v87, v212, v221
	v_fma_f32 v80, v80, v212, v222
	v_fma_f32 v81, v81, v212, v223
	v_fma_f32 v82, v82, v212, v224
	v_fma_f32 v83, v83, v212, v225
	v_fma_f32 v76, v76, v213, v202
	v_fma_f32 v77, v77, v213, v203
	v_fma_f32 v78, v78, v213, v204
	v_fma_f32 v79, v79, v213, v205
	v_fma_f32 v72, v72, v213, v206
	v_fma_f32 v73, v73, v213, v207
	v_fma_f32 v74, v74, v213, v208
	v_fma_f32 v75, v75, v213, v209
	v_fma_f32 v68, v68, v213, v218
	v_fma_f32 v69, v69, v213, v219
	v_fma_f32 v70, v70, v213, v220
	v_fma_f32 v71, v71, v213, v221
	v_fma_f32 v64, v64, v213, v222
	v_fma_f32 v65, v65, v213, v223
	v_fma_f32 v66, v66, v213, v224
	v_fma_f32 v67, v67, v213, v225
	v_fma_f32 v60, v60, v214, v202
	v_fma_f32 v61, v61, v214, v203
	v_fma_f32 v62, v62, v214, v204
	v_fma_f32 v63, v63, v214, v205
	v_fma_f32 v56, v56, v214, v206
	v_fma_f32 v57, v57, v214, v207
	v_fma_f32 v58, v58, v214, v208
	v_fma_f32 v59, v59, v214, v209
	v_fma_f32 v52, v52, v214, v218
	v_fma_f32 v53, v53, v214, v219
	v_fma_f32 v54, v54, v214, v220
	v_fma_f32 v55, v55, v214, v221
	v_fma_f32 v48, v48, v214, v222
	v_fma_f32 v49, v49, v214, v223
	v_fma_f32 v50, v50, v214, v224
	v_fma_f32 v51, v51, v214, v225
	v_fma_f32 v44, v44, v215, v202
	v_fma_f32 v45, v45, v215, v203
	v_fma_f32 v46, v46, v215, v204
	v_fma_f32 v47, v47, v215, v205
	v_fma_f32 v40, v40, v215, v206
	v_fma_f32 v41, v41, v215, v207
	v_fma_f32 v42, v42, v215, v208
	v_fma_f32 v43, v43, v215, v209
	v_fma_f32 v36, v36, v215, v218
	v_fma_f32 v37, v37, v215, v219
	v_fma_f32 v38, v38, v215, v220
	v_fma_f32 v39, v39, v215, v221
	v_fma_f32 v32, v32, v215, v222
	v_fma_f32 v33, v33, v215, v223
	v_fma_f32 v34, v34, v215, v224
	v_fma_f32 v35, v35, v215, v225
	v_fma_f32 v28, v28, v216, v202
	v_fma_f32 v29, v29, v216, v203
	v_fma_f32 v30, v30, v216, v204
	v_fma_f32 v31, v31, v216, v205
	v_fma_f32 v24, v24, v216, v206
	v_fma_f32 v25, v25, v216, v207
	v_fma_f32 v26, v26, v216, v208
	v_fma_f32 v27, v27, v216, v209
	v_fma_f32 v20, v20, v216, v218
	v_fma_f32 v21, v21, v216, v219
	v_fma_f32 v22, v22, v216, v220
	v_fma_f32 v23, v23, v216, v221
	v_fma_f32 v16, v16, v216, v222
	v_fma_f32 v17, v17, v216, v223
	v_fma_f32 v18, v18, v216, v224
	v_fma_f32 v19, v19, v216, v225
	v_fma_f32 v12, v12, v217, v202
	v_fma_f32 v13, v13, v217, v203
	v_fma_f32 v14, v14, v217, v204
	v_fma_f32 v15, v15, v217, v205
	v_fma_f32 v8, v8, v217, v206
	v_fma_f32 v9, v9, v217, v207
	v_fma_f32 v10, v10, v217, v208
	v_fma_f32 v11, v11, v217, v209
	v_fma_f32 v4, v4, v217, v218
	v_fma_f32 v5, v5, v217, v219
	v_fma_f32 v6, v6, v217, v220
	v_fma_f32 v7, v7, v217, v221
	v_fma_f32 v0, v0, v217, v222
	v_fma_f32 v1, v1, v217, v223
	v_fma_f32 v2, v2, v217, v224
	v_fma_f32 v3, v3, v217, v225
	v_mov_b32_e32 v214, 0
	v_mov_b32_e32 v215, 0
	v_mov_b32_e32 v216, 0
	v_mov_b32_e32 v217, 0
	s_lshl_b32 s100, s32, 12
	s_sub_i32 s100, 0x2000, s100
	s_mul_i32 s101, s32, 0x1400
	s_add_i32 s101, s101, 0xc00
	s_lshl_b32 s67, s32, 10
	s_add_i32 s98, s67, 5120
	s_add_i32 s99, s67, 1024
	s_mov_b64 s[90:91], exec
	s_mov_b64 exec, s[78:79]
	v_add_u32_e32 v250, s100, v169
	ds_write_b128 v250, v[140:143] offset:0
	ds_write_b128 v250, v[136:139] offset:16
	ds_write_b128 v250, v[120:123] offset:512
	ds_write_b128 v250, v[112:115] offset:528
	v_add_u32_e32 v250, s98, v169
	ds_write_b128 v250, v[60:63] offset:0
	ds_write_b128 v250, v[56:59] offset:16
	ds_write_b128 v250, v[52:55] offset:512
	ds_write_b128 v250, v[48:51] offset:528
	ds_write_b128 v169, v[214:217] offset:0
	ds_write_b128 v169, v[214:217] offset:16
	ds_write_b128 v169, v[214:217] offset:512
	ds_write_b128 v169, v[214:217] offset:528
	s_mov_b64 exec, s[80:81]
	v_add_u32_e32 v251, s99, v169
	ds_write_b128 v251, v[76:79] offset:0
	ds_write_b128 v251, v[72:75] offset:16
	ds_write_b128 v251, v[68:71] offset:512
	ds_write_b128 v251, v[64:67] offset:528
	v_add_u32_e32 v251, s101, v169
	ds_write_b128 v251, v[12:15] offset:0
	ds_write_b128 v251, v[8:11] offset:16
	ds_write_b128 v251, v[4:7] offset:512
	ds_write_b128 v251, v[0:3] offset:528
	ds_write_b128 v169, v[214:217] offset:7168
	ds_write_b128 v169, v[214:217] offset:7184
	ds_write_b128 v169, v[214:217] offset:7680
	ds_write_b128 v169, v[214:217] offset:7696
	s_mov_b64 exec, s[90:91]
	s_waitcnt lgkmcnt(0)
	s_barrier
	ds_read_b128 v[186:189], v231 offset:0
	ds_read_b128 v[190:193], v231 offset:512
	ds_read_b128 v[194:197], v231 offset:2048
	ds_read_b128 v[198:201], v231 offset:2560
	s_waitcnt vmcnt(0)
	v_cndmask_b32_e64 v218, 0, v116, s[78:79]
	v_cndmask_b32_e64 v222, 0, v128, s[80:81]
	v_cndmask_b32_e64 v219, 0, v117, s[78:79]
	v_cndmask_b32_e64 v223, 0, v129, s[80:81]
	v_cndmask_b32_e64 v220, 0, v118, s[78:79]
	v_cndmask_b32_e64 v224, 0, v130, s[80:81]
	v_cndmask_b32_e64 v221, 0, v119, s[78:79]
	v_cndmask_b32_e64 v225, 0, v131, s[80:81]
	v_cndmask_b32_e64 v226, 0, v160, s[78:79]
	v_cndmask_b32_e64 v232, 0, v178, s[80:81]
	v_cndmask_b32_e64 v227, 0, v161, s[78:79]
	v_cndmask_b32_e64 v233, 0, v179, s[80:81]
	v_cndmask_b32_e64 v228, 0, v162, s[78:79]
	v_cndmask_b32_e64 v234, 0, v180, s[80:81]
	v_cndmask_b32_e64 v229, 0, v163, s[78:79]
	v_cndmask_b32_e64 v235, 0, v181, s[80:81]
	s_waitcnt lgkmcnt(0)
	s_nop 1
	v_fma_f32 v202, v124, v140, v132
	v_fma_f32 v203, v125, v141, v133
	v_fma_f32 v204, v126, v142, v134
	v_fma_f32 v205, v127, v143, v135
	v_fmac_f32_dpp v202, v76, v116 row_shr:1 row_mask:0xf bank_mask:0xf
	v_fmac_f32_dpp v203, v77, v117 row_shr:1 row_mask:0xf bank_mask:0xf
	v_fmac_f32_dpp v204, v78, v118 row_shr:1 row_mask:0xf bank_mask:0xf
	v_fmac_f32_dpp v205, v79, v119 row_shr:1 row_mask:0xf bank_mask:0xf
	v_fmac_f32_e32 v202, v186, v218
	v_fmac_f32_e32 v203, v187, v219
	v_fmac_f32_e32 v204, v188, v220
	v_fmac_f32_e32 v205, v189, v221
	v_fmac_f32_e32 v202, v108, v128
	v_fmac_f32_e32 v203, v109, v129
	v_fmac_f32_e32 v204, v110, v130
	v_fmac_f32_e32 v205, v111, v131
	v_fma_f32 v206, v164, v120, v182
	v_fma_f32 v207, v165, v121, v183
	v_fma_f32 v208, v166, v122, v184
	v_fma_f32 v209, v167, v123, v185
	v_fmac_f32_dpp v206, v68, v160 row_shr:1 row_mask:0xf bank_mask:0xf
	v_fmac_f32_dpp v207, v69, v161 row_shr:1 row_mask:0xf bank_mask:0xf
	v_fmac_f32_dpp v208, v70, v162 row_shr:1 row_mask:0xf bank_mask:0xf
	v_fmac_f32_dpp v209, v71, v163 row_shr:1 row_mask:0xf bank_mask:0xf
	v_fmac_f32_e32 v206, v190, v226
	v_fmac_f32_e32 v207, v191, v227
	v_fmac_f32_e32 v208, v192, v228
	v_fmac_f32_e32 v209, v193, v229
	v_fmac_f32_e32 v206, v100, v178
	v_fmac_f32_e32 v207, v101, v179
	v_fmac_f32_e32 v208, v102, v180
	v_fmac_f32_e32 v209, v103, v181
	v_mul_f32_e32 v210, 0xbfb8aa3b, v202
	v_mul_f32_e32 v211, 0xbfb8aa3b, v203
	v_mul_f32_e32 v212, 0xbfb8aa3b, v204
	v_mul_f32_e32 v213, 0xbfb8aa3b, v205
	v_exp_f32_e32 v210, v210
	v_exp_f32_e32 v211, v211
	v_exp_f32_e32 v212, v212
	v_exp_f32_e32 v213, v213
	v_add_f32_e32 v210, 1.0, v210
	v_add_f32_e32 v211, 1.0, v211
	v_add_f32_e32 v212, 1.0, v212
	v_add_f32_e32 v213, 1.0, v213
	v_rcp_f32_e32 v210, v210
	v_rcp_f32_e32 v211, v211
	v_rcp_f32_e32 v212, v212
	v_rcp_f32_e32 v213, v213
	v_mul_f32_e32 v202, v202, v210
	v_mul_f32_e32 v203, v203, v211
	v_mul_f32_e32 v204, v204, v212
	v_mul_f32_e32 v205, v205, v213
	v_mul_f32_e32 v202, v202, v206
	v_mul_f32_e32 v203, v203, v207
	v_mul_f32_e32 v204, v204, v208
	v_mul_f32_e32 v205, v205, v209
	v_cvt_pk_bf16_f32 v236, v202, v203
	v_cvt_pk_bf16_f32 v237, v204, v205
	v_fma_f32 v202, v124, v108, v132
	v_fma_f32 v203, v125, v109, v133
	v_fma_f32 v204, v126, v110, v134
	v_fma_f32 v205, v127, v111, v135
	v_fmac_f32_e32 v202, v140, v116
	v_fmac_f32_e32 v203, v141, v117
	v_fmac_f32_e32 v204, v142, v118
	v_fmac_f32_e32 v205, v143, v119
	v_fmac_f32_e32 v202, v92, v128
	v_fmac_f32_e32 v203, v93, v129
	v_fmac_f32_e32 v204, v94, v130
	v_fmac_f32_e32 v205, v95, v131
	v_fma_f32 v206, v164, v100, v182
	v_fma_f32 v207, v165, v101, v183
	v_fma_f32 v208, v166, v102, v184
	v_fma_f32 v209, v167, v103, v185
	v_fmac_f32_e32 v206, v120, v160
	v_fmac_f32_e32 v207, v121, v161
	v_fmac_f32_e32 v208, v122, v162
	v_fmac_f32_e32 v209, v123, v163
	v_fmac_f32_e32 v206, v84, v178
	v_fmac_f32_e32 v207, v85, v179
	v_fmac_f32_e32 v208, v86, v180
	v_fmac_f32_e32 v209, v87, v181
	v_mul_f32_e32 v210, 0xbfb8aa3b, v202
	v_mul_f32_e32 v211, 0xbfb8aa3b, v203
	v_mul_f32_e32 v212, 0xbfb8aa3b, v204
	v_mul_f32_e32 v213, 0xbfb8aa3b, v205
	v_exp_f32_e32 v210, v210
	v_exp_f32_e32 v211, v211
	v_exp_f32_e32 v212, v212
	v_exp_f32_e32 v213, v213
	v_add_f32_e32 v210, 1.0, v210
	v_add_f32_e32 v211, 1.0, v211
	v_add_f32_e32 v212, 1.0, v212
	v_add_f32_e32 v213, 1.0, v213
	v_rcp_f32_e32 v210, v210
	v_rcp_f32_e32 v211, v211
	v_rcp_f32_e32 v212, v212
	v_rcp_f32_e32 v213, v213
	v_mul_f32_e32 v202, v202, v210
	v_mul_f32_e32 v203, v203, v211
	v_mul_f32_e32 v204, v204, v212
	v_mul_f32_e32 v205, v205, v213
	v_mul_f32_e32 v202, v202, v206
	v_mul_f32_e32 v203, v203, v207
	v_mul_f32_e32 v204, v204, v208
	v_mul_f32_e32 v205, v205, v209
	v_cvt_pk_bf16_f32 v238, v202, v203
	v_cvt_pk_bf16_f32 v239, v204, v205
	v_fma_f32 v202, v124, v92, v132
	v_fma_f32 v203, v125, v93, v133
	v_fma_f32 v204, v126, v94, v134
	v_fma_f32 v205, v127, v95, v135
	v_fmac_f32_e32 v202, v108, v116
	v_fmac_f32_e32 v203, v109, v117
	v_fmac_f32_e32 v204, v110, v118
	v_fmac_f32_e32 v205, v111, v119
	v_fmac_f32_e32 v202, v76, v128
	v_fmac_f32_e32 v203, v77, v129
	v_fmac_f32_e32 v204, v78, v130
	v_fmac_f32_e32 v205, v79, v131
	v_fma_f32 v206, v164, v84, v182
	v_fma_f32 v207, v165, v85, v183
	v_fma_f32 v208, v166, v86, v184
	v_fma_f32 v209, v167, v87, v185
	v_fmac_f32_e32 v206, v100, v160
	v_fmac_f32_e32 v207, v101, v161
	v_fmac_f32_e32 v208, v102, v162
	v_fmac_f32_e32 v209, v103, v163
	v_fmac_f32_e32 v206, v68, v178
	v_fmac_f32_e32 v207, v69, v179
	v_fmac_f32_e32 v208, v70, v180
	v_fmac_f32_e32 v209, v71, v181
	v_mul_f32_e32 v210, 0xbfb8aa3b, v202
	v_mul_f32_e32 v211, 0xbfb8aa3b, v203
	v_mul_f32_e32 v212, 0xbfb8aa3b, v204
	v_mul_f32_e32 v213, 0xbfb8aa3b, v205
	v_exp_f32_e32 v210, v210
	v_exp_f32_e32 v211, v211
	v_exp_f32_e32 v212, v212
	v_exp_f32_e32 v213, v213
	v_add_f32_e32 v210, 1.0, v210
	v_add_f32_e32 v211, 1.0, v211
	v_add_f32_e32 v212, 1.0, v212
	v_add_f32_e32 v213, 1.0, v213
	v_rcp_f32_e32 v210, v210
	v_rcp_f32_e32 v211, v211
	v_rcp_f32_e32 v212, v212
	v_rcp_f32_e32 v213, v213
	v_mul_f32_e32 v202, v202, v210
	v_mul_f32_e32 v203, v203, v211
	v_mul_f32_e32 v204, v204, v212
	v_mul_f32_e32 v205, v205, v213
	v_mul_f32_e32 v202, v202, v206
	v_mul_f32_e32 v203, v203, v207
	v_mul_f32_e32 v204, v204, v208
	v_mul_f32_e32 v205, v205, v209
	v_cvt_pk_bf16_f32 v240, v202, v203
	v_cvt_pk_bf16_f32 v241, v204, v205
	v_fma_f32 v202, v124, v76, v132
	v_fma_f32 v203, v125, v77, v133
	v_fma_f32 v204, v126, v78, v134
	v_fma_f32 v205, v127, v79, v135
	v_fmac_f32_e32 v202, v92, v116
	v_fmac_f32_e32 v203, v93, v117
	v_fmac_f32_e32 v204, v94, v118
	v_fmac_f32_e32 v205, v95, v119
	v_fmac_f32_dpp v202, v140, v128 row_shl:1 row_mask:0xf bank_mask:0xf
	v_fmac_f32_dpp v203, v141, v129 row_shl:1 row_mask:0xf bank_mask:0xf
	v_fmac_f32_dpp v204, v142, v130 row_shl:1 row_mask:0xf bank_mask:0xf
	v_fmac_f32_dpp v205, v143, v131 row_shl:1 row_mask:0xf bank_mask:0xf
	v_fmac_f32_e32 v202, v186, v222
	v_fmac_f32_e32 v203, v187, v223
	v_fmac_f32_e32 v204, v188, v224
	v_fmac_f32_e32 v205, v189, v225
	v_fma_f32 v206, v164, v68, v182
	v_fma_f32 v207, v165, v69, v183
	v_fma_f32 v208, v166, v70, v184
	v_fma_f32 v209, v167, v71, v185
	v_fmac_f32_e32 v206, v84, v160
	v_fmac_f32_e32 v207, v85, v161
	v_fmac_f32_e32 v208, v86, v162
	v_fmac_f32_e32 v209, v87, v163
	v_fmac_f32_dpp v206, v120, v178 row_shl:1 row_mask:0xf bank_mask:0xf
	v_fmac_f32_dpp v207, v121, v179 row_shl:1 row_mask:0xf bank_mask:0xf
	v_fmac_f32_dpp v208, v122, v180 row_shl:1 row_mask:0xf bank_mask:0xf
	v_fmac_f32_dpp v209, v123, v181 row_shl:1 row_mask:0xf bank_mask:0xf
	v_fmac_f32_e32 v206, v190, v232
	v_fmac_f32_e32 v207, v191, v233
	v_fmac_f32_e32 v208, v192, v234
	v_fmac_f32_e32 v209, v193, v235
	v_mul_f32_e32 v210, 0xbfb8aa3b, v202
	v_mul_f32_e32 v211, 0xbfb8aa3b, v203
	v_mul_f32_e32 v212, 0xbfb8aa3b, v204
	v_mul_f32_e32 v213, 0xbfb8aa3b, v205
	v_exp_f32_e32 v210, v210
	v_exp_f32_e32 v211, v211
	v_exp_f32_e32 v212, v212
	v_exp_f32_e32 v213, v213
	v_add_f32_e32 v210, 1.0, v210
	v_add_f32_e32 v211, 1.0, v211
	v_add_f32_e32 v212, 1.0, v212
	v_add_f32_e32 v213, 1.0, v213
	v_rcp_f32_e32 v210, v210
	v_rcp_f32_e32 v211, v211
	v_rcp_f32_e32 v212, v212
	v_rcp_f32_e32 v213, v213
	v_mul_f32_e32 v202, v202, v210
	v_mul_f32_e32 v203, v203, v211
	v_mul_f32_e32 v204, v204, v212
	v_mul_f32_e32 v205, v205, v213
	v_mul_f32_e32 v202, v202, v206
	v_mul_f32_e32 v203, v203, v207
	v_mul_f32_e32 v204, v204, v208
	v_mul_f32_e32 v205, v205, v209
	v_cvt_pk_bf16_f32 v242, v202, v203
	v_cvt_pk_bf16_f32 v243, v204, v205
	v_fma_f32 v202, v124, v60, v132
	v_fma_f32 v203, v125, v61, v133
	v_fma_f32 v204, v126, v62, v134
	v_fma_f32 v205, v127, v63, v135
	v_fmac_f32_dpp v202, v12, v116 row_shr:1 row_mask:0xf bank_mask:0xf
	v_fmac_f32_dpp v203, v13, v117 row_shr:1 row_mask:0xf bank_mask:0xf
	v_fmac_f32_dpp v204, v14, v118 row_shr:1 row_mask:0xf bank_mask:0xf
	v_fmac_f32_dpp v205, v15, v119 row_shr:1 row_mask:0xf bank_mask:0xf
	v_fmac_f32_e32 v202, v194, v218
	v_fmac_f32_e32 v203, v195, v219
	v_fmac_f32_e32 v204, v196, v220
	v_fmac_f32_e32 v205, v197, v221
	v_fmac_f32_e32 v202, v44, v128
	v_fmac_f32_e32 v203, v45, v129
	v_fmac_f32_e32 v204, v46, v130
	v_fmac_f32_e32 v205, v47, v131
	v_fma_f32 v206, v164, v52, v182
	v_fma_f32 v207, v165, v53, v183
	v_fma_f32 v208, v166, v54, v184
	v_fma_f32 v209, v167, v55, v185
	v_fmac_f32_dpp v206, v4, v160 row_shr:1 row_mask:0xf bank_mask:0xf
	v_fmac_f32_dpp v207, v5, v161 row_shr:1 row_mask:0xf bank_mask:0xf
	v_fmac_f32_dpp v208, v6, v162 row_shr:1 row_mask:0xf bank_mask:0xf
	v_fmac_f32_dpp v209, v7, v163 row_shr:1 row_mask:0xf bank_mask:0xf
	v_fmac_f32_e32 v206, v198, v226
	v_fmac_f32_e32 v207, v199, v227
	v_fmac_f32_e32 v208, v200, v228
	v_fmac_f32_e32 v209, v201, v229
	v_fmac_f32_e32 v206, v36, v178
	v_fmac_f32_e32 v207, v37, v179
	v_fmac_f32_e32 v208, v38, v180
	v_fmac_f32_e32 v209, v39, v181
	v_mul_f32_e32 v210, 0xbfb8aa3b, v202
	v_mul_f32_e32 v211, 0xbfb8aa3b, v203
	v_mul_f32_e32 v212, 0xbfb8aa3b, v204
	v_mul_f32_e32 v213, 0xbfb8aa3b, v205
	v_exp_f32_e32 v210, v210
	v_exp_f32_e32 v211, v211
	v_exp_f32_e32 v212, v212
	v_exp_f32_e32 v213, v213
	v_add_f32_e32 v210, 1.0, v210
	v_add_f32_e32 v211, 1.0, v211
	v_add_f32_e32 v212, 1.0, v212
	v_add_f32_e32 v213, 1.0, v213
	v_rcp_f32_e32 v210, v210
	v_rcp_f32_e32 v211, v211
	v_rcp_f32_e32 v212, v212
	v_rcp_f32_e32 v213, v213
	v_mul_f32_e32 v202, v202, v210
	v_mul_f32_e32 v203, v203, v211
	v_mul_f32_e32 v204, v204, v212
	v_mul_f32_e32 v205, v205, v213
	v_mul_f32_e32 v202, v202, v206
	v_mul_f32_e32 v203, v203, v207
	v_mul_f32_e32 v204, v204, v208
	v_mul_f32_e32 v205, v205, v209
	v_cvt_pk_bf16_f32 v244, v202, v203
	v_cvt_pk_bf16_f32 v245, v204, v205
	v_fma_f32 v202, v124, v44, v132
	v_fma_f32 v203, v125, v45, v133
	v_fma_f32 v204, v126, v46, v134
	v_fma_f32 v205, v127, v47, v135
	v_fmac_f32_e32 v202, v60, v116
	v_fmac_f32_e32 v203, v61, v117
	v_fmac_f32_e32 v204, v62, v118
	v_fmac_f32_e32 v205, v63, v119
	v_fmac_f32_e32 v202, v28, v128
	v_fmac_f32_e32 v203, v29, v129
	v_fmac_f32_e32 v204, v30, v130
	v_fmac_f32_e32 v205, v31, v131
	v_fma_f32 v206, v164, v36, v182
	v_fma_f32 v207, v165, v37, v183
	v_fma_f32 v208, v166, v38, v184
	v_fma_f32 v209, v167, v39, v185
	v_fmac_f32_e32 v206, v52, v160
	v_fmac_f32_e32 v207, v53, v161
	v_fmac_f32_e32 v208, v54, v162
	v_fmac_f32_e32 v209, v55, v163
	v_fmac_f32_e32 v206, v20, v178
	v_fmac_f32_e32 v207, v21, v179
	v_fmac_f32_e32 v208, v22, v180
	v_fmac_f32_e32 v209, v23, v181
	v_mul_f32_e32 v210, 0xbfb8aa3b, v202
	v_mul_f32_e32 v211, 0xbfb8aa3b, v203
	v_mul_f32_e32 v212, 0xbfb8aa3b, v204
	v_mul_f32_e32 v213, 0xbfb8aa3b, v205
	v_exp_f32_e32 v210, v210
	v_exp_f32_e32 v211, v211
	v_exp_f32_e32 v212, v212
	v_exp_f32_e32 v213, v213
	v_add_f32_e32 v210, 1.0, v210
	v_add_f32_e32 v211, 1.0, v211
	v_add_f32_e32 v212, 1.0, v212
	v_add_f32_e32 v213, 1.0, v213
	v_rcp_f32_e32 v210, v210
	v_rcp_f32_e32 v211, v211
	v_rcp_f32_e32 v212, v212
	v_rcp_f32_e32 v213, v213
	v_mul_f32_e32 v202, v202, v210
	v_mul_f32_e32 v203, v203, v211
	v_mul_f32_e32 v204, v204, v212
	v_mul_f32_e32 v205, v205, v213
	v_mul_f32_e32 v202, v202, v206
	v_mul_f32_e32 v203, v203, v207
	v_mul_f32_e32 v204, v204, v208
	v_mul_f32_e32 v205, v205, v209
	v_cvt_pk_bf16_f32 v246, v202, v203
	v_cvt_pk_bf16_f32 v247, v204, v205
	v_fma_f32 v202, v124, v28, v132
	v_fma_f32 v203, v125, v29, v133
	v_fma_f32 v204, v126, v30, v134
	v_fma_f32 v205, v127, v31, v135
	v_fmac_f32_e32 v202, v44, v116
	v_fmac_f32_e32 v203, v45, v117
	v_fmac_f32_e32 v204, v46, v118
	v_fmac_f32_e32 v205, v47, v119
	v_fmac_f32_e32 v202, v12, v128
	v_fmac_f32_e32 v203, v13, v129
	v_fmac_f32_e32 v204, v14, v130
	v_fmac_f32_e32 v205, v15, v131
	v_fma_f32 v206, v164, v20, v182
	v_fma_f32 v207, v165, v21, v183
	v_fma_f32 v208, v166, v22, v184
	v_fma_f32 v209, v167, v23, v185
	v_fmac_f32_e32 v206, v36, v160
	v_fmac_f32_e32 v207, v37, v161
	v_fmac_f32_e32 v208, v38, v162
	v_fmac_f32_e32 v209, v39, v163
	v_fmac_f32_e32 v206, v4, v178
	v_fmac_f32_e32 v207, v5, v179
	v_fmac_f32_e32 v208, v6, v180
	v_fmac_f32_e32 v209, v7, v181
	v_mul_f32_e32 v210, 0xbfb8aa3b, v202
	v_mul_f32_e32 v211, 0xbfb8aa3b, v203
	v_mul_f32_e32 v212, 0xbfb8aa3b, v204
	v_mul_f32_e32 v213, 0xbfb8aa3b, v205
	v_exp_f32_e32 v210, v210
	v_exp_f32_e32 v211, v211
	v_exp_f32_e32 v212, v212
	v_exp_f32_e32 v213, v213
	v_add_f32_e32 v210, 1.0, v210
	v_add_f32_e32 v211, 1.0, v211
	v_add_f32_e32 v212, 1.0, v212
	v_add_f32_e32 v213, 1.0, v213
	v_rcp_f32_e32 v210, v210
	v_rcp_f32_e32 v211, v211
	v_rcp_f32_e32 v212, v212
	v_rcp_f32_e32 v213, v213
	v_mul_f32_e32 v202, v202, v210
	v_mul_f32_e32 v203, v203, v211
	v_mul_f32_e32 v204, v204, v212
	v_mul_f32_e32 v205, v205, v213
	v_mul_f32_e32 v202, v202, v206
	v_mul_f32_e32 v203, v203, v207
	v_mul_f32_e32 v204, v204, v208
	v_mul_f32_e32 v205, v205, v209
	v_cvt_pk_bf16_f32 v248, v202, v203
	v_cvt_pk_bf16_f32 v249, v204, v205
	v_fma_f32 v202, v124, v12, v132
	v_fma_f32 v203, v125, v13, v133
	v_fma_f32 v204, v126, v14, v134
	v_fma_f32 v205, v127, v15, v135
	v_fmac_f32_e32 v202, v28, v116
	v_fmac_f32_e32 v203, v29, v117
	v_fmac_f32_e32 v204, v30, v118
	v_fmac_f32_e32 v205, v31, v119
	v_fmac_f32_dpp v202, v60, v128 row_shl:1 row_mask:0xf bank_mask:0xf
	v_fmac_f32_dpp v203, v61, v129 row_shl:1 row_mask:0xf bank_mask:0xf
	v_fmac_f32_dpp v204, v62, v130 row_shl:1 row_mask:0xf bank_mask:0xf
	v_fmac_f32_dpp v205, v63, v131 row_shl:1 row_mask:0xf bank_mask:0xf
	v_fmac_f32_e32 v202, v194, v222
	v_fmac_f32_e32 v203, v195, v223
	v_fmac_f32_e32 v204, v196, v224
	v_fmac_f32_e32 v205, v197, v225
	v_fma_f32 v206, v164, v4, v182
	v_fma_f32 v207, v165, v5, v183
	v_fma_f32 v208, v166, v6, v184
	v_fma_f32 v209, v167, v7, v185
	v_fmac_f32_e32 v206, v20, v160
	v_fmac_f32_e32 v207, v21, v161
	v_fmac_f32_e32 v208, v22, v162
	v_fmac_f32_e32 v209, v23, v163
	v_fmac_f32_dpp v206, v52, v178 row_shl:1 row_mask:0xf bank_mask:0xf
	v_fmac_f32_dpp v207, v53, v179 row_shl:1 row_mask:0xf bank_mask:0xf
	v_fmac_f32_dpp v208, v54, v180 row_shl:1 row_mask:0xf bank_mask:0xf
	v_fmac_f32_dpp v209, v55, v181 row_shl:1 row_mask:0xf bank_mask:0xf
	v_fmac_f32_e32 v206, v198, v232
	v_fmac_f32_e32 v207, v199, v233
	v_fmac_f32_e32 v208, v200, v234
	v_fmac_f32_e32 v209, v201, v235
	v_mul_f32_e32 v210, 0xbfb8aa3b, v202
	v_mul_f32_e32 v211, 0xbfb8aa3b, v203
	v_mul_f32_e32 v212, 0xbfb8aa3b, v204
	v_mul_f32_e32 v213, 0xbfb8aa3b, v205
	v_exp_f32_e32 v210, v210
	v_exp_f32_e32 v211, v211
	v_exp_f32_e32 v212, v212
	v_exp_f32_e32 v213, v213
	v_add_f32_e32 v210, 1.0, v210
	v_add_f32_e32 v211, 1.0, v211
	v_add_f32_e32 v212, 1.0, v212
	v_add_f32_e32 v213, 1.0, v213
	v_rcp_f32_e32 v210, v210
	v_rcp_f32_e32 v211, v211
	v_rcp_f32_e32 v212, v212
	v_rcp_f32_e32 v213, v213
	v_mul_f32_e32 v202, v202, v210
	v_mul_f32_e32 v203, v203, v211
	v_mul_f32_e32 v204, v204, v212
	v_mul_f32_e32 v205, v205, v213
	v_mul_f32_e32 v202, v202, v206
	v_mul_f32_e32 v203, v203, v207
	v_mul_f32_e32 v204, v204, v208
	v_mul_f32_e32 v205, v205, v209
	v_cvt_pk_bf16_f32 v250, v202, v203
	v_cvt_pk_bf16_f32 v251, v204, v205
	global_load_dwordx4 v[116:119], v177, s[2:3] offset:16
	v_add_u32_e32 v213, 0x5800, v177
	global_load_dwordx4 v[124:127], v213, s[2:3] offset:16
	v_add_u32_e32 v212, 0xb000, v177
	global_load_dwordx4 v[128:131], v212, s[2:3] offset:16
	global_load_dwordx4 v[132:135], v177, s[28:29] offset:16
	v_add_u32_e32 v212, 0x2c00, v177
	global_load_dwordx4 v[160:163], v212, s[2:3] offset:16
	v_add_u32_e32 v213, 0x8400, v177
	global_load_dwordx4 v[164:167], v213, s[2:3] offset:16
	v_add_u32_e32 v212, 0xdc00, v177
	global_load_dwordx4 v[178:181], v212, s[2:3] offset:16
	v_add_u32_e32 v213, 0x2c00, v177
	global_load_dwordx4 v[182:185], v213, s[28:29] offset:16
	v_mov_b32_e32 v140, v236
	v_mov_b32_e32 v141, v237
	v_mov_b32_e32 v108, v238
	v_mov_b32_e32 v109, v239
	v_mov_b32_e32 v92, v240
	v_mov_b32_e32 v93, v241
	v_mov_b32_e32 v76, v242
	v_mov_b32_e32 v77, v243
	v_mov_b32_e32 v60, v244
	v_mov_b32_e32 v61, v245
	v_mov_b32_e32 v44, v246
	v_mov_b32_e32 v45, v247
	v_mov_b32_e32 v28, v248
	v_mov_b32_e32 v29, v249
	v_mov_b32_e32 v12, v250
	v_mov_b32_e32 v13, v251
	ds_read_b128 v[186:189], v231 offset:16
	ds_read_b128 v[190:193], v231 offset:528
	ds_read_b128 v[194:197], v231 offset:2064
	ds_read_b128 v[198:201], v231 offset:2576
	s_waitcnt vmcnt(0)
	v_cndmask_b32_e64 v218, 0, v116, s[78:79]
	v_cndmask_b32_e64 v222, 0, v128, s[80:81]
	v_cndmask_b32_e64 v219, 0, v117, s[78:79]
	v_cndmask_b32_e64 v223, 0, v129, s[80:81]
	v_cndmask_b32_e64 v220, 0, v118, s[78:79]
	v_cndmask_b32_e64 v224, 0, v130, s[80:81]
	v_cndmask_b32_e64 v221, 0, v119, s[78:79]
	v_cndmask_b32_e64 v225, 0, v131, s[80:81]
	v_cndmask_b32_e64 v226, 0, v160, s[78:79]
	v_cndmask_b32_e64 v232, 0, v178, s[80:81]
	v_cndmask_b32_e64 v227, 0, v161, s[78:79]
	v_cndmask_b32_e64 v233, 0, v179, s[80:81]
	v_cndmask_b32_e64 v228, 0, v162, s[78:79]
	v_cndmask_b32_e64 v234, 0, v180, s[80:81]
	v_cndmask_b32_e64 v229, 0, v163, s[78:79]
	v_cndmask_b32_e64 v235, 0, v181, s[80:81]
	s_waitcnt lgkmcnt(0)
	s_nop 1
	v_fma_f32 v202, v124, v136, v132
	v_fma_f32 v203, v125, v137, v133
	v_fma_f32 v204, v126, v138, v134
	v_fma_f32 v205, v127, v139, v135
	v_fmac_f32_dpp v202, v72, v116 row_shr:1 row_mask:0xf bank_mask:0xf
	v_fmac_f32_dpp v203, v73, v117 row_shr:1 row_mask:0xf bank_mask:0xf
	v_fmac_f32_dpp v204, v74, v118 row_shr:1 row_mask:0xf bank_mask:0xf
	v_fmac_f32_dpp v205, v75, v119 row_shr:1 row_mask:0xf bank_mask:0xf
	v_fmac_f32_e32 v202, v186, v218
	v_fmac_f32_e32 v203, v187, v219
	v_fmac_f32_e32 v204, v188, v220
	v_fmac_f32_e32 v205, v189, v221
	v_fmac_f32_e32 v202, v104, v128
	v_fmac_f32_e32 v203, v105, v129
	v_fmac_f32_e32 v204, v106, v130
	v_fmac_f32_e32 v205, v107, v131
	v_fma_f32 v206, v164, v112, v182
	v_fma_f32 v207, v165, v113, v183
	v_fma_f32 v208, v166, v114, v184
	v_fma_f32 v209, v167, v115, v185
	v_fmac_f32_dpp v206, v64, v160 row_shr:1 row_mask:0xf bank_mask:0xf
	v_fmac_f32_dpp v207, v65, v161 row_shr:1 row_mask:0xf bank_mask:0xf
	v_fmac_f32_dpp v208, v66, v162 row_shr:1 row_mask:0xf bank_mask:0xf
	v_fmac_f32_dpp v209, v67, v163 row_shr:1 row_mask:0xf bank_mask:0xf
	v_fmac_f32_e32 v206, v190, v226
	v_fmac_f32_e32 v207, v191, v227
	v_fmac_f32_e32 v208, v192, v228
	v_fmac_f32_e32 v209, v193, v229
	v_fmac_f32_e32 v206, v96, v178
	v_fmac_f32_e32 v207, v97, v179
	v_fmac_f32_e32 v208, v98, v180
	v_fmac_f32_e32 v209, v99, v181
	v_mul_f32_e32 v210, 0xbfb8aa3b, v202
	v_mul_f32_e32 v211, 0xbfb8aa3b, v203
	v_mul_f32_e32 v212, 0xbfb8aa3b, v204
	v_mul_f32_e32 v213, 0xbfb8aa3b, v205
	v_exp_f32_e32 v210, v210
	v_exp_f32_e32 v211, v211
	v_exp_f32_e32 v212, v212
	v_exp_f32_e32 v213, v213
	v_add_f32_e32 v210, 1.0, v210
	v_add_f32_e32 v211, 1.0, v211
	v_add_f32_e32 v212, 1.0, v212
	v_add_f32_e32 v213, 1.0, v213
	v_rcp_f32_e32 v210, v210
	v_rcp_f32_e32 v211, v211
	v_rcp_f32_e32 v212, v212
	v_rcp_f32_e32 v213, v213
	v_mul_f32_e32 v202, v202, v210
	v_mul_f32_e32 v203, v203, v211
	v_mul_f32_e32 v204, v204, v212
	v_mul_f32_e32 v205, v205, v213
	v_mul_f32_e32 v202, v202, v206
	v_mul_f32_e32 v203, v203, v207
	v_mul_f32_e32 v204, v204, v208
	v_mul_f32_e32 v205, v205, v209
	v_cvt_pk_bf16_f32 v142, v202, v203
	v_cvt_pk_bf16_f32 v143, v204, v205
	v_fma_f32 v202, v124, v104, v132
	v_fma_f32 v203, v125, v105, v133
	v_fma_f32 v204, v126, v106, v134
	v_fma_f32 v205, v127, v107, v135
	v_fmac_f32_e32 v202, v136, v116
	v_fmac_f32_e32 v203, v137, v117
	v_fmac_f32_e32 v204, v138, v118
	v_fmac_f32_e32 v205, v139, v119
	v_fmac_f32_e32 v202, v88, v128
	v_fmac_f32_e32 v203, v89, v129
	v_fmac_f32_e32 v204, v90, v130
	v_fmac_f32_e32 v205, v91, v131
	v_fma_f32 v206, v164, v96, v182
	v_fma_f32 v207, v165, v97, v183
	v_fma_f32 v208, v166, v98, v184
	v_fma_f32 v209, v167, v99, v185
	v_fmac_f32_e32 v206, v112, v160
	v_fmac_f32_e32 v207, v113, v161
	v_fmac_f32_e32 v208, v114, v162
	v_fmac_f32_e32 v209, v115, v163
	v_fmac_f32_e32 v206, v80, v178
	v_fmac_f32_e32 v207, v81, v179
	v_fmac_f32_e32 v208, v82, v180
	v_fmac_f32_e32 v209, v83, v181
	v_mul_f32_e32 v210, 0xbfb8aa3b, v202
	v_mul_f32_e32 v211, 0xbfb8aa3b, v203
	v_mul_f32_e32 v212, 0xbfb8aa3b, v204
	v_mul_f32_e32 v213, 0xbfb8aa3b, v205
	v_exp_f32_e32 v210, v210
	v_exp_f32_e32 v211, v211
	v_exp_f32_e32 v212, v212
	v_exp_f32_e32 v213, v213
	v_add_f32_e32 v210, 1.0, v210
	v_add_f32_e32 v211, 1.0, v211
	v_add_f32_e32 v212, 1.0, v212
	v_add_f32_e32 v213, 1.0, v213
	v_rcp_f32_e32 v210, v210
	v_rcp_f32_e32 v211, v211
	v_rcp_f32_e32 v212, v212
	v_rcp_f32_e32 v213, v213
	v_mul_f32_e32 v202, v202, v210
	v_mul_f32_e32 v203, v203, v211
	v_mul_f32_e32 v204, v204, v212
	v_mul_f32_e32 v205, v205, v213
	v_mul_f32_e32 v202, v202, v206
	v_mul_f32_e32 v203, v203, v207
	v_mul_f32_e32 v204, v204, v208
	v_mul_f32_e32 v205, v205, v209
	v_cvt_pk_bf16_f32 v110, v202, v203
	v_cvt_pk_bf16_f32 v111, v204, v205
	v_fma_f32 v202, v124, v88, v132
	v_fma_f32 v203, v125, v89, v133
	v_fma_f32 v204, v126, v90, v134
	v_fma_f32 v205, v127, v91, v135
	v_fmac_f32_e32 v202, v104, v116
	v_fmac_f32_e32 v203, v105, v117
	v_fmac_f32_e32 v204, v106, v118
	v_fmac_f32_e32 v205, v107, v119
	v_fmac_f32_e32 v202, v72, v128
	v_fmac_f32_e32 v203, v73, v129
	v_fmac_f32_e32 v204, v74, v130
	v_fmac_f32_e32 v205, v75, v131
	v_fma_f32 v206, v164, v80, v182
	v_fma_f32 v207, v165, v81, v183
	v_fma_f32 v208, v166, v82, v184
	v_fma_f32 v209, v167, v83, v185
	v_fmac_f32_e32 v206, v96, v160
	v_fmac_f32_e32 v207, v97, v161
	v_fmac_f32_e32 v208, v98, v162
	v_fmac_f32_e32 v209, v99, v163
	v_fmac_f32_e32 v206, v64, v178
	v_fmac_f32_e32 v207, v65, v179
	v_fmac_f32_e32 v208, v66, v180
	v_fmac_f32_e32 v209, v67, v181
	v_mul_f32_e32 v210, 0xbfb8aa3b, v202
	v_mul_f32_e32 v211, 0xbfb8aa3b, v203
	v_mul_f32_e32 v212, 0xbfb8aa3b, v204
	v_mul_f32_e32 v213, 0xbfb8aa3b, v205
	v_exp_f32_e32 v210, v210
	v_exp_f32_e32 v211, v211
	v_exp_f32_e32 v212, v212
	v_exp_f32_e32 v213, v213
	v_add_f32_e32 v210, 1.0, v210
	v_add_f32_e32 v211, 1.0, v211
	v_add_f32_e32 v212, 1.0, v212
	v_add_f32_e32 v213, 1.0, v213
	v_rcp_f32_e32 v210, v210
	v_rcp_f32_e32 v211, v211
	v_rcp_f32_e32 v212, v212
	v_rcp_f32_e32 v213, v213
	v_mul_f32_e32 v202, v202, v210
	v_mul_f32_e32 v203, v203, v211
	v_mul_f32_e32 v204, v204, v212
	v_mul_f32_e32 v205, v205, v213
	v_mul_f32_e32 v202, v202, v206
	v_mul_f32_e32 v203, v203, v207
	v_mul_f32_e32 v204, v204, v208
	v_mul_f32_e32 v205, v205, v209
	v_cvt_pk_bf16_f32 v94, v202, v203
	v_cvt_pk_bf16_f32 v95, v204, v205
	v_fma_f32 v202, v124, v72, v132
	v_fma_f32 v203, v125, v73, v133
	v_fma_f32 v204, v126, v74, v134
	v_fma_f32 v205, v127, v75, v135
	v_fmac_f32_e32 v202, v88, v116
	v_fmac_f32_e32 v203, v89, v117
	v_fmac_f32_e32 v204, v90, v118
	v_fmac_f32_e32 v205, v91, v119
	v_fmac_f32_dpp v202, v136, v128 row_shl:1 row_mask:0xf bank_mask:0xf
	v_fmac_f32_dpp v203, v137, v129 row_shl:1 row_mask:0xf bank_mask:0xf
	v_fmac_f32_dpp v204, v138, v130 row_shl:1 row_mask:0xf bank_mask:0xf
	v_fmac_f32_dpp v205, v139, v131 row_shl:1 row_mask:0xf bank_mask:0xf
	v_fmac_f32_e32 v202, v186, v222
	v_fmac_f32_e32 v203, v187, v223
	v_fmac_f32_e32 v204, v188, v224
	v_fmac_f32_e32 v205, v189, v225
	v_fma_f32 v206, v164, v64, v182
	v_fma_f32 v207, v165, v65, v183
	v_fma_f32 v208, v166, v66, v184
	v_fma_f32 v209, v167, v67, v185
	v_fmac_f32_e32 v206, v80, v160
	v_fmac_f32_e32 v207, v81, v161
	v_fmac_f32_e32 v208, v82, v162
	v_fmac_f32_e32 v209, v83, v163
	v_fmac_f32_dpp v206, v112, v178 row_shl:1 row_mask:0xf bank_mask:0xf
	v_fmac_f32_dpp v207, v113, v179 row_shl:1 row_mask:0xf bank_mask:0xf
	v_fmac_f32_dpp v208, v114, v180 row_shl:1 row_mask:0xf bank_mask:0xf
	v_fmac_f32_dpp v209, v115, v181 row_shl:1 row_mask:0xf bank_mask:0xf
	v_fmac_f32_e32 v206, v190, v232
	v_fmac_f32_e32 v207, v191, v233
	v_fmac_f32_e32 v208, v192, v234
	v_fmac_f32_e32 v209, v193, v235
	v_mul_f32_e32 v210, 0xbfb8aa3b, v202
	v_mul_f32_e32 v211, 0xbfb8aa3b, v203
	v_mul_f32_e32 v212, 0xbfb8aa3b, v204
	v_mul_f32_e32 v213, 0xbfb8aa3b, v205
	v_exp_f32_e32 v210, v210
	v_exp_f32_e32 v211, v211
	v_exp_f32_e32 v212, v212
	v_exp_f32_e32 v213, v213
	v_add_f32_e32 v210, 1.0, v210
	v_add_f32_e32 v211, 1.0, v211
	v_add_f32_e32 v212, 1.0, v212
	v_add_f32_e32 v213, 1.0, v213
	v_rcp_f32_e32 v210, v210
	v_rcp_f32_e32 v211, v211
	v_rcp_f32_e32 v212, v212
	v_rcp_f32_e32 v213, v213
	v_mul_f32_e32 v202, v202, v210
	v_mul_f32_e32 v203, v203, v211
	v_mul_f32_e32 v204, v204, v212
	v_mul_f32_e32 v205, v205, v213
	v_mul_f32_e32 v202, v202, v206
	v_mul_f32_e32 v203, v203, v207
	v_mul_f32_e32 v204, v204, v208
	v_mul_f32_e32 v205, v205, v209
	v_cvt_pk_bf16_f32 v78, v202, v203
	v_cvt_pk_bf16_f32 v79, v204, v205
	v_fma_f32 v202, v124, v56, v132
	v_fma_f32 v203, v125, v57, v133
	v_fma_f32 v204, v126, v58, v134
	v_fma_f32 v205, v127, v59, v135
	v_fmac_f32_dpp v202, v8, v116 row_shr:1 row_mask:0xf bank_mask:0xf
	v_fmac_f32_dpp v203, v9, v117 row_shr:1 row_mask:0xf bank_mask:0xf
	v_fmac_f32_dpp v204, v10, v118 row_shr:1 row_mask:0xf bank_mask:0xf
	v_fmac_f32_dpp v205, v11, v119 row_shr:1 row_mask:0xf bank_mask:0xf
	v_fmac_f32_e32 v202, v194, v218
	v_fmac_f32_e32 v203, v195, v219
	v_fmac_f32_e32 v204, v196, v220
	v_fmac_f32_e32 v205, v197, v221
	v_fmac_f32_e32 v202, v40, v128
	v_fmac_f32_e32 v203, v41, v129
	v_fmac_f32_e32 v204, v42, v130
	v_fmac_f32_e32 v205, v43, v131
	v_fma_f32 v206, v164, v48, v182
	v_fma_f32 v207, v165, v49, v183
	v_fma_f32 v208, v166, v50, v184
	v_fma_f32 v209, v167, v51, v185
	v_fmac_f32_dpp v206, v0, v160 row_shr:1 row_mask:0xf bank_mask:0xf
	v_fmac_f32_dpp v207, v1, v161 row_shr:1 row_mask:0xf bank_mask:0xf
	v_fmac_f32_dpp v208, v2, v162 row_shr:1 row_mask:0xf bank_mask:0xf
	v_fmac_f32_dpp v209, v3, v163 row_shr:1 row_mask:0xf bank_mask:0xf
	v_fmac_f32_e32 v206, v198, v226
	v_fmac_f32_e32 v207, v199, v227
	v_fmac_f32_e32 v208, v200, v228
	v_fmac_f32_e32 v209, v201, v229
	v_fmac_f32_e32 v206, v32, v178
	v_fmac_f32_e32 v207, v33, v179
	v_fmac_f32_e32 v208, v34, v180
	v_fmac_f32_e32 v209, v35, v181
	v_mul_f32_e32 v210, 0xbfb8aa3b, v202
	v_mul_f32_e32 v211, 0xbfb8aa3b, v203
	v_mul_f32_e32 v212, 0xbfb8aa3b, v204
	v_mul_f32_e32 v213, 0xbfb8aa3b, v205
	v_exp_f32_e32 v210, v210
	v_exp_f32_e32 v211, v211
	v_exp_f32_e32 v212, v212
	v_exp_f32_e32 v213, v213
	v_add_f32_e32 v210, 1.0, v210
	v_add_f32_e32 v211, 1.0, v211
	v_add_f32_e32 v212, 1.0, v212
	v_add_f32_e32 v213, 1.0, v213
	v_rcp_f32_e32 v210, v210
	v_rcp_f32_e32 v211, v211
	v_rcp_f32_e32 v212, v212
	v_rcp_f32_e32 v213, v213
	v_mul_f32_e32 v202, v202, v210
	v_mul_f32_e32 v203, v203, v211
	v_mul_f32_e32 v204, v204, v212
	v_mul_f32_e32 v205, v205, v213
	v_mul_f32_e32 v202, v202, v206
	v_mul_f32_e32 v203, v203, v207
	v_mul_f32_e32 v204, v204, v208
	v_mul_f32_e32 v205, v205, v209
	v_cvt_pk_bf16_f32 v62, v202, v203
	v_cvt_pk_bf16_f32 v63, v204, v205
	v_fma_f32 v202, v124, v40, v132
	v_fma_f32 v203, v125, v41, v133
	v_fma_f32 v204, v126, v42, v134
	v_fma_f32 v205, v127, v43, v135
	v_fmac_f32_e32 v202, v56, v116
	v_fmac_f32_e32 v203, v57, v117
	v_fmac_f32_e32 v204, v58, v118
	v_fmac_f32_e32 v205, v59, v119
	v_fmac_f32_e32 v202, v24, v128
	v_fmac_f32_e32 v203, v25, v129
	v_fmac_f32_e32 v204, v26, v130
	v_fmac_f32_e32 v205, v27, v131
	v_fma_f32 v206, v164, v32, v182
	v_fma_f32 v207, v165, v33, v183
	v_fma_f32 v208, v166, v34, v184
	v_fma_f32 v209, v167, v35, v185
	v_fmac_f32_e32 v206, v48, v160
	v_fmac_f32_e32 v207, v49, v161
	v_fmac_f32_e32 v208, v50, v162
	v_fmac_f32_e32 v209, v51, v163
	v_fmac_f32_e32 v206, v16, v178
	v_fmac_f32_e32 v207, v17, v179
	v_fmac_f32_e32 v208, v18, v180
	v_fmac_f32_e32 v209, v19, v181
	v_mul_f32_e32 v210, 0xbfb8aa3b, v202
	v_mul_f32_e32 v211, 0xbfb8aa3b, v203
	v_mul_f32_e32 v212, 0xbfb8aa3b, v204
	v_mul_f32_e32 v213, 0xbfb8aa3b, v205
	v_exp_f32_e32 v210, v210
	v_exp_f32_e32 v211, v211
	v_exp_f32_e32 v212, v212
	v_exp_f32_e32 v213, v213
	v_add_f32_e32 v210, 1.0, v210
	v_add_f32_e32 v211, 1.0, v211
	v_add_f32_e32 v212, 1.0, v212
	v_add_f32_e32 v213, 1.0, v213
	v_rcp_f32_e32 v210, v210
	v_rcp_f32_e32 v211, v211
	v_rcp_f32_e32 v212, v212
	v_rcp_f32_e32 v213, v213
	v_mul_f32_e32 v202, v202, v210
	v_mul_f32_e32 v203, v203, v211
	v_mul_f32_e32 v204, v204, v212
	v_mul_f32_e32 v205, v205, v213
	v_mul_f32_e32 v202, v202, v206
	v_mul_f32_e32 v203, v203, v207
	v_mul_f32_e32 v204, v204, v208
	v_mul_f32_e32 v205, v205, v209
	v_cvt_pk_bf16_f32 v46, v202, v203
	v_cvt_pk_bf16_f32 v47, v204, v205
	v_fma_f32 v202, v124, v24, v132
	v_fma_f32 v203, v125, v25, v133
	v_fma_f32 v204, v126, v26, v134
	v_fma_f32 v205, v127, v27, v135
	v_fmac_f32_e32 v202, v40, v116
	v_fmac_f32_e32 v203, v41, v117
	v_fmac_f32_e32 v204, v42, v118
	v_fmac_f32_e32 v205, v43, v119
	v_fmac_f32_e32 v202, v8, v128
	v_fmac_f32_e32 v203, v9, v129
	v_fmac_f32_e32 v204, v10, v130
	v_fmac_f32_e32 v205, v11, v131
	v_fma_f32 v206, v164, v16, v182
	v_fma_f32 v207, v165, v17, v183
	v_fma_f32 v208, v166, v18, v184
	v_fma_f32 v209, v167, v19, v185
	v_fmac_f32_e32 v206, v32, v160
	v_fmac_f32_e32 v207, v33, v161
	v_fmac_f32_e32 v208, v34, v162
	v_fmac_f32_e32 v209, v35, v163
	v_fmac_f32_e32 v206, v0, v178
	v_fmac_f32_e32 v207, v1, v179
	v_fmac_f32_e32 v208, v2, v180
	v_fmac_f32_e32 v209, v3, v181
	v_mul_f32_e32 v210, 0xbfb8aa3b, v202
	v_mul_f32_e32 v211, 0xbfb8aa3b, v203
	v_mul_f32_e32 v212, 0xbfb8aa3b, v204
	v_mul_f32_e32 v213, 0xbfb8aa3b, v205
	v_exp_f32_e32 v210, v210
	v_exp_f32_e32 v211, v211
	v_exp_f32_e32 v212, v212
	v_exp_f32_e32 v213, v213
	v_add_f32_e32 v210, 1.0, v210
	v_add_f32_e32 v211, 1.0, v211
	v_add_f32_e32 v212, 1.0, v212
	v_add_f32_e32 v213, 1.0, v213
	v_rcp_f32_e32 v210, v210
	v_rcp_f32_e32 v211, v211
	v_rcp_f32_e32 v212, v212
	v_rcp_f32_e32 v213, v213
	v_mul_f32_e32 v202, v202, v210
	v_mul_f32_e32 v203, v203, v211
	v_mul_f32_e32 v204, v204, v212
	v_mul_f32_e32 v205, v205, v213
	v_mul_f32_e32 v202, v202, v206
	v_mul_f32_e32 v203, v203, v207
	v_mul_f32_e32 v204, v204, v208
	v_mul_f32_e32 v205, v205, v209
	v_cvt_pk_bf16_f32 v30, v202, v203
	v_cvt_pk_bf16_f32 v31, v204, v205
	v_fma_f32 v202, v124, v8, v132
	v_fma_f32 v203, v125, v9, v133
	v_fma_f32 v204, v126, v10, v134
	v_fma_f32 v205, v127, v11, v135
	v_fmac_f32_e32 v202, v24, v116
	v_fmac_f32_e32 v203, v25, v117
	v_fmac_f32_e32 v204, v26, v118
	v_fmac_f32_e32 v205, v27, v119
	v_fmac_f32_dpp v202, v56, v128 row_shl:1 row_mask:0xf bank_mask:0xf
	v_fmac_f32_dpp v203, v57, v129 row_shl:1 row_mask:0xf bank_mask:0xf
	v_fmac_f32_dpp v204, v58, v130 row_shl:1 row_mask:0xf bank_mask:0xf
	v_fmac_f32_dpp v205, v59, v131 row_shl:1 row_mask:0xf bank_mask:0xf
	v_fmac_f32_e32 v202, v194, v222
	v_fmac_f32_e32 v203, v195, v223
	v_fmac_f32_e32 v204, v196, v224
	v_fmac_f32_e32 v205, v197, v225
	v_fma_f32 v206, v164, v0, v182
	v_fma_f32 v207, v165, v1, v183
	v_fma_f32 v208, v166, v2, v184
	v_fma_f32 v209, v167, v3, v185
	v_fmac_f32_e32 v206, v16, v160
	v_fmac_f32_e32 v207, v17, v161
	v_fmac_f32_e32 v208, v18, v162
	v_fmac_f32_e32 v209, v19, v163
	v_fmac_f32_dpp v206, v48, v178 row_shl:1 row_mask:0xf bank_mask:0xf
	v_fmac_f32_dpp v207, v49, v179 row_shl:1 row_mask:0xf bank_mask:0xf
	v_fmac_f32_dpp v208, v50, v180 row_shl:1 row_mask:0xf bank_mask:0xf
	v_fmac_f32_dpp v209, v51, v181 row_shl:1 row_mask:0xf bank_mask:0xf
	v_fmac_f32_e32 v206, v198, v232
	v_fmac_f32_e32 v207, v199, v233
	v_fmac_f32_e32 v208, v200, v234
	v_fmac_f32_e32 v209, v201, v235
	v_mul_f32_e32 v210, 0xbfb8aa3b, v202
	v_mul_f32_e32 v211, 0xbfb8aa3b, v203
	v_mul_f32_e32 v212, 0xbfb8aa3b, v204
	v_mul_f32_e32 v213, 0xbfb8aa3b, v205
	v_exp_f32_e32 v210, v210
	v_exp_f32_e32 v211, v211
	v_exp_f32_e32 v212, v212
	v_exp_f32_e32 v213, v213
	v_add_f32_e32 v210, 1.0, v210
	v_add_f32_e32 v211, 1.0, v211
	v_add_f32_e32 v212, 1.0, v212
	v_add_f32_e32 v213, 1.0, v213
	v_rcp_f32_e32 v210, v210
	v_rcp_f32_e32 v211, v211
	v_rcp_f32_e32 v212, v212
	v_rcp_f32_e32 v213, v213
	v_mul_f32_e32 v202, v202, v210
	v_mul_f32_e32 v203, v203, v211
	v_mul_f32_e32 v204, v204, v212
	v_mul_f32_e32 v205, v205, v213
	v_mul_f32_e32 v202, v202, v206
	v_mul_f32_e32 v203, v203, v207
	v_mul_f32_e32 v204, v204, v208
	v_mul_f32_e32 v205, v205, v209
	v_cvt_pk_bf16_f32 v14, v202, v203
	v_cvt_pk_bf16_f32 v15, v204, v205
	global_store_dwordx4 v168, v[140:143], s[76:77]
	v_add_u32_e32 v250, 0x1600, v168
	global_store_dwordx4 v250, v[108:111], s[76:77]
	s_nop 0
	v_add_u32_e32 v250, 0x2c00, v168
	global_store_dwordx4 v250, v[92:95], s[76:77]
	s_nop 0
	v_add_u32_e32 v250, 0x4200, v168
	global_store_dwordx4 v250, v[76:79], s[76:77]
	s_nop 0
	v_add_u32_e32 v250, 0xb0000, v168
	global_store_dwordx4 v250, v[60:63], s[76:77]
	s_nop 0
	v_add_u32_e32 v250, 0xb1600, v168
	global_store_dwordx4 v250, v[44:47], s[76:77]
	s_nop 0
	v_add_u32_e32 v250, 0xb2c00, v168
	global_store_dwordx4 v250, v[28:31], s[76:77]
	s_nop 0
	v_add_u32_e32 v250, 0xb4200, v168
	global_store_dwordx4 v250, v[12:15], s[76:77]
	s_nop 0
	s_andn2_b64 vcc, exec, s[6:7]
	s_mov_b64 s[4:5], -1
	s_cbranch_vccnz .LBB0_824
	s_andn2_b64 vcc, exec, s[12:13]
	s_cbranch_vccnz .LBB0_823
	s_barrier
	s_branch .LBB0_823

.LBB0_957:
	s_cmp_gt_i32 s72, 9
	s_cselect_b64 s[4:5], -1, 0
	s_cmp_lt_i32 s73, 10
	s_cselect_b64 s[6:7], -1, 0
	s_or_b64 s[4:5], s[4:5], s[6:7]
	s_and_b64 vcc, exec, s[4:5]
	s_cbranch_vccnz .LBB0_1038
	v_readlane_b32 s2, v255, 2
	v_mov_b32_e32 v14, v230
	v_readlane_b32 s3, v255, 3
	s_and_b64 vcc, exec, s[2:3]
	v_readfirstlane_b32 s5, v14
	s_cbranch_vccnz .LBB0_973
	v_lshlrev_b32_e32 v0, 4, v14
	s_waitcnt lgkmcnt(0)
	v_add_u32_e32 v1, 0x2000, v0
	v_ashrrev_i32_e32 v2, 31, v1
	v_lshrrev_b32_e32 v2, 22, v2
	v_add_u32_e32 v2, v1, v2
	v_ashrrev_i32_e32 v8, 10, v2
	v_mul_i32_i24_e32 v2, 0x400, v8
	v_sub_u32_e32 v1, v1, v2
	v_lshrrev_b32_e32 v2, 4, v1
	v_bitop3_b32 v1, v2, v1, 32 bitop3:0x6c
	v_ashrrev_i32_e32 v2, 31, v1
	v_lshrrev_b32_e32 v2, 26, v2
	v_add_u32_e32 v2, v1, v2
	v_lshlrev_b32_e32 v3, 3, v8
	v_ashrrev_i32_e32 v9, 6, v2
	v_and_b32_e32 v3, -16, v3
	v_add_u32_e32 v3, v9, v3
	v_and_b32_e32 v4, 3, v9
	s_mov_b32 s4, 0x1fffe0
	v_lshrrev_b32_e32 v5, 2, v3
	v_lshlrev_b32_e32 v6, 1, v3
	v_and_b32_e32 v2, 0xc0, v2
	v_and_or_b32 v4, v3, s4, v4
	v_and_b32_e32 v5, 4, v5
	v_and_b32_e32 v6, 24, v6
	v_sub_u32_e32 v1, v1, v2
	v_mov_b32_e32 v2, 1
	v_or3_b32 v4, v4, v5, v6
	v_lshlrev_b32_e32 v5, 5, v8
	v_ashrrev_i16_sdwa v1, v2, sext(v1) dst_sel:DWORD dst_unused:UNUSED_PAD src0_sel:DWORD src1_sel:BYTE_0
	v_and_b32_e32 v5, 32, v5
	v_bfe_i32 v10, v1, 0, 16
	v_add_lshl_u32 v1, v5, v10, 1
	v_lshl_add_u32 v144, v4, 11, v1
	v_lshl_add_u32 v146, v3, 11, v1
	v_lshrrev_b32_e32 v248, 11, v146
	v_and_b32_e32 v249, 0x7ff, v146
	v_and_b32_e32 v250, 15, v248
	v_lshlrev_b32_e32 v250, 2, v250
	v_bfe_u32 v251, v248, 4, 2
	v_and_or_b32 v248, v248, 64, v250
	v_or_b32_e32 v248, v248, v251
	v_lshl_or_b32 v146, v248, 11, v249
	v_bfe_i32 v1, v14, 27, 1
	v_lshrrev_b32_e32 v1, 22, v1
	v_add_u32_e32 v1, v0, v1
	v_and_b32_e32 v1, 0xfffffc00, v1
	v_sub_u32_e32 v0, v0, v1
	v_lshrrev_b32_e32 v1, 4, v0
	v_ashrrev_i32_e32 v3, 31, v14
	v_bitop3_b32 v0, v1, v0, 32 bitop3:0x6c
	v_lshrrev_b32_e32 v3, 26, v3
	v_ashrrev_i32_e32 v1, 31, v0
	v_add_u32_e32 v3, v14, v3
	s_add_u32 s0, s70, 0x4b00000
	v_lshrrev_b32_e32 v1, 26, v1
	v_ashrrev_i32_e32 v12, 6, v3
	s_addc_u32 s20, s71, 0
	s_ashr_i32 s6, s5, 6
	v_add_u32_e32 v1, v0, v1
	v_lshlrev_b32_e32 v3, 3, v12
	v_readlane_b32 s2, v254, 62
	s_ashr_i32 s7, s5, 8
	s_lshl_b32 s21, s6, 10
	v_ashrrev_i32_e32 v11, 6, v1
	v_and_b32_e32 v3, -16, v3
	v_readlane_b32 s3, v254, 63
	v_add_u32_e32 v3, v11, v3
	v_and_b32_e32 v4, 3, v11
	s_movk_i32 s30, 0x59
	s_and_b64 s[10:11], s[2:3], exec
	v_and_or_b32 v4, v3, s4, v4
	s_cselect_b32 s4, s30, 0x58
	v_readlane_b32 s2, v254, 51
	s_mul_i32 s4, s4, s2
	v_readlane_b32 s2, v254, 61
	s_add_i32 s4, s4, s2
	s_mul_hi_i32 s10, s4, 0x2e8ba2e9
	s_lshr_b32 s11, s10, 31
	s_ashr_i32 s10, s10, 5
	s_add_i32 s10, s10, s11
	s_lshl_b32 s11, s10, 3
	s_mulk_i32 s10, 0xb0
	s_sub_i32 s10, s4, s10
	s_bfe_u32 s4, s10, 0x3001c
	s_add_i32 s12, s10, s4
	s_sext_i32_i16 s4, s12
	s_and_b32 s12, s12, 0xfff8
	s_sub_i32 s10, s10, s12
	s_sext_i32_i16 s10, s10
	v_lshrrev_b32_e32 v5, 2, v3
	v_lshlrev_b32_e32 v6, 1, v3
	v_and_b32_e32 v1, 0xc0, v1
	s_lshr_b32 s4, s4, 3
	s_add_i32 s88, s11, s10
	v_and_b32_e32 v5, 4, v5
	v_and_b32_e32 v6, 24, v6
	v_sub_u32_e32 v0, v0, v1
	s_ashr_i32 s89, s88, 31
	s_bfe_i64 s[12:13], s[4:5], 0x100000
	v_or3_b32 v4, v4, v5, v6
	v_lshlrev_b32_e32 v5, 5, v12
	v_ashrrev_i16_sdwa v0, v2, sext(v0) dst_sel:DWORD dst_unused:UNUSED_PAD src0_sel:DWORD src1_sel:BYTE_0
	s_lshl_b64 s[10:11], s[88:89], 19
	s_lshl_b64 s[12:13], s[12:13], 18
	v_and_b32_e32 v5, 32, v5
	v_bfe_i32 v13, v0, 0, 16
	s_add_u32 s92, s33, s12
	v_add_lshl_u32 v0, v5, v13, 1
	s_addc_u32 s93, s82, s13
	s_add_i32 s31, s21, 0
	v_lshl_add_u32 v148, v4, 11, v0
	s_add_i32 m0, s31, 0x10000
	v_lshl_add_u32 v150, v3, 11, v0
	v_lshrrev_b32_e32 v248, 11, v150
	v_and_b32_e32 v249, 0x7ff, v150
	v_and_b32_e32 v250, 15, v248
	v_lshlrev_b32_e32 v250, 2, v250
	v_bfe_u32 v251, v248, 4, 2
	v_and_or_b32 v248, v248, 64, v250
	v_or_b32_e32 v248, v248, v251
	v_lshl_or_b32 v150, v248, 11, v249
	global_load_lds_dwordx4 v148, s[92:93]
	s_add_i32 m0, s31, 0x12000
	s_add_u32 s12, s92, 0x580000
	global_load_lds_dwordx4 v144, s[92:93]
	s_addc_u32 s13, s93, 0
	s_add_i32 m0, s31, 0x14000
	v_mov_b32_e32 v149, 0
	global_load_lds_dwordx4 v148, s[12:13]
	s_add_i32 m0, s31, 0x16000
	s_add_u32 s90, s0, s10
	s_addc_u32 s91, s20, s11
	s_add_i32 s52, s31, 0x2000
	global_load_lds_dwordx4 v144, s[12:13]
	s_mov_b32 m0, s31
	s_add_u32 s10, s90, 0x40000
	global_load_lds_dwordx4 v150, s[90:91]
	s_mov_b32 m0, s52
	s_addc_u32 s11, s91, 0
	s_add_i32 s53, s31, 0x4000
	global_load_lds_dwordx4 v146, s[90:91]
	s_mov_b32 m0, s53
	s_add_i32 s58, s31, 0x6000
	global_load_lds_dwordx4 v150, s[10:11]
	s_mov_b32 m0, s58
	v_mov_b32_e32 v145, v149
	global_load_lds_dwordx4 v146, s[10:11]
	v_mov_b32_e32 v151, v149
	v_mov_b32_e32 v147, v149
	s_cmp_eq_u32 s7, 1
	s_mov_b32 s59, 0
	v_lshl_add_u64 v[6:7], s[92:93], 0, v[148:149]
	v_lshl_add_u64 v[4:5], s[92:93], 0, v[144:145]
	v_lshl_add_u64 v[0:1], s[90:91], 0, v[150:151]
	s_cselect_b64 s[10:11], -1, 0
	s_cmp_lg_u32 s7, 1
	v_lshl_add_u64 v[2:3], s[90:91], 0, v[146:147]
	s_cbranch_scc1 .LBB0_961
	s_barrier
.LBB0_961:
	s_add_u32 s12, s70, 0x108000
	v_lshrrev_b32_e32 v16, 1, v14
	s_addc_u32 s13, s71, 0
	v_and_b32_e32 v16, 24, v16
	s_add_u32 s14, s70, 0x3b00000
	v_and_b32_e32 v15, 15, v14
	v_lshlrev_b32_e32 v17, 1, v16
	v_lshlrev_b32_e32 v14, 2, v14
	s_sext_i32_i16 s66, s4
	s_addc_u32 s15, s71, 0
	v_lshl_or_b32 v170, s7, 6, v15
	v_lshl_or_b32 v15, v15, 6, v17
	s_lshl_b32 s4, s7, 13
	v_and_b32_e32 v14, 32, v14
	v_bitop3_b32 v17, v15, s4, v14 bitop3:0xde
	s_lshl_b32 s4, s6, 5
	s_mov_b64 s[16:17], 0x80
	s_and_b32 s4, s4, 0x60
	s_add_i32 m0, s31, 0x18000
	v_lshl_add_u64 v[6:7], v[6:7], 0, s[16:17]
	s_lshl_b32 s6, s4, 7
	s_waitcnt vmcnt(2)
	s_barrier
	global_load_lds_dwordx4 v[6:7], off
	v_lshl_add_u64 v[4:5], v[4:5], 0, s[16:17]
	s_add_i32 m0, s31, 0x1a000
	s_add_i32 s60, s31, 0x8000
	s_add_i32 s61, s31, 0xa000
	v_bitop3_b32 v171, v15, s6, v14 bitop3:0xde
	global_load_lds_dwordx4 v[4:5], off
	v_lshl_add_u64 v[0:1], v[0:1], 0, s[16:17]
	s_mov_b32 m0, s60
	s_add_u32 s6, s92, 0x580080
	global_load_lds_dwordx4 v[0:1], off
	v_lshl_add_u64 v[0:1], v[2:3], 0, s[16:17]
	s_mov_b32 m0, s61
	s_addc_u32 s7, s93, 0
	global_load_lds_dwordx4 v[0:1], off
	s_add_i32 m0, s31, 0x1c000
	v_lshl_add_u64 v[0:1], s[6:7], 0, v[148:149]
	global_load_lds_dwordx4 v[0:1], off
	v_lshl_add_u64 v[0:1], s[6:7], 0, v[144:145]
	s_add_i32 m0, s31, 0x1e000
	s_cmpk_lt_u32 s5, 0x100
	global_load_lds_dwordx4 v[0:1], off
	v_lshlrev_b32_e32 v0, 14, v12
	v_and_b32_e32 v0, 0xffff8000, v0
	v_lshl_add_u32 v0, v11, 11, v0
	v_and_b32_e32 v1, 1, v12
	v_lshl_or_b32 v0, v1, 6, v0
	v_lshl_add_u32 v152, v13, 1, v0
	v_lshrrev_b32_e32 v248, 11, v152
	v_and_b32_e32 v249, 0x7ff, v152
	v_and_b32_e32 v250, 15, v248
	v_lshlrev_b32_e32 v250, 2, v250
	v_bfe_u32 v251, v248, 4, 2
	v_and_or_b32 v248, v248, 64, v250
	v_or_b32_e32 v248, v248, v251
	v_lshl_or_b32 v152, v248, 11, v249
	v_lshlrev_b32_e32 v0, 14, v8
	v_and_b32_e32 v0, 0xffff8000, v0
	s_waitcnt vmcnt(6)
	v_lshl_add_u32 v0, v9, 11, v0
	v_and_b32_e32 v1, 1, v8
	s_cselect_b64 s[34:35], -1, 0
	v_lshl_or_b32 v0, v1, 6, v0
	s_add_i32 s62, 0, 0x10000
	s_add_i32 s63, 0, 0x14000
	v_or_b32_e32 v172, s4, v16
	v_mov_b32_e32 v153, v149
	v_lshl_add_u32 v154, v10, 1, v0
	v_lshrrev_b32_e32 v248, 11, v154
	v_and_b32_e32 v249, 0x7ff, v154
	v_and_b32_e32 v250, 15, v248
	v_lshlrev_b32_e32 v250, 2, v250
	v_bfe_u32 v251, v248, 4, 2
	v_and_or_b32 v248, v248, 64, v250
	v_or_b32_e32 v248, v248, v251
	v_lshl_or_b32 v154, v248, 11, v249
	v_mov_b32_e32 v155, v149
	v_mov_b64_e32 v[156:157], 0x2c0
	v_mov_b64_e32 v[158:159], 0x2bf
	v_add_u32_e32 v173, s62, v171
	v_add_u32_e32 v174, s63, v171
	v_add_u32_e32 v175, 0, v17
	v_mov_b32_e32 v176, 0x358637bd
	s_mov_b32 s64, 0x800000
	s_movk_i32 s65, 0x2c00
	s_barrier
	s_branch .LBB0_964

.LBB0_970:
	s_and_b32 s32, s10, 1
	v_readlane_b32 s98, v254, 49
	v_readlane_b32 s99, v254, 50
	s_nop 0
	s_add_i32 s4, s88, 0
	s_ashr_i32 s4, s4, 2
	s_add_i32 s4, s4, 1
	s_cmp_gt_i32 s88, -1
	s_cselect_b32 s4, s4, 0
	s_mul_hi_i32 s5, s4, 0x5800
	s_mulk_i32 s4, 0x5800
	s_add_u32 s4, s98, s4
	s_addc_u32 s5, s99, s5
	v_and_b32_e32 v237, 15, v170
	v_and_b32_e32 v236, 64, v170
	v_lshl_add_u32 v236, v237, 2, v236
	v_mul_u32_u24_e32 v168, 0x1600, v236
	v_lshl_add_u32 v168, v172, 1, v168
	v_lshl_add_u32 v236, s88, 8, v236
	v_lshlrev_b32_e32 v236, 2, v236
	v_lshl_or_b32 v177, s66, 7, v172
	v_lshlrev_b32_e32 v177, 2, v177
	global_load_dwordx4 v[210:213], v236, s[12:13]
	global_load_dwordx4 v[214:217], v236, s[12:13] offset:512
	global_load_dwordx4 v[202:205], v177, s[4:5]
	global_load_dwordx4 v[206:209], v177, s[4:5] offset:16
	v_add_u32_e32 v226, 0x2c00, v177
	global_load_dwordx4 v[218:221], v226, s[4:5]
	global_load_dwordx4 v[222:225], v226, s[4:5] offset:16
	v_readlane_b32 s2, v254, 5
	v_readlane_b32 s3, v254, 6
	v_readlane_b32 s28, v254, 7
	v_readlane_b32 s29, v254, 8
	s_mul_i32 s76, s88, 0x160000
	s_lshl_b32 s57, s66, 8
	s_add_i32 s76, s76, s57
	s_add_i32 s76, s76, 0xbf00000
	s_add_u32 s76, s76, s70
	s_addc_u32 s77, s71, 0
	s_mov_b32 s55, 0x20800
	v_lshl_add_u32 v169, v172, 2, s55
	v_cmp_eq_u32_e64 s[78:79], 0, v237
	v_cmp_eq_u32_e64 s[80:81], 15, v237
	v_and_b32_e32 v231, 8, v237
	v_lshlrev_b32_e32 v231, 9, v231
	s_lshl_b32 s57, s32, 10
	v_add3_u32 v231, v231, v169, s57
	global_load_dwordx4 v[116:119], v177, s[2:3]
	v_add_u32_e32 v229, 0x5800, v177
	global_load_dwordx4 v[124:127], v229, s[2:3]
	v_add_u32_e32 v228, 0xb000, v177
	global_load_dwordx4 v[128:131], v228, s[2:3]
	global_load_dwordx4 v[132:135], v177, s[28:29]
	v_add_u32_e32 v228, 0x2c00, v177
	global_load_dwordx4 v[160:163], v228, s[2:3]
	v_add_u32_e32 v229, 0x8400, v177
	global_load_dwordx4 v[164:167], v229, s[2:3]
	v_add_u32_e32 v228, 0xdc00, v177
	global_load_dwordx4 v[178:181], v228, s[2:3]
	v_add_u32_e32 v229, 0x2c00, v177
	global_load_dwordx4 v[182:185], v229, s[28:29]
	s_waitcnt vmcnt(12)
	v_fmamk_f32 v210, v210, 0x3a800000, v176
	v_fmamk_f32 v211, v211, 0x3a800000, v176
	v_fmamk_f32 v212, v212, 0x3a800000, v176
	v_fmamk_f32 v213, v213, 0x3a800000, v176
	v_fmamk_f32 v214, v214, 0x3a800000, v176
	v_fmamk_f32 v215, v215, 0x3a800000, v176
	v_fmamk_f32 v216, v216, 0x3a800000, v176
	v_fmamk_f32 v217, v217, 0x3a800000, v176
	s_mov_b32 s57, 0x800000
	v_mul_f32_e32 v226, 0x4b800000, v210
	v_mul_f32_e32 v227, 0x4b800000, v211
	v_mul_f32_e32 v228, 0x4b800000, v212
	v_mul_f32_e32 v229, 0x4b800000, v213
	v_mul_f32_e32 v232, 0x4b800000, v214
	v_mul_f32_e32 v233, 0x4b800000, v215
	v_mul_f32_e32 v234, 0x4b800000, v216
	v_mul_f32_e32 v235, 0x4b800000, v217
	v_cmp_gt_f32_e32 vcc, s57, v210
	s_nop 1
	v_cndmask_b32_e32 v210, v210, v226, vcc
	v_rsq_f32_e32 v210, v210
	s_nop 0
	v_mul_f32_e32 v226, 0x45800000, v210
	v_cndmask_b32_e32 v210, v210, v226, vcc
	v_cmp_gt_f32_e32 vcc, s57, v211
	s_nop 1
	v_cndmask_b32_e32 v211, v211, v227, vcc
	v_rsq_f32_e32 v211, v211
	s_nop 0
	v_mul_f32_e32 v227, 0x45800000, v211
	v_cndmask_b32_e32 v211, v211, v227, vcc
	v_cmp_gt_f32_e32 vcc, s57, v212
	s_nop 1
	v_cndmask_b32_e32 v212, v212, v228, vcc
	v_rsq_f32_e32 v212, v212
	s_nop 0
	v_mul_f32_e32 v228, 0x45800000, v212
	v_cndmask_b32_e32 v212, v212, v228, vcc
	v_cmp_gt_f32_e32 vcc, s57, v213
	s_nop 1
	v_cndmask_b32_e32 v213, v213, v229, vcc
	v_rsq_f32_e32 v213, v213
	s_nop 0
	v_mul_f32_e32 v229, 0x45800000, v213
	v_cndmask_b32_e32 v213, v213, v229, vcc
	v_cmp_gt_f32_e32 vcc, s57, v214
	s_nop 1
	v_cndmask_b32_e32 v214, v214, v232, vcc
	v_rsq_f32_e32 v214, v214
	s_nop 0
	v_mul_f32_e32 v232, 0x45800000, v214
	v_cndmask_b32_e32 v214, v214, v232, vcc
	v_cmp_gt_f32_e32 vcc, s57, v215
	s_nop 1
	v_cndmask_b32_e32 v215, v215, v233, vcc
	v_rsq_f32_e32 v215, v215
	s_nop 0
	v_mul_f32_e32 v233, 0x45800000, v215
	v_cndmask_b32_e32 v215, v215, v233, vcc
	v_cmp_gt_f32_e32 vcc, s57, v216
	s_nop 1
	v_cndmask_b32_e32 v216, v216, v234, vcc
	v_rsq_f32_e32 v216, v216
	s_nop 0
	v_mul_f32_e32 v234, 0x45800000, v216
	v_cndmask_b32_e32 v216, v216, v234, vcc
	v_cmp_gt_f32_e32 vcc, s57, v217
	s_nop 1
	v_cndmask_b32_e32 v217, v217, v235, vcc
	v_rsq_f32_e32 v217, v217
	s_nop 0
	v_mul_f32_e32 v235, 0x45800000, v217
	v_cndmask_b32_e32 v217, v217, v235, vcc
	s_waitcnt vmcnt(8)
	v_fma_f32 v140, v140, v210, v202
	v_fma_f32 v141, v141, v210, v203
	v_fma_f32 v142, v142, v210, v204
	v_fma_f32 v143, v143, v210, v205
	v_fma_f32 v136, v136, v210, v206
	v_fma_f32 v137, v137, v210, v207
	v_fma_f32 v138, v138, v210, v208
	v_fma_f32 v139, v139, v210, v209
	v_fma_f32 v120, v120, v210, v218
	v_fma_f32 v121, v121, v210, v219
	v_fma_f32 v122, v122, v210, v220
	v_fma_f32 v123, v123, v210, v221
	v_fma_f32 v112, v112, v210, v222
	v_fma_f32 v113, v113, v210, v223
	v_fma_f32 v114, v114, v210, v224
	v_fma_f32 v115, v115, v210, v225
	v_fma_f32 v108, v108, v211, v202
	v_fma_f32 v109, v109, v211, v203
	v_fma_f32 v110, v110, v211, v204
	v_fma_f32 v111, v111, v211, v205
	v_fma_f32 v104, v104, v211, v206
	v_fma_f32 v105, v105, v211, v207
	v_fma_f32 v106, v106, v211, v208
	v_fma_f32 v107, v107, v211, v209
	v_fma_f32 v100, v100, v211, v218
	v_fma_f32 v101, v101, v211, v219
	v_fma_f32 v102, v102, v211, v220
	v_fma_f32 v103, v103, v211, v221
	v_fma_f32 v96, v96, v211, v222
	v_fma_f32 v97, v97, v211, v223
	v_fma_f32 v98, v98, v211, v224
	v_fma_f32 v99, v99, v211, v225
	v_fma_f32 v92, v92, v212, v202
	v_fma_f32 v93, v93, v212, v203
	v_fma_f32 v94, v94, v212, v204
	v_fma_f32 v95, v95, v212, v205
	v_fma_f32 v88, v88, v212, v206
	v_fma_f32 v89, v89, v212, v207
	v_fma_f32 v90, v90, v212, v208
	v_fma_f32 v91, v91, v212, v209
	v_fma_f32 v84, v84, v212, v218
	v_fma_f32 v85, v85, v212, v219
	v_fma_f32 v86, v86, v212, v220
	v_fma_f32 v87, v87, v212, v221
	v_fma_f32 v80, v80, v212, v222
	v_fma_f32 v81, v81, v212, v223
	v_fma_f32 v82, v82, v212, v224
	v_fma_f32 v83, v83, v212, v225
	v_fma_f32 v76, v76, v213, v202
	v_fma_f32 v77, v77, v213, v203
	v_fma_f32 v78, v78, v213, v204
	v_fma_f32 v79, v79, v213, v205
	v_fma_f32 v72, v72, v213, v206
	v_fma_f32 v73, v73, v213, v207
	v_fma_f32 v74, v74, v213, v208
	v_fma_f32 v75, v75, v213, v209
	v_fma_f32 v68, v68, v213, v218
	v_fma_f32 v69, v69, v213, v219
	v_fma_f32 v70, v70, v213, v220
	v_fma_f32 v71, v71, v213, v221
	v_fma_f32 v64, v64, v213, v222
	v_fma_f32 v65, v65, v213, v223
	v_fma_f32 v66, v66, v213, v224
	v_fma_f32 v67, v67, v213, v225
	v_fma_f32 v60, v60, v214, v202
	v_fma_f32 v61, v61, v214, v203
	v_fma_f32 v62, v62, v214, v204
	v_fma_f32 v63, v63, v214, v205
	v_fma_f32 v56, v56, v214, v206
	v_fma_f32 v57, v57, v214, v207
	v_fma_f32 v58, v58, v214, v208
	v_fma_f32 v59, v59, v214, v209
	v_fma_f32 v52, v52, v214, v218
	v_fma_f32 v53, v53, v214, v219
	v_fma_f32 v54, v54, v214, v220
	v_fma_f32 v55, v55, v214, v221
	v_fma_f32 v48, v48, v214, v222
	v_fma_f32 v49, v49, v214, v223
	v_fma_f32 v50, v50, v214, v224
	v_fma_f32 v51, v51, v214, v225
	v_fma_f32 v44, v44, v215, v202
	v_fma_f32 v45, v45, v215, v203
	v_fma_f32 v46, v46, v215, v204
	v_fma_f32 v47, v47, v215, v205
	v_fma_f32 v40, v40, v215, v206
	v_fma_f32 v41, v41, v215, v207
	v_fma_f32 v42, v42, v215, v208
	v_fma_f32 v43, v43, v215, v209
	v_fma_f32 v36, v36, v215, v218
	v_fma_f32 v37, v37, v215, v219
	v_fma_f32 v38, v38, v215, v220
	v_fma_f32 v39, v39, v215, v221
	v_fma_f32 v32, v32, v215, v222
	v_fma_f32 v33, v33, v215, v223
	v_fma_f32 v34, v34, v215, v224
	v_fma_f32 v35, v35, v215, v225
	v_fma_f32 v28, v28, v216, v202
	v_fma_f32 v29, v29, v216, v203
	v_fma_f32 v30, v30, v216, v204
	v_fma_f32 v31, v31, v216, v205
	v_fma_f32 v24, v24, v216, v206
	v_fma_f32 v25, v25, v216, v207
	v_fma_f32 v26, v26, v216, v208
	v_fma_f32 v27, v27, v216, v209
	v_fma_f32 v20, v20, v216, v218
	v_fma_f32 v21, v21, v216, v219
	v_fma_f32 v22, v22, v216, v220
	v_fma_f32 v23, v23, v216, v221
	v_fma_f32 v16, v16, v216, v222
	v_fma_f32 v17, v17, v216, v223
	v_fma_f32 v18, v18, v216, v224
	v_fma_f32 v19, v19, v216, v225
	v_fma_f32 v12, v12, v217, v202
	v_fma_f32 v13, v13, v217, v203
	v_fma_f32 v14, v14, v217, v204
	v_fma_f32 v15, v15, v217, v205
	v_fma_f32 v8, v8, v217, v206
	v_fma_f32 v9, v9, v217, v207
	v_fma_f32 v10, v10, v217, v208
	v_fma_f32 v11, v11, v217, v209
	v_fma_f32 v4, v4, v217, v218
	v_fma_f32 v5, v5, v217, v219
	v_fma_f32 v6, v6, v217, v220
	v_fma_f32 v7, v7, v217, v221
	v_fma_f32 v0, v0, v217, v222
	v_fma_f32 v1, v1, v217, v223
	v_fma_f32 v2, v2, v217, v224
	v_fma_f32 v3, v3, v217, v225
	v_mov_b32_e32 v214, 0
	v_mov_b32_e32 v215, 0
	v_mov_b32_e32 v216, 0
	v_mov_b32_e32 v217, 0
	s_lshl_b32 s67, s32, 12
	s_sub_i32 s67, 0x2000, s67
	s_mul_i32 s89, s32, 0x1400
	s_add_i32 s89, s89, 0xc00
	s_lshl_b32 s57, s32, 10
	s_add_i32 s100, s57, 5120
	s_add_i32 s101, s57, 1024
	s_mov_b64 s[90:91], exec
	s_mov_b64 exec, s[78:79]
	v_add_u32_e32 v250, s67, v169
	ds_write_b128 v250, v[140:143] offset:0
	ds_write_b128 v250, v[136:139] offset:16
	ds_write_b128 v250, v[120:123] offset:512
	ds_write_b128 v250, v[112:115] offset:528
	v_add_u32_e32 v250, s100, v169
	ds_write_b128 v250, v[60:63] offset:0
	ds_write_b128 v250, v[56:59] offset:16
	ds_write_b128 v250, v[52:55] offset:512
	ds_write_b128 v250, v[48:51] offset:528
	ds_write_b128 v169, v[214:217] offset:0
	ds_write_b128 v169, v[214:217] offset:16
	ds_write_b128 v169, v[214:217] offset:512
	ds_write_b128 v169, v[214:217] offset:528
	s_mov_b64 exec, s[80:81]
	v_add_u32_e32 v251, s101, v169
	ds_write_b128 v251, v[76:79] offset:0
	ds_write_b128 v251, v[72:75] offset:16
	ds_write_b128 v251, v[68:71] offset:512
	ds_write_b128 v251, v[64:67] offset:528
	v_add_u32_e32 v251, s89, v169
	ds_write_b128 v251, v[12:15] offset:0
	ds_write_b128 v251, v[8:11] offset:16
	ds_write_b128 v251, v[4:7] offset:512
	ds_write_b128 v251, v[0:3] offset:528
	ds_write_b128 v169, v[214:217] offset:7168
	ds_write_b128 v169, v[214:217] offset:7184
	ds_write_b128 v169, v[214:217] offset:7680
	ds_write_b128 v169, v[214:217] offset:7696
	s_mov_b64 exec, s[90:91]
	s_cmp_eq_u32 s32, 0
	s_cselect_b64 s[92:93], s[78:79], 0
	s_cselect_b64 s[94:95], 0, s[80:81]
	s_mul_i32 s98, s88, 0x16000
	s_add_u32 s98, s98, 0x5b00000
	s_add_u32 s98, s98, s70
	s_addc_u32 s99, s71, 0
	s_mov_b64 exec, s[92:93]
	global_store_dwordx4 v177, v[140:143], s[98:99]
	global_store_dwordx4 v177, v[136:139], s[98:99] offset:16
	v_add_u32_e32 v250, 0x2c00, v177
	global_store_dwordx4 v250, v[120:123], s[98:99]
	global_store_dwordx4 v250, v[112:115], s[98:99] offset:16
	s_mov_b64 exec, s[94:95]
	v_add_u32_e32 v250, 0xb000, v177
	global_store_dwordx4 v250, v[12:15], s[98:99]
	global_store_dwordx4 v250, v[8:11], s[98:99] offset:16
	v_add_u32_e32 v250, 0xdc00, v177
	global_store_dwordx4 v250, v[4:7], s[98:99]
	global_store_dwordx4 v250, v[0:3], s[98:99] offset:16
	s_mov_b64 exec, s[90:91]
	s_waitcnt lgkmcnt(0)
	s_barrier
	ds_read_b128 v[186:189], v231 offset:0
	ds_read_b128 v[190:193], v231 offset:512
	ds_read_b128 v[194:197], v231 offset:2048
	ds_read_b128 v[198:201], v231 offset:2560
	s_waitcnt vmcnt(0)
	v_cndmask_b32_e64 v218, 0, v116, s[78:79]
	v_cndmask_b32_e64 v222, 0, v128, s[80:81]
	v_cndmask_b32_e64 v219, 0, v117, s[78:79]
	v_cndmask_b32_e64 v223, 0, v129, s[80:81]
	v_cndmask_b32_e64 v220, 0, v118, s[78:79]
	v_cndmask_b32_e64 v224, 0, v130, s[80:81]
	v_cndmask_b32_e64 v221, 0, v119, s[78:79]
	v_cndmask_b32_e64 v225, 0, v131, s[80:81]
	v_cndmask_b32_e64 v226, 0, v160, s[78:79]
	v_cndmask_b32_e64 v232, 0, v178, s[80:81]
	v_cndmask_b32_e64 v227, 0, v161, s[78:79]
	v_cndmask_b32_e64 v233, 0, v179, s[80:81]
	v_cndmask_b32_e64 v228, 0, v162, s[78:79]
	v_cndmask_b32_e64 v234, 0, v180, s[80:81]
	v_cndmask_b32_e64 v229, 0, v163, s[78:79]
	v_cndmask_b32_e64 v235, 0, v181, s[80:81]
	s_waitcnt lgkmcnt(0)
	s_nop 1
	v_fma_f32 v202, v124, v140, v132
	v_fma_f32 v203, v125, v141, v133
	v_fma_f32 v204, v126, v142, v134
	v_fma_f32 v205, v127, v143, v135
	v_fmac_f32_dpp v202, v76, v116 row_shr:1 row_mask:0xf bank_mask:0xf
	v_fmac_f32_dpp v203, v77, v117 row_shr:1 row_mask:0xf bank_mask:0xf
	v_fmac_f32_dpp v204, v78, v118 row_shr:1 row_mask:0xf bank_mask:0xf
	v_fmac_f32_dpp v205, v79, v119 row_shr:1 row_mask:0xf bank_mask:0xf
	v_fmac_f32_e32 v202, v186, v218
	v_fmac_f32_e32 v203, v187, v219
	v_fmac_f32_e32 v204, v188, v220
	v_fmac_f32_e32 v205, v189, v221
	v_fmac_f32_e32 v202, v108, v128
	v_fmac_f32_e32 v203, v109, v129
	v_fmac_f32_e32 v204, v110, v130
	v_fmac_f32_e32 v205, v111, v131
	v_fma_f32 v206, v164, v120, v182
	v_fma_f32 v207, v165, v121, v183
	v_fma_f32 v208, v166, v122, v184
	v_fma_f32 v209, v167, v123, v185
	v_fmac_f32_dpp v206, v68, v160 row_shr:1 row_mask:0xf bank_mask:0xf
	v_fmac_f32_dpp v207, v69, v161 row_shr:1 row_mask:0xf bank_mask:0xf
	v_fmac_f32_dpp v208, v70, v162 row_shr:1 row_mask:0xf bank_mask:0xf
	v_fmac_f32_dpp v209, v71, v163 row_shr:1 row_mask:0xf bank_mask:0xf
	v_fmac_f32_e32 v206, v190, v226
	v_fmac_f32_e32 v207, v191, v227
	v_fmac_f32_e32 v208, v192, v228
	v_fmac_f32_e32 v209, v193, v229
	v_fmac_f32_e32 v206, v100, v178
	v_fmac_f32_e32 v207, v101, v179
	v_fmac_f32_e32 v208, v102, v180
	v_fmac_f32_e32 v209, v103, v181
	s_mov_b64 exec, s[92:93]
	v_add_u32_e32 v250, 0x5800, v177
	global_store_dwordx4 v250, v[202:205], s[98:99]
	v_add_u32_e32 v250, 0x8400, v177
	global_store_dwordx4 v250, v[206:209], s[98:99]
	s_mov_b64 exec, s[90:91]
	s_nop 4
	v_mul_f32_e32 v210, 0xbfb8aa3b, v202
	v_mul_f32_e32 v211, 0xbfb8aa3b, v203
	v_mul_f32_e32 v212, 0xbfb8aa3b, v204
	v_mul_f32_e32 v213, 0xbfb8aa3b, v205
	v_exp_f32_e32 v210, v210
	v_exp_f32_e32 v211, v211
	v_exp_f32_e32 v212, v212
	v_exp_f32_e32 v213, v213
	v_add_f32_e32 v210, 1.0, v210
	v_add_f32_e32 v211, 1.0, v211
	v_add_f32_e32 v212, 1.0, v212
	v_add_f32_e32 v213, 1.0, v213
	v_rcp_f32_e32 v210, v210
	v_rcp_f32_e32 v211, v211
	v_rcp_f32_e32 v212, v212
	v_rcp_f32_e32 v213, v213
	v_mul_f32_e32 v202, v202, v210
	v_mul_f32_e32 v203, v203, v211
	v_mul_f32_e32 v204, v204, v212
	v_mul_f32_e32 v205, v205, v213
	v_mul_f32_e32 v202, v202, v206
	v_mul_f32_e32 v203, v203, v207
	v_mul_f32_e32 v204, v204, v208
	v_mul_f32_e32 v205, v205, v209
	v_cvt_pk_bf16_f32 v236, v202, v203
	v_cvt_pk_bf16_f32 v237, v204, v205
	v_fma_f32 v202, v124, v108, v132
	v_fma_f32 v203, v125, v109, v133
	v_fma_f32 v204, v126, v110, v134
	v_fma_f32 v205, v127, v111, v135
	v_fmac_f32_e32 v202, v140, v116
	v_fmac_f32_e32 v203, v141, v117
	v_fmac_f32_e32 v204, v142, v118
	v_fmac_f32_e32 v205, v143, v119
	v_fmac_f32_e32 v202, v92, v128
	v_fmac_f32_e32 v203, v93, v129
	v_fmac_f32_e32 v204, v94, v130
	v_fmac_f32_e32 v205, v95, v131
	v_fma_f32 v206, v164, v100, v182
	v_fma_f32 v207, v165, v101, v183
	v_fma_f32 v208, v166, v102, v184
	v_fma_f32 v209, v167, v103, v185
	v_fmac_f32_e32 v206, v120, v160
	v_fmac_f32_e32 v207, v121, v161
	v_fmac_f32_e32 v208, v122, v162
	v_fmac_f32_e32 v209, v123, v163
	v_fmac_f32_e32 v206, v84, v178
	v_fmac_f32_e32 v207, v85, v179
	v_fmac_f32_e32 v208, v86, v180
	v_fmac_f32_e32 v209, v87, v181
	v_mul_f32_e32 v210, 0xbfb8aa3b, v202
	v_mul_f32_e32 v211, 0xbfb8aa3b, v203
	v_mul_f32_e32 v212, 0xbfb8aa3b, v204
	v_mul_f32_e32 v213, 0xbfb8aa3b, v205
	v_exp_f32_e32 v210, v210
	v_exp_f32_e32 v211, v211
	v_exp_f32_e32 v212, v212
	v_exp_f32_e32 v213, v213
	v_add_f32_e32 v210, 1.0, v210
	v_add_f32_e32 v211, 1.0, v211
	v_add_f32_e32 v212, 1.0, v212
	v_add_f32_e32 v213, 1.0, v213
	v_rcp_f32_e32 v210, v210
	v_rcp_f32_e32 v211, v211
	v_rcp_f32_e32 v212, v212
	v_rcp_f32_e32 v213, v213
	v_mul_f32_e32 v202, v202, v210
	v_mul_f32_e32 v203, v203, v211
	v_mul_f32_e32 v204, v204, v212
	v_mul_f32_e32 v205, v205, v213
	v_mul_f32_e32 v202, v202, v206
	v_mul_f32_e32 v203, v203, v207
	v_mul_f32_e32 v204, v204, v208
	v_mul_f32_e32 v205, v205, v209
	v_cvt_pk_bf16_f32 v238, v202, v203
	v_cvt_pk_bf16_f32 v239, v204, v205
	v_fma_f32 v202, v124, v92, v132
	v_fma_f32 v203, v125, v93, v133
	v_fma_f32 v204, v126, v94, v134
	v_fma_f32 v205, v127, v95, v135
	v_fmac_f32_e32 v202, v108, v116
	v_fmac_f32_e32 v203, v109, v117
	v_fmac_f32_e32 v204, v110, v118
	v_fmac_f32_e32 v205, v111, v119
	v_fmac_f32_e32 v202, v76, v128
	v_fmac_f32_e32 v203, v77, v129
	v_fmac_f32_e32 v204, v78, v130
	v_fmac_f32_e32 v205, v79, v131
	v_fma_f32 v206, v164, v84, v182
	v_fma_f32 v207, v165, v85, v183
	v_fma_f32 v208, v166, v86, v184
	v_fma_f32 v209, v167, v87, v185
	v_fmac_f32_e32 v206, v100, v160
	v_fmac_f32_e32 v207, v101, v161
	v_fmac_f32_e32 v208, v102, v162
	v_fmac_f32_e32 v209, v103, v163
	v_fmac_f32_e32 v206, v68, v178
	v_fmac_f32_e32 v207, v69, v179
	v_fmac_f32_e32 v208, v70, v180
	v_fmac_f32_e32 v209, v71, v181
	v_mul_f32_e32 v210, 0xbfb8aa3b, v202
	v_mul_f32_e32 v211, 0xbfb8aa3b, v203
	v_mul_f32_e32 v212, 0xbfb8aa3b, v204
	v_mul_f32_e32 v213, 0xbfb8aa3b, v205
	v_exp_f32_e32 v210, v210
	v_exp_f32_e32 v211, v211
	v_exp_f32_e32 v212, v212
	v_exp_f32_e32 v213, v213
	v_add_f32_e32 v210, 1.0, v210
	v_add_f32_e32 v211, 1.0, v211
	v_add_f32_e32 v212, 1.0, v212
	v_add_f32_e32 v213, 1.0, v213
	v_rcp_f32_e32 v210, v210
	v_rcp_f32_e32 v211, v211
	v_rcp_f32_e32 v212, v212
	v_rcp_f32_e32 v213, v213
	v_mul_f32_e32 v202, v202, v210
	v_mul_f32_e32 v203, v203, v211
	v_mul_f32_e32 v204, v204, v212
	v_mul_f32_e32 v205, v205, v213
	v_mul_f32_e32 v202, v202, v206
	v_mul_f32_e32 v203, v203, v207
	v_mul_f32_e32 v204, v204, v208
	v_mul_f32_e32 v205, v205, v209
	v_cvt_pk_bf16_f32 v240, v202, v203
	v_cvt_pk_bf16_f32 v241, v204, v205
	v_fma_f32 v202, v124, v76, v132
	v_fma_f32 v203, v125, v77, v133
	v_fma_f32 v204, v126, v78, v134
	v_fma_f32 v205, v127, v79, v135
	v_fmac_f32_e32 v202, v92, v116
	v_fmac_f32_e32 v203, v93, v117
	v_fmac_f32_e32 v204, v94, v118
	v_fmac_f32_e32 v205, v95, v119
	v_fmac_f32_dpp v202, v140, v128 row_shl:1 row_mask:0xf bank_mask:0xf
	v_fmac_f32_dpp v203, v141, v129 row_shl:1 row_mask:0xf bank_mask:0xf
	v_fmac_f32_dpp v204, v142, v130 row_shl:1 row_mask:0xf bank_mask:0xf
	v_fmac_f32_dpp v205, v143, v131 row_shl:1 row_mask:0xf bank_mask:0xf
	v_fmac_f32_e32 v202, v186, v222
	v_fmac_f32_e32 v203, v187, v223
	v_fmac_f32_e32 v204, v188, v224
	v_fmac_f32_e32 v205, v189, v225
	v_fma_f32 v206, v164, v68, v182
	v_fma_f32 v207, v165, v69, v183
	v_fma_f32 v208, v166, v70, v184
	v_fma_f32 v209, v167, v71, v185
	v_fmac_f32_e32 v206, v84, v160
	v_fmac_f32_e32 v207, v85, v161
	v_fmac_f32_e32 v208, v86, v162
	v_fmac_f32_e32 v209, v87, v163
	v_fmac_f32_dpp v206, v120, v178 row_shl:1 row_mask:0xf bank_mask:0xf
	v_fmac_f32_dpp v207, v121, v179 row_shl:1 row_mask:0xf bank_mask:0xf
	v_fmac_f32_dpp v208, v122, v180 row_shl:1 row_mask:0xf bank_mask:0xf
	v_fmac_f32_dpp v209, v123, v181 row_shl:1 row_mask:0xf bank_mask:0xf
	v_fmac_f32_e32 v206, v190, v232
	v_fmac_f32_e32 v207, v191, v233
	v_fmac_f32_e32 v208, v192, v234
	v_fmac_f32_e32 v209, v193, v235
	v_mul_f32_e32 v210, 0xbfb8aa3b, v202
	v_mul_f32_e32 v211, 0xbfb8aa3b, v203
	v_mul_f32_e32 v212, 0xbfb8aa3b, v204
	v_mul_f32_e32 v213, 0xbfb8aa3b, v205
	v_exp_f32_e32 v210, v210
	v_exp_f32_e32 v211, v211
	v_exp_f32_e32 v212, v212
	v_exp_f32_e32 v213, v213
	v_add_f32_e32 v210, 1.0, v210
	v_add_f32_e32 v211, 1.0, v211
	v_add_f32_e32 v212, 1.0, v212
	v_add_f32_e32 v213, 1.0, v213
	v_rcp_f32_e32 v210, v210
	v_rcp_f32_e32 v211, v211
	v_rcp_f32_e32 v212, v212
	v_rcp_f32_e32 v213, v213
	v_mul_f32_e32 v202, v202, v210
	v_mul_f32_e32 v203, v203, v211
	v_mul_f32_e32 v204, v204, v212
	v_mul_f32_e32 v205, v205, v213
	v_mul_f32_e32 v202, v202, v206
	v_mul_f32_e32 v203, v203, v207
	v_mul_f32_e32 v204, v204, v208
	v_mul_f32_e32 v205, v205, v209
	v_cvt_pk_bf16_f32 v242, v202, v203
	v_cvt_pk_bf16_f32 v243, v204, v205
	v_fma_f32 v202, v124, v60, v132
	v_fma_f32 v203, v125, v61, v133
	v_fma_f32 v204, v126, v62, v134
	v_fma_f32 v205, v127, v63, v135
	v_fmac_f32_dpp v202, v12, v116 row_shr:1 row_mask:0xf bank_mask:0xf
	v_fmac_f32_dpp v203, v13, v117 row_shr:1 row_mask:0xf bank_mask:0xf
	v_fmac_f32_dpp v204, v14, v118 row_shr:1 row_mask:0xf bank_mask:0xf
	v_fmac_f32_dpp v205, v15, v119 row_shr:1 row_mask:0xf bank_mask:0xf
	v_fmac_f32_e32 v202, v194, v218
	v_fmac_f32_e32 v203, v195, v219
	v_fmac_f32_e32 v204, v196, v220
	v_fmac_f32_e32 v205, v197, v221
	v_fmac_f32_e32 v202, v44, v128
	v_fmac_f32_e32 v203, v45, v129
	v_fmac_f32_e32 v204, v46, v130
	v_fmac_f32_e32 v205, v47, v131
	v_fma_f32 v206, v164, v52, v182
	v_fma_f32 v207, v165, v53, v183
	v_fma_f32 v208, v166, v54, v184
	v_fma_f32 v209, v167, v55, v185
	v_fmac_f32_dpp v206, v4, v160 row_shr:1 row_mask:0xf bank_mask:0xf
	v_fmac_f32_dpp v207, v5, v161 row_shr:1 row_mask:0xf bank_mask:0xf
	v_fmac_f32_dpp v208, v6, v162 row_shr:1 row_mask:0xf bank_mask:0xf
	v_fmac_f32_dpp v209, v7, v163 row_shr:1 row_mask:0xf bank_mask:0xf
	v_fmac_f32_e32 v206, v198, v226
	v_fmac_f32_e32 v207, v199, v227
	v_fmac_f32_e32 v208, v200, v228
	v_fmac_f32_e32 v209, v201, v229
	v_fmac_f32_e32 v206, v36, v178
	v_fmac_f32_e32 v207, v37, v179
	v_fmac_f32_e32 v208, v38, v180
	v_fmac_f32_e32 v209, v39, v181
	v_mul_f32_e32 v210, 0xbfb8aa3b, v202
	v_mul_f32_e32 v211, 0xbfb8aa3b, v203
	v_mul_f32_e32 v212, 0xbfb8aa3b, v204
	v_mul_f32_e32 v213, 0xbfb8aa3b, v205
	v_exp_f32_e32 v210, v210
	v_exp_f32_e32 v211, v211
	v_exp_f32_e32 v212, v212
	v_exp_f32_e32 v213, v213
	v_add_f32_e32 v210, 1.0, v210
	v_add_f32_e32 v211, 1.0, v211
	v_add_f32_e32 v212, 1.0, v212
	v_add_f32_e32 v213, 1.0, v213
	v_rcp_f32_e32 v210, v210
	v_rcp_f32_e32 v211, v211
	v_rcp_f32_e32 v212, v212
	v_rcp_f32_e32 v213, v213
	v_mul_f32_e32 v202, v202, v210
	v_mul_f32_e32 v203, v203, v211
	v_mul_f32_e32 v204, v204, v212
	v_mul_f32_e32 v205, v205, v213
	v_mul_f32_e32 v202, v202, v206
	v_mul_f32_e32 v203, v203, v207
	v_mul_f32_e32 v204, v204, v208
	v_mul_f32_e32 v205, v205, v209
	v_cvt_pk_bf16_f32 v244, v202, v203
	v_cvt_pk_bf16_f32 v245, v204, v205
	v_fma_f32 v202, v124, v44, v132
	v_fma_f32 v203, v125, v45, v133
	v_fma_f32 v204, v126, v46, v134
	v_fma_f32 v205, v127, v47, v135
	v_fmac_f32_e32 v202, v60, v116
	v_fmac_f32_e32 v203, v61, v117
	v_fmac_f32_e32 v204, v62, v118
	v_fmac_f32_e32 v205, v63, v119
	v_fmac_f32_e32 v202, v28, v128
	v_fmac_f32_e32 v203, v29, v129
	v_fmac_f32_e32 v204, v30, v130
	v_fmac_f32_e32 v205, v31, v131
	v_fma_f32 v206, v164, v36, v182
	v_fma_f32 v207, v165, v37, v183
	v_fma_f32 v208, v166, v38, v184
	v_fma_f32 v209, v167, v39, v185
	v_fmac_f32_e32 v206, v52, v160
	v_fmac_f32_e32 v207, v53, v161
	v_fmac_f32_e32 v208, v54, v162
	v_fmac_f32_e32 v209, v55, v163
	v_fmac_f32_e32 v206, v20, v178
	v_fmac_f32_e32 v207, v21, v179
	v_fmac_f32_e32 v208, v22, v180
	v_fmac_f32_e32 v209, v23, v181
	v_mul_f32_e32 v210, 0xbfb8aa3b, v202
	v_mul_f32_e32 v211, 0xbfb8aa3b, v203
	v_mul_f32_e32 v212, 0xbfb8aa3b, v204
	v_mul_f32_e32 v213, 0xbfb8aa3b, v205
	v_exp_f32_e32 v210, v210
	v_exp_f32_e32 v211, v211
	v_exp_f32_e32 v212, v212
	v_exp_f32_e32 v213, v213
	v_add_f32_e32 v210, 1.0, v210
	v_add_f32_e32 v211, 1.0, v211
	v_add_f32_e32 v212, 1.0, v212
	v_add_f32_e32 v213, 1.0, v213
	v_rcp_f32_e32 v210, v210
	v_rcp_f32_e32 v211, v211
	v_rcp_f32_e32 v212, v212
	v_rcp_f32_e32 v213, v213
	v_mul_f32_e32 v202, v202, v210
	v_mul_f32_e32 v203, v203, v211
	v_mul_f32_e32 v204, v204, v212
	v_mul_f32_e32 v205, v205, v213
	v_mul_f32_e32 v202, v202, v206
	v_mul_f32_e32 v203, v203, v207
	v_mul_f32_e32 v204, v204, v208
	v_mul_f32_e32 v205, v205, v209
	v_cvt_pk_bf16_f32 v246, v202, v203
	v_cvt_pk_bf16_f32 v247, v204, v205
	v_fma_f32 v202, v124, v28, v132
	v_fma_f32 v203, v125, v29, v133
	v_fma_f32 v204, v126, v30, v134
	v_fma_f32 v205, v127, v31, v135
	v_fmac_f32_e32 v202, v44, v116
	v_fmac_f32_e32 v203, v45, v117
	v_fmac_f32_e32 v204, v46, v118
	v_fmac_f32_e32 v205, v47, v119
	v_fmac_f32_e32 v202, v12, v128
	v_fmac_f32_e32 v203, v13, v129
	v_fmac_f32_e32 v204, v14, v130
	v_fmac_f32_e32 v205, v15, v131
	v_fma_f32 v206, v164, v20, v182
	v_fma_f32 v207, v165, v21, v183
	v_fma_f32 v208, v166, v22, v184
	v_fma_f32 v209, v167, v23, v185
	v_fmac_f32_e32 v206, v36, v160
	v_fmac_f32_e32 v207, v37, v161
	v_fmac_f32_e32 v208, v38, v162
	v_fmac_f32_e32 v209, v39, v163
	v_fmac_f32_e32 v206, v4, v178
	v_fmac_f32_e32 v207, v5, v179
	v_fmac_f32_e32 v208, v6, v180
	v_fmac_f32_e32 v209, v7, v181
	v_mul_f32_e32 v210, 0xbfb8aa3b, v202
	v_mul_f32_e32 v211, 0xbfb8aa3b, v203
	v_mul_f32_e32 v212, 0xbfb8aa3b, v204
	v_mul_f32_e32 v213, 0xbfb8aa3b, v205
	v_exp_f32_e32 v210, v210
	v_exp_f32_e32 v211, v211
	v_exp_f32_e32 v212, v212
	v_exp_f32_e32 v213, v213
	v_add_f32_e32 v210, 1.0, v210
	v_add_f32_e32 v211, 1.0, v211
	v_add_f32_e32 v212, 1.0, v212
	v_add_f32_e32 v213, 1.0, v213
	v_rcp_f32_e32 v210, v210
	v_rcp_f32_e32 v211, v211
	v_rcp_f32_e32 v212, v212
	v_rcp_f32_e32 v213, v213
	v_mul_f32_e32 v202, v202, v210
	v_mul_f32_e32 v203, v203, v211
	v_mul_f32_e32 v204, v204, v212
	v_mul_f32_e32 v205, v205, v213
	v_mul_f32_e32 v202, v202, v206
	v_mul_f32_e32 v203, v203, v207
	v_mul_f32_e32 v204, v204, v208
	v_mul_f32_e32 v205, v205, v209
	v_cvt_pk_bf16_f32 v248, v202, v203
	v_cvt_pk_bf16_f32 v249, v204, v205
	v_fma_f32 v202, v124, v12, v132
	v_fma_f32 v203, v125, v13, v133
	v_fma_f32 v204, v126, v14, v134
	v_fma_f32 v205, v127, v15, v135
	v_fmac_f32_e32 v202, v28, v116
	v_fmac_f32_e32 v203, v29, v117
	v_fmac_f32_e32 v204, v30, v118
	v_fmac_f32_e32 v205, v31, v119
	v_fmac_f32_dpp v202, v60, v128 row_shl:1 row_mask:0xf bank_mask:0xf
	v_fmac_f32_dpp v203, v61, v129 row_shl:1 row_mask:0xf bank_mask:0xf
	v_fmac_f32_dpp v204, v62, v130 row_shl:1 row_mask:0xf bank_mask:0xf
	v_fmac_f32_dpp v205, v63, v131 row_shl:1 row_mask:0xf bank_mask:0xf
	v_fmac_f32_e32 v202, v194, v222
	v_fmac_f32_e32 v203, v195, v223
	v_fmac_f32_e32 v204, v196, v224
	v_fmac_f32_e32 v205, v197, v225
	v_fma_f32 v206, v164, v4, v182
	v_fma_f32 v207, v165, v5, v183
	v_fma_f32 v208, v166, v6, v184
	v_fma_f32 v209, v167, v7, v185
	v_fmac_f32_e32 v206, v20, v160
	v_fmac_f32_e32 v207, v21, v161
	v_fmac_f32_e32 v208, v22, v162
	v_fmac_f32_e32 v209, v23, v163
	v_fmac_f32_dpp v206, v52, v178 row_shl:1 row_mask:0xf bank_mask:0xf
	v_fmac_f32_dpp v207, v53, v179 row_shl:1 row_mask:0xf bank_mask:0xf
	v_fmac_f32_dpp v208, v54, v180 row_shl:1 row_mask:0xf bank_mask:0xf
	v_fmac_f32_dpp v209, v55, v181 row_shl:1 row_mask:0xf bank_mask:0xf
	v_fmac_f32_e32 v206, v198, v232
	v_fmac_f32_e32 v207, v199, v233
	v_fmac_f32_e32 v208, v200, v234
	v_fmac_f32_e32 v209, v201, v235
	s_mov_b64 exec, s[94:95]
	v_add_u32_e32 v250, 0x10800, v177
	global_store_dwordx4 v250, v[202:205], s[98:99]
	v_add_u32_e32 v250, 0x13400, v177
	global_store_dwordx4 v250, v[206:209], s[98:99]
	s_mov_b64 exec, s[90:91]
	s_nop 4
	v_mul_f32_e32 v210, 0xbfb8aa3b, v202
	v_mul_f32_e32 v211, 0xbfb8aa3b, v203
	v_mul_f32_e32 v212, 0xbfb8aa3b, v204
	v_mul_f32_e32 v213, 0xbfb8aa3b, v205
	v_exp_f32_e32 v210, v210
	v_exp_f32_e32 v211, v211
	v_exp_f32_e32 v212, v212
	v_exp_f32_e32 v213, v213
	v_add_f32_e32 v210, 1.0, v210
	v_add_f32_e32 v211, 1.0, v211
	v_add_f32_e32 v212, 1.0, v212
	v_add_f32_e32 v213, 1.0, v213
	v_rcp_f32_e32 v210, v210
	v_rcp_f32_e32 v211, v211
	v_rcp_f32_e32 v212, v212
	v_rcp_f32_e32 v213, v213
	v_mul_f32_e32 v202, v202, v210
	v_mul_f32_e32 v203, v203, v211
	v_mul_f32_e32 v204, v204, v212
	v_mul_f32_e32 v205, v205, v213
	v_mul_f32_e32 v202, v202, v206
	v_mul_f32_e32 v203, v203, v207
	v_mul_f32_e32 v204, v204, v208
	v_mul_f32_e32 v205, v205, v209
	v_cvt_pk_bf16_f32 v250, v202, v203
	v_cvt_pk_bf16_f32 v251, v204, v205
	global_load_dwordx4 v[116:119], v177, s[2:3] offset:16
	v_add_u32_e32 v213, 0x5800, v177
	global_load_dwordx4 v[124:127], v213, s[2:3] offset:16
	v_add_u32_e32 v212, 0xb000, v177
	global_load_dwordx4 v[128:131], v212, s[2:3] offset:16
	global_load_dwordx4 v[132:135], v177, s[28:29] offset:16
	v_add_u32_e32 v212, 0x2c00, v177
	global_load_dwordx4 v[160:163], v212, s[2:3] offset:16
	v_add_u32_e32 v213, 0x8400, v177
	global_load_dwordx4 v[164:167], v213, s[2:3] offset:16
	v_add_u32_e32 v212, 0xdc00, v177
	global_load_dwordx4 v[178:181], v212, s[2:3] offset:16
	v_add_u32_e32 v213, 0x2c00, v177
	global_load_dwordx4 v[182:185], v213, s[28:29] offset:16
	v_mov_b32_e32 v140, v236
	v_mov_b32_e32 v141, v237
	v_mov_b32_e32 v108, v238
	v_mov_b32_e32 v109, v239
	v_mov_b32_e32 v92, v240
	v_mov_b32_e32 v93, v241
	v_mov_b32_e32 v76, v242
	v_mov_b32_e32 v77, v243
	v_mov_b32_e32 v60, v244
	v_mov_b32_e32 v61, v245
	v_mov_b32_e32 v44, v246
	v_mov_b32_e32 v45, v247
	v_mov_b32_e32 v28, v248
	v_mov_b32_e32 v29, v249
	v_mov_b32_e32 v12, v250
	v_mov_b32_e32 v13, v251
	ds_read_b128 v[186:189], v231 offset:16
	ds_read_b128 v[190:193], v231 offset:528
	ds_read_b128 v[194:197], v231 offset:2064
	ds_read_b128 v[198:201], v231 offset:2576
	s_waitcnt vmcnt(0)
	v_cndmask_b32_e64 v218, 0, v116, s[78:79]
	v_cndmask_b32_e64 v222, 0, v128, s[80:81]
	v_cndmask_b32_e64 v219, 0, v117, s[78:79]
	v_cndmask_b32_e64 v223, 0, v129, s[80:81]
	v_cndmask_b32_e64 v220, 0, v118, s[78:79]
	v_cndmask_b32_e64 v224, 0, v130, s[80:81]
	v_cndmask_b32_e64 v221, 0, v119, s[78:79]
	v_cndmask_b32_e64 v225, 0, v131, s[80:81]
	v_cndmask_b32_e64 v226, 0, v160, s[78:79]
	v_cndmask_b32_e64 v232, 0, v178, s[80:81]
	v_cndmask_b32_e64 v227, 0, v161, s[78:79]
	v_cndmask_b32_e64 v233, 0, v179, s[80:81]
	v_cndmask_b32_e64 v228, 0, v162, s[78:79]
	v_cndmask_b32_e64 v234, 0, v180, s[80:81]
	v_cndmask_b32_e64 v229, 0, v163, s[78:79]
	v_cndmask_b32_e64 v235, 0, v181, s[80:81]
	s_waitcnt lgkmcnt(0)
	s_nop 1
	v_fma_f32 v202, v124, v136, v132
	v_fma_f32 v203, v125, v137, v133
	v_fma_f32 v204, v126, v138, v134
	v_fma_f32 v205, v127, v139, v135
	v_fmac_f32_dpp v202, v72, v116 row_shr:1 row_mask:0xf bank_mask:0xf
	v_fmac_f32_dpp v203, v73, v117 row_shr:1 row_mask:0xf bank_mask:0xf
	v_fmac_f32_dpp v204, v74, v118 row_shr:1 row_mask:0xf bank_mask:0xf
	v_fmac_f32_dpp v205, v75, v119 row_shr:1 row_mask:0xf bank_mask:0xf
	v_fmac_f32_e32 v202, v186, v218
	v_fmac_f32_e32 v203, v187, v219
	v_fmac_f32_e32 v204, v188, v220
	v_fmac_f32_e32 v205, v189, v221
	v_fmac_f32_e32 v202, v104, v128
	v_fmac_f32_e32 v203, v105, v129
	v_fmac_f32_e32 v204, v106, v130
	v_fmac_f32_e32 v205, v107, v131
	v_fma_f32 v206, v164, v112, v182
	v_fma_f32 v207, v165, v113, v183
	v_fma_f32 v208, v166, v114, v184
	v_fma_f32 v209, v167, v115, v185
	v_fmac_f32_dpp v206, v64, v160 row_shr:1 row_mask:0xf bank_mask:0xf
	v_fmac_f32_dpp v207, v65, v161 row_shr:1 row_mask:0xf bank_mask:0xf
	v_fmac_f32_dpp v208, v66, v162 row_shr:1 row_mask:0xf bank_mask:0xf
	v_fmac_f32_dpp v209, v67, v163 row_shr:1 row_mask:0xf bank_mask:0xf
	v_fmac_f32_e32 v206, v190, v226
	v_fmac_f32_e32 v207, v191, v227
	v_fmac_f32_e32 v208, v192, v228
	v_fmac_f32_e32 v209, v193, v229
	v_fmac_f32_e32 v206, v96, v178
	v_fmac_f32_e32 v207, v97, v179
	v_fmac_f32_e32 v208, v98, v180
	v_fmac_f32_e32 v209, v99, v181
	s_mov_b64 exec, s[92:93]
	v_add_u32_e32 v250, 0x5800, v177
	global_store_dwordx4 v250, v[202:205], s[98:99] offset:16
	v_add_u32_e32 v250, 0x8400, v177
	global_store_dwordx4 v250, v[206:209], s[98:99] offset:16
	s_mov_b64 exec, s[90:91]
	s_nop 4
	v_mul_f32_e32 v210, 0xbfb8aa3b, v202
	v_mul_f32_e32 v211, 0xbfb8aa3b, v203
	v_mul_f32_e32 v212, 0xbfb8aa3b, v204
	v_mul_f32_e32 v213, 0xbfb8aa3b, v205
	v_exp_f32_e32 v210, v210
	v_exp_f32_e32 v211, v211
	v_exp_f32_e32 v212, v212
	v_exp_f32_e32 v213, v213
	v_add_f32_e32 v210, 1.0, v210
	v_add_f32_e32 v211, 1.0, v211
	v_add_f32_e32 v212, 1.0, v212
	v_add_f32_e32 v213, 1.0, v213
	v_rcp_f32_e32 v210, v210
	v_rcp_f32_e32 v211, v211
	v_rcp_f32_e32 v212, v212
	v_rcp_f32_e32 v213, v213
	v_mul_f32_e32 v202, v202, v210
	v_mul_f32_e32 v203, v203, v211
	v_mul_f32_e32 v204, v204, v212
	v_mul_f32_e32 v205, v205, v213
	v_mul_f32_e32 v202, v202, v206
	v_mul_f32_e32 v203, v203, v207
	v_mul_f32_e32 v204, v204, v208
	v_mul_f32_e32 v205, v205, v209
	v_cvt_pk_bf16_f32 v142, v202, v203
	v_cvt_pk_bf16_f32 v143, v204, v205
	v_fma_f32 v202, v124, v104, v132
	v_fma_f32 v203, v125, v105, v133
	v_fma_f32 v204, v126, v106, v134
	v_fma_f32 v205, v127, v107, v135
	v_fmac_f32_e32 v202, v136, v116
	v_fmac_f32_e32 v203, v137, v117
	v_fmac_f32_e32 v204, v138, v118
	v_fmac_f32_e32 v205, v139, v119
	v_fmac_f32_e32 v202, v88, v128
	v_fmac_f32_e32 v203, v89, v129
	v_fmac_f32_e32 v204, v90, v130
	v_fmac_f32_e32 v205, v91, v131
	v_fma_f32 v206, v164, v96, v182
	v_fma_f32 v207, v165, v97, v183
	v_fma_f32 v208, v166, v98, v184
	v_fma_f32 v209, v167, v99, v185
	v_fmac_f32_e32 v206, v112, v160
	v_fmac_f32_e32 v207, v113, v161
	v_fmac_f32_e32 v208, v114, v162
	v_fmac_f32_e32 v209, v115, v163
	v_fmac_f32_e32 v206, v80, v178
	v_fmac_f32_e32 v207, v81, v179
	v_fmac_f32_e32 v208, v82, v180
	v_fmac_f32_e32 v209, v83, v181
	v_mul_f32_e32 v210, 0xbfb8aa3b, v202
	v_mul_f32_e32 v211, 0xbfb8aa3b, v203
	v_mul_f32_e32 v212, 0xbfb8aa3b, v204
	v_mul_f32_e32 v213, 0xbfb8aa3b, v205
	v_exp_f32_e32 v210, v210
	v_exp_f32_e32 v211, v211
	v_exp_f32_e32 v212, v212
	v_exp_f32_e32 v213, v213
	v_add_f32_e32 v210, 1.0, v210
	v_add_f32_e32 v211, 1.0, v211
	v_add_f32_e32 v212, 1.0, v212
	v_add_f32_e32 v213, 1.0, v213
	v_rcp_f32_e32 v210, v210
	v_rcp_f32_e32 v211, v211
	v_rcp_f32_e32 v212, v212
	v_rcp_f32_e32 v213, v213
	v_mul_f32_e32 v202, v202, v210
	v_mul_f32_e32 v203, v203, v211
	v_mul_f32_e32 v204, v204, v212
	v_mul_f32_e32 v205, v205, v213
	v_mul_f32_e32 v202, v202, v206
	v_mul_f32_e32 v203, v203, v207
	v_mul_f32_e32 v204, v204, v208
	v_mul_f32_e32 v205, v205, v209
	v_cvt_pk_bf16_f32 v110, v202, v203
	v_cvt_pk_bf16_f32 v111, v204, v205
	v_fma_f32 v202, v124, v88, v132
	v_fma_f32 v203, v125, v89, v133
	v_fma_f32 v204, v126, v90, v134
	v_fma_f32 v205, v127, v91, v135
	v_fmac_f32_e32 v202, v104, v116
	v_fmac_f32_e32 v203, v105, v117
	v_fmac_f32_e32 v204, v106, v118
	v_fmac_f32_e32 v205, v107, v119
	v_fmac_f32_e32 v202, v72, v128
	v_fmac_f32_e32 v203, v73, v129
	v_fmac_f32_e32 v204, v74, v130
	v_fmac_f32_e32 v205, v75, v131
	v_fma_f32 v206, v164, v80, v182
	v_fma_f32 v207, v165, v81, v183
	v_fma_f32 v208, v166, v82, v184
	v_fma_f32 v209, v167, v83, v185
	v_fmac_f32_e32 v206, v96, v160
	v_fmac_f32_e32 v207, v97, v161
	v_fmac_f32_e32 v208, v98, v162
	v_fmac_f32_e32 v209, v99, v163
	v_fmac_f32_e32 v206, v64, v178
	v_fmac_f32_e32 v207, v65, v179
	v_fmac_f32_e32 v208, v66, v180
	v_fmac_f32_e32 v209, v67, v181
	v_mul_f32_e32 v210, 0xbfb8aa3b, v202
	v_mul_f32_e32 v211, 0xbfb8aa3b, v203
	v_mul_f32_e32 v212, 0xbfb8aa3b, v204
	v_mul_f32_e32 v213, 0xbfb8aa3b, v205
	v_exp_f32_e32 v210, v210
	v_exp_f32_e32 v211, v211
	v_exp_f32_e32 v212, v212
	v_exp_f32_e32 v213, v213
	v_add_f32_e32 v210, 1.0, v210
	v_add_f32_e32 v211, 1.0, v211
	v_add_f32_e32 v212, 1.0, v212
	v_add_f32_e32 v213, 1.0, v213
	v_rcp_f32_e32 v210, v210
	v_rcp_f32_e32 v211, v211
	v_rcp_f32_e32 v212, v212
	v_rcp_f32_e32 v213, v213
	v_mul_f32_e32 v202, v202, v210
	v_mul_f32_e32 v203, v203, v211
	v_mul_f32_e32 v204, v204, v212
	v_mul_f32_e32 v205, v205, v213
	v_mul_f32_e32 v202, v202, v206
	v_mul_f32_e32 v203, v203, v207
	v_mul_f32_e32 v204, v204, v208
	v_mul_f32_e32 v205, v205, v209
	v_cvt_pk_bf16_f32 v94, v202, v203
	v_cvt_pk_bf16_f32 v95, v204, v205
	v_fma_f32 v202, v124, v72, v132
	v_fma_f32 v203, v125, v73, v133
	v_fma_f32 v204, v126, v74, v134
	v_fma_f32 v205, v127, v75, v135
	v_fmac_f32_e32 v202, v88, v116
	v_fmac_f32_e32 v203, v89, v117
	v_fmac_f32_e32 v204, v90, v118
	v_fmac_f32_e32 v205, v91, v119
	v_fmac_f32_dpp v202, v136, v128 row_shl:1 row_mask:0xf bank_mask:0xf
	v_fmac_f32_dpp v203, v137, v129 row_shl:1 row_mask:0xf bank_mask:0xf
	v_fmac_f32_dpp v204, v138, v130 row_shl:1 row_mask:0xf bank_mask:0xf
	v_fmac_f32_dpp v205, v139, v131 row_shl:1 row_mask:0xf bank_mask:0xf
	v_fmac_f32_e32 v202, v186, v222
	v_fmac_f32_e32 v203, v187, v223
	v_fmac_f32_e32 v204, v188, v224
	v_fmac_f32_e32 v205, v189, v225
	v_fma_f32 v206, v164, v64, v182
	v_fma_f32 v207, v165, v65, v183
	v_fma_f32 v208, v166, v66, v184
	v_fma_f32 v209, v167, v67, v185
	v_fmac_f32_e32 v206, v80, v160
	v_fmac_f32_e32 v207, v81, v161
	v_fmac_f32_e32 v208, v82, v162
	v_fmac_f32_e32 v209, v83, v163
	v_fmac_f32_dpp v206, v112, v178 row_shl:1 row_mask:0xf bank_mask:0xf
	v_fmac_f32_dpp v207, v113, v179 row_shl:1 row_mask:0xf bank_mask:0xf
	v_fmac_f32_dpp v208, v114, v180 row_shl:1 row_mask:0xf bank_mask:0xf
	v_fmac_f32_dpp v209, v115, v181 row_shl:1 row_mask:0xf bank_mask:0xf
	v_fmac_f32_e32 v206, v190, v232
	v_fmac_f32_e32 v207, v191, v233
	v_fmac_f32_e32 v208, v192, v234
	v_fmac_f32_e32 v209, v193, v235
	v_mul_f32_e32 v210, 0xbfb8aa3b, v202
	v_mul_f32_e32 v211, 0xbfb8aa3b, v203
	v_mul_f32_e32 v212, 0xbfb8aa3b, v204
	v_mul_f32_e32 v213, 0xbfb8aa3b, v205
	v_exp_f32_e32 v210, v210
	v_exp_f32_e32 v211, v211
	v_exp_f32_e32 v212, v212
	v_exp_f32_e32 v213, v213
	v_add_f32_e32 v210, 1.0, v210
	v_add_f32_e32 v211, 1.0, v211
	v_add_f32_e32 v212, 1.0, v212
	v_add_f32_e32 v213, 1.0, v213
	v_rcp_f32_e32 v210, v210
	v_rcp_f32_e32 v211, v211
	v_rcp_f32_e32 v212, v212
	v_rcp_f32_e32 v213, v213
	v_mul_f32_e32 v202, v202, v210
	v_mul_f32_e32 v203, v203, v211
	v_mul_f32_e32 v204, v204, v212
	v_mul_f32_e32 v205, v205, v213
	v_mul_f32_e32 v202, v202, v206
	v_mul_f32_e32 v203, v203, v207
	v_mul_f32_e32 v204, v204, v208
	v_mul_f32_e32 v205, v205, v209
	v_cvt_pk_bf16_f32 v78, v202, v203
	v_cvt_pk_bf16_f32 v79, v204, v205
	v_fma_f32 v202, v124, v56, v132
	v_fma_f32 v203, v125, v57, v133
	v_fma_f32 v204, v126, v58, v134
	v_fma_f32 v205, v127, v59, v135
	v_fmac_f32_dpp v202, v8, v116 row_shr:1 row_mask:0xf bank_mask:0xf
	v_fmac_f32_dpp v203, v9, v117 row_shr:1 row_mask:0xf bank_mask:0xf
	v_fmac_f32_dpp v204, v10, v118 row_shr:1 row_mask:0xf bank_mask:0xf
	v_fmac_f32_dpp v205, v11, v119 row_shr:1 row_mask:0xf bank_mask:0xf
	v_fmac_f32_e32 v202, v194, v218
	v_fmac_f32_e32 v203, v195, v219
	v_fmac_f32_e32 v204, v196, v220
	v_fmac_f32_e32 v205, v197, v221
	v_fmac_f32_e32 v202, v40, v128
	v_fmac_f32_e32 v203, v41, v129
	v_fmac_f32_e32 v204, v42, v130
	v_fmac_f32_e32 v205, v43, v131
	v_fma_f32 v206, v164, v48, v182
	v_fma_f32 v207, v165, v49, v183
	v_fma_f32 v208, v166, v50, v184
	v_fma_f32 v209, v167, v51, v185
	v_fmac_f32_dpp v206, v0, v160 row_shr:1 row_mask:0xf bank_mask:0xf
	v_fmac_f32_dpp v207, v1, v161 row_shr:1 row_mask:0xf bank_mask:0xf
	v_fmac_f32_dpp v208, v2, v162 row_shr:1 row_mask:0xf bank_mask:0xf
	v_fmac_f32_dpp v209, v3, v163 row_shr:1 row_mask:0xf bank_mask:0xf
	v_fmac_f32_e32 v206, v198, v226
	v_fmac_f32_e32 v207, v199, v227
	v_fmac_f32_e32 v208, v200, v228
	v_fmac_f32_e32 v209, v201, v229
	v_fmac_f32_e32 v206, v32, v178
	v_fmac_f32_e32 v207, v33, v179
	v_fmac_f32_e32 v208, v34, v180
	v_fmac_f32_e32 v209, v35, v181
	v_mul_f32_e32 v210, 0xbfb8aa3b, v202
	v_mul_f32_e32 v211, 0xbfb8aa3b, v203
	v_mul_f32_e32 v212, 0xbfb8aa3b, v204
	v_mul_f32_e32 v213, 0xbfb8aa3b, v205
	v_exp_f32_e32 v210, v210
	v_exp_f32_e32 v211, v211
	v_exp_f32_e32 v212, v212
	v_exp_f32_e32 v213, v213
	v_add_f32_e32 v210, 1.0, v210
	v_add_f32_e32 v211, 1.0, v211
	v_add_f32_e32 v212, 1.0, v212
	v_add_f32_e32 v213, 1.0, v213
	v_rcp_f32_e32 v210, v210
	v_rcp_f32_e32 v211, v211
	v_rcp_f32_e32 v212, v212
	v_rcp_f32_e32 v213, v213
	v_mul_f32_e32 v202, v202, v210
	v_mul_f32_e32 v203, v203, v211
	v_mul_f32_e32 v204, v204, v212
	v_mul_f32_e32 v205, v205, v213
	v_mul_f32_e32 v202, v202, v206
	v_mul_f32_e32 v203, v203, v207
	v_mul_f32_e32 v204, v204, v208
	v_mul_f32_e32 v205, v205, v209
	v_cvt_pk_bf16_f32 v62, v202, v203
	v_cvt_pk_bf16_f32 v63, v204, v205
	v_fma_f32 v202, v124, v40, v132
	v_fma_f32 v203, v125, v41, v133
	v_fma_f32 v204, v126, v42, v134
	v_fma_f32 v205, v127, v43, v135
	v_fmac_f32_e32 v202, v56, v116
	v_fmac_f32_e32 v203, v57, v117
	v_fmac_f32_e32 v204, v58, v118
	v_fmac_f32_e32 v205, v59, v119
	v_fmac_f32_e32 v202, v24, v128
	v_fmac_f32_e32 v203, v25, v129
	v_fmac_f32_e32 v204, v26, v130
	v_fmac_f32_e32 v205, v27, v131
	v_fma_f32 v206, v164, v32, v182
	v_fma_f32 v207, v165, v33, v183
	v_fma_f32 v208, v166, v34, v184
	v_fma_f32 v209, v167, v35, v185
	v_fmac_f32_e32 v206, v48, v160
	v_fmac_f32_e32 v207, v49, v161
	v_fmac_f32_e32 v208, v50, v162
	v_fmac_f32_e32 v209, v51, v163
	v_fmac_f32_e32 v206, v16, v178
	v_fmac_f32_e32 v207, v17, v179
	v_fmac_f32_e32 v208, v18, v180
	v_fmac_f32_e32 v209, v19, v181
	v_mul_f32_e32 v210, 0xbfb8aa3b, v202
	v_mul_f32_e32 v211, 0xbfb8aa3b, v203
	v_mul_f32_e32 v212, 0xbfb8aa3b, v204
	v_mul_f32_e32 v213, 0xbfb8aa3b, v205
	v_exp_f32_e32 v210, v210
	v_exp_f32_e32 v211, v211
	v_exp_f32_e32 v212, v212
	v_exp_f32_e32 v213, v213
	v_add_f32_e32 v210, 1.0, v210
	v_add_f32_e32 v211, 1.0, v211
	v_add_f32_e32 v212, 1.0, v212
	v_add_f32_e32 v213, 1.0, v213
	v_rcp_f32_e32 v210, v210
	v_rcp_f32_e32 v211, v211
	v_rcp_f32_e32 v212, v212
	v_rcp_f32_e32 v213, v213
	v_mul_f32_e32 v202, v202, v210
	v_mul_f32_e32 v203, v203, v211
	v_mul_f32_e32 v204, v204, v212
	v_mul_f32_e32 v205, v205, v213
	v_mul_f32_e32 v202, v202, v206
	v_mul_f32_e32 v203, v203, v207
	v_mul_f32_e32 v204, v204, v208
	v_mul_f32_e32 v205, v205, v209
	v_cvt_pk_bf16_f32 v46, v202, v203
	v_cvt_pk_bf16_f32 v47, v204, v205
	v_fma_f32 v202, v124, v24, v132
	v_fma_f32 v203, v125, v25, v133
	v_fma_f32 v204, v126, v26, v134
	v_fma_f32 v205, v127, v27, v135
	v_fmac_f32_e32 v202, v40, v116
	v_fmac_f32_e32 v203, v41, v117
	v_fmac_f32_e32 v204, v42, v118
	v_fmac_f32_e32 v205, v43, v119
	v_fmac_f32_e32 v202, v8, v128
	v_fmac_f32_e32 v203, v9, v129
	v_fmac_f32_e32 v204, v10, v130
	v_fmac_f32_e32 v205, v11, v131
	v_fma_f32 v206, v164, v16, v182
	v_fma_f32 v207, v165, v17, v183
	v_fma_f32 v208, v166, v18, v184
	v_fma_f32 v209, v167, v19, v185
	v_fmac_f32_e32 v206, v32, v160
	v_fmac_f32_e32 v207, v33, v161
	v_fmac_f32_e32 v208, v34, v162
	v_fmac_f32_e32 v209, v35, v163
	v_fmac_f32_e32 v206, v0, v178
	v_fmac_f32_e32 v207, v1, v179
	v_fmac_f32_e32 v208, v2, v180
	v_fmac_f32_e32 v209, v3, v181
	v_mul_f32_e32 v210, 0xbfb8aa3b, v202
	v_mul_f32_e32 v211, 0xbfb8aa3b, v203
	v_mul_f32_e32 v212, 0xbfb8aa3b, v204
	v_mul_f32_e32 v213, 0xbfb8aa3b, v205
	v_exp_f32_e32 v210, v210
	v_exp_f32_e32 v211, v211
	v_exp_f32_e32 v212, v212
	v_exp_f32_e32 v213, v213
	v_add_f32_e32 v210, 1.0, v210
	v_add_f32_e32 v211, 1.0, v211
	v_add_f32_e32 v212, 1.0, v212
	v_add_f32_e32 v213, 1.0, v213
	v_rcp_f32_e32 v210, v210
	v_rcp_f32_e32 v211, v211
	v_rcp_f32_e32 v212, v212
	v_rcp_f32_e32 v213, v213
	v_mul_f32_e32 v202, v202, v210
	v_mul_f32_e32 v203, v203, v211
	v_mul_f32_e32 v204, v204, v212
	v_mul_f32_e32 v205, v205, v213
	v_mul_f32_e32 v202, v202, v206
	v_mul_f32_e32 v203, v203, v207
	v_mul_f32_e32 v204, v204, v208
	v_mul_f32_e32 v205, v205, v209
	v_cvt_pk_bf16_f32 v30, v202, v203
	v_cvt_pk_bf16_f32 v31, v204, v205
	v_fma_f32 v202, v124, v8, v132
	v_fma_f32 v203, v125, v9, v133
	v_fma_f32 v204, v126, v10, v134
	v_fma_f32 v205, v127, v11, v135
	v_fmac_f32_e32 v202, v24, v116
	v_fmac_f32_e32 v203, v25, v117
	v_fmac_f32_e32 v204, v26, v118
	v_fmac_f32_e32 v205, v27, v119
	v_fmac_f32_dpp v202, v56, v128 row_shl:1 row_mask:0xf bank_mask:0xf
	v_fmac_f32_dpp v203, v57, v129 row_shl:1 row_mask:0xf bank_mask:0xf
	v_fmac_f32_dpp v204, v58, v130 row_shl:1 row_mask:0xf bank_mask:0xf
	v_fmac_f32_dpp v205, v59, v131 row_shl:1 row_mask:0xf bank_mask:0xf
	v_fmac_f32_e32 v202, v194, v222
	v_fmac_f32_e32 v203, v195, v223
	v_fmac_f32_e32 v204, v196, v224
	v_fmac_f32_e32 v205, v197, v225
	v_fma_f32 v206, v164, v0, v182
	v_fma_f32 v207, v165, v1, v183
	v_fma_f32 v208, v166, v2, v184
	v_fma_f32 v209, v167, v3, v185
	v_fmac_f32_e32 v206, v16, v160
	v_fmac_f32_e32 v207, v17, v161
	v_fmac_f32_e32 v208, v18, v162
	v_fmac_f32_e32 v209, v19, v163
	v_fmac_f32_dpp v206, v48, v178 row_shl:1 row_mask:0xf bank_mask:0xf
	v_fmac_f32_dpp v207, v49, v179 row_shl:1 row_mask:0xf bank_mask:0xf
	v_fmac_f32_dpp v208, v50, v180 row_shl:1 row_mask:0xf bank_mask:0xf
	v_fmac_f32_dpp v209, v51, v181 row_shl:1 row_mask:0xf bank_mask:0xf
	v_fmac_f32_e32 v206, v198, v232
	v_fmac_f32_e32 v207, v199, v233
	v_fmac_f32_e32 v208, v200, v234
	v_fmac_f32_e32 v209, v201, v235
	s_mov_b64 exec, s[94:95]
	v_add_u32_e32 v250, 0x10800, v177
	global_store_dwordx4 v250, v[202:205], s[98:99] offset:16
	v_add_u32_e32 v250, 0x13400, v177
	global_store_dwordx4 v250, v[206:209], s[98:99] offset:16
	s_mov_b64 exec, s[90:91]
	s_nop 4
	v_mul_f32_e32 v210, 0xbfb8aa3b, v202
	v_mul_f32_e32 v211, 0xbfb8aa3b, v203
	v_mul_f32_e32 v212, 0xbfb8aa3b, v204
	v_mul_f32_e32 v213, 0xbfb8aa3b, v205
	v_exp_f32_e32 v210, v210
	v_exp_f32_e32 v211, v211
	v_exp_f32_e32 v212, v212
	v_exp_f32_e32 v213, v213
	v_add_f32_e32 v210, 1.0, v210
	v_add_f32_e32 v211, 1.0, v211
	v_add_f32_e32 v212, 1.0, v212
	v_add_f32_e32 v213, 1.0, v213
	v_rcp_f32_e32 v210, v210
	v_rcp_f32_e32 v211, v211
	v_rcp_f32_e32 v212, v212
	v_rcp_f32_e32 v213, v213
	v_mul_f32_e32 v202, v202, v210
	v_mul_f32_e32 v203, v203, v211
	v_mul_f32_e32 v204, v204, v212
	v_mul_f32_e32 v205, v205, v213
	v_mul_f32_e32 v202, v202, v206
	v_mul_f32_e32 v203, v203, v207
	v_mul_f32_e32 v204, v204, v208
	v_mul_f32_e32 v205, v205, v209
	v_cvt_pk_bf16_f32 v14, v202, v203
	v_cvt_pk_bf16_f32 v15, v204, v205
	global_store_dwordx4 v168, v[140:143], s[76:77]
	v_add_u32_e32 v250, 0x1600, v168
	global_store_dwordx4 v250, v[108:111], s[76:77]
	s_nop 0
	v_add_u32_e32 v250, 0x2c00, v168
	global_store_dwordx4 v250, v[92:95], s[76:77]
	s_nop 0
	v_add_u32_e32 v250, 0x4200, v168
	global_store_dwordx4 v250, v[76:79], s[76:77]
	s_nop 0
	v_add_u32_e32 v250, 0xb0000, v168
	global_store_dwordx4 v250, v[60:63], s[76:77]
	s_nop 0
	v_add_u32_e32 v250, 0xb1600, v168
	global_store_dwordx4 v250, v[44:47], s[76:77]
	s_nop 0
	v_add_u32_e32 v250, 0xb2c00, v168
	global_store_dwordx4 v250, v[28:31], s[76:77]
	s_nop 0
	v_add_u32_e32 v250, 0xb4200, v168
	global_store_dwordx4 v250, v[12:15], s[76:77]
	s_nop 0
	s_mov_b64 s[4:5], -1
	s_and_b64 vcc, exec, s[6:7]
	s_cbranch_vccz .LBB0_963
	s_andn2_b64 vcc, exec, s[10:11]
	s_cbranch_vccnz .LBB0_962
	s_barrier
	s_branch .LBB0_962

.LBB0_1742:
	s_add_u32 s0, s70, 0xf500000
	s_addc_u32 s1, s71, 0
	s_add_u32 s33, s70, 0xec63000
	s_addc_u32 s50, s71, 0
	s_cmp_gt_i32 s72, 18
	s_cselect_b64 s[4:5], -1, 0
	s_cmp_lt_i32 s73, 19
	s_cselect_b64 s[6:7], -1, 0
	s_or_b64 s[4:5], s[4:5], s[6:7]
	s_and_b64 vcc, exec, s[4:5]
	s_cbranch_vccnz .LBB0_1809
	v_readlane_b32 s4, v255, 2
	v_mov_b32_e32 v9, v230
	v_readlane_b32 s5, v255, 3
	s_and_b64 vcc, exec, s[4:5]
	v_readfirstlane_b32 s4, v9
	s_cbranch_vccnz .LBB0_1759
	v_lshlrev_b32_e32 v0, 4, v9
	s_waitcnt lgkmcnt(0)
	v_add_u32_e32 v1, 0x2000, v0
	v_ashrrev_i32_e32 v2, 31, v1
	v_lshrrev_b32_e32 v2, 22, v2
	v_add_u32_e32 v2, v1, v2
	v_ashrrev_i32_e32 v8, 10, v2
	v_mul_i32_i24_e32 v2, 0x400, v8
	v_sub_u32_e32 v1, v1, v2
	v_lshrrev_b32_e32 v2, 4, v1
	v_bitop3_b32 v1, v2, v1, 32 bitop3:0x6c
	v_ashrrev_i32_e32 v2, 31, v1
	v_lshrrev_b32_e32 v2, 26, v2
	v_add_u32_e32 v2, v1, v2
	v_lshlrev_b32_e32 v3, 3, v8
	v_ashrrev_i32_e32 v10, 6, v2
	v_and_b32_e32 v3, -16, v3
	v_add_u32_e32 v3, v10, v3
	v_and_b32_e32 v4, 3, v10
	s_mov_b32 s6, 0x1fffe0
	v_lshrrev_b32_e32 v5, 2, v3
	v_lshlrev_b32_e32 v6, 1, v3
	v_and_b32_e32 v2, 0xc0, v2
	v_and_or_b32 v4, v3, s6, v4
	v_and_b32_e32 v5, 4, v5
	v_and_b32_e32 v6, 24, v6
	v_sub_u32_e32 v1, v1, v2
	v_mov_b32_e32 v2, 1
	v_or3_b32 v4, v4, v5, v6
	v_lshlrev_b32_e32 v5, 5, v8
	v_ashrrev_i16_sdwa v1, v2, sext(v1) dst_sel:DWORD dst_unused:UNUSED_PAD src0_sel:DWORD src1_sel:BYTE_0
	v_and_b32_e32 v5, 32, v5
	v_bfe_i32 v11, v1, 0, 16
	v_add_lshl_u32 v1, v5, v11, 1
	v_lshl_add_u32 v144, v4, 11, v1
	v_lshl_add_u32 v146, v3, 11, v1
	v_lshrrev_b32_e32 v248, 11, v146
	v_and_b32_e32 v249, 0x7ff, v146
	v_and_b32_e32 v250, 15, v248
	v_lshlrev_b32_e32 v250, 2, v250
	v_bfe_u32 v251, v248, 4, 2
	v_and_or_b32 v248, v248, 64, v250
	v_or_b32_e32 v248, v248, v251
	v_lshl_or_b32 v146, v248, 11, v249
	v_bfe_i32 v1, v9, 27, 1
	v_lshrrev_b32_e32 v1, 22, v1
	v_add_u32_e32 v1, v0, v1
	v_and_b32_e32 v1, 0xfffffc00, v1
	v_sub_u32_e32 v0, v0, v1
	v_lshrrev_b32_e32 v1, 4, v0
	v_ashrrev_i32_e32 v3, 31, v9
	v_bitop3_b32 v0, v1, v0, 32 bitop3:0x6c
	v_lshrrev_b32_e32 v3, 26, v3
	v_ashrrev_i32_e32 v1, 31, v0
	v_add_u32_e32 v3, v9, v3
	s_add_u32 s20, s70, 0x3b00000
	v_lshrrev_b32_e32 v1, 26, v1
	v_ashrrev_i32_e32 v13, 6, v3
	s_addc_u32 s21, s71, 0
	s_ashr_i32 s7, s4, 6
	v_add_u32_e32 v1, v0, v1
	v_lshlrev_b32_e32 v3, 3, v13
	v_readlane_b32 s8, v254, 62
	s_ashr_i32 s5, s4, 8
	s_lshl_b32 s30, s7, 10
	v_ashrrev_i32_e32 v12, 6, v1
	v_and_b32_e32 v3, -16, v3
	v_readlane_b32 s9, v254, 63
	v_add_u32_e32 v3, v12, v3
	v_and_b32_e32 v4, 3, v12
	s_movk_i32 s31, 0x59
	s_and_b64 s[8:9], s[8:9], exec
	v_and_or_b32 v4, v3, s6, v4
	s_cselect_b32 s6, s31, 0x58
	v_readlane_b32 s8, v254, 51
	s_mul_i32 s6, s6, s8
	v_readlane_b32 s8, v254, 61
	s_add_i32 s6, s6, s8
	s_mul_hi_i32 s8, s6, 0x2e8ba2e9
	s_lshr_b32 s9, s8, 31
	s_ashr_i32 s8, s8, 5
	s_add_i32 s8, s8, s9
	s_lshl_b32 s9, s8, 3
	s_mulk_i32 s8, 0xb0
	s_sub_i32 s8, s6, s8
	s_bfe_u32 s6, s8, 0x3001c
	s_add_i32 s12, s8, s6
	s_sext_i32_i16 s6, s12
	s_and_b32 s12, s12, 0xfff8
	s_sub_i32 s8, s8, s12
	s_sext_i32_i16 s8, s8
	v_lshrrev_b32_e32 v5, 2, v3
	v_lshlrev_b32_e32 v6, 1, v3
	v_and_b32_e32 v1, 0xc0, v1
	s_lshr_b32 s6, s6, 3
	s_add_i32 s8, s9, s8
	v_and_b32_e32 v5, 4, v5
	v_and_b32_e32 v6, 24, v6
	v_sub_u32_e32 v0, v0, v1
	s_ashr_i32 s9, s8, 31
	s_bfe_i64 s[14:15], s[6:7], 0x100000
	v_or3_b32 v4, v4, v5, v6
	v_lshlrev_b32_e32 v5, 5, v13
	v_ashrrev_i16_sdwa v0, v2, sext(v0) dst_sel:DWORD dst_unused:UNUSED_PAD src0_sel:DWORD src1_sel:BYTE_0
	s_lshl_b64 s[12:13], s[8:9], 19
	s_lshl_b64 s[14:15], s[14:15], 18
	v_and_b32_e32 v5, 32, v5
	v_bfe_i32 v14, v0, 0, 16
	s_add_u32 s38, s0, s14
	v_add_lshl_u32 v0, v5, v14, 1
	s_addc_u32 s39, s1, s15
	s_add_i32 s42, s30, 0
	v_lshl_add_u32 v148, v4, 11, v0
	s_add_i32 m0, s42, 0x10000
	v_lshl_add_u32 v150, v3, 11, v0
	v_lshrrev_b32_e32 v248, 11, v150
	v_and_b32_e32 v249, 0x7ff, v150
	v_and_b32_e32 v250, 15, v248
	v_lshlrev_b32_e32 v250, 2, v250
	v_bfe_u32 v251, v248, 4, 2
	v_and_or_b32 v248, v248, 64, v250
	v_or_b32_e32 v248, v248, v251
	v_lshl_or_b32 v150, v248, 11, v249
	global_load_lds_dwordx4 v148, s[38:39]
	s_add_i32 m0, s42, 0x12000
	s_add_u32 s14, s38, 0x580000
	global_load_lds_dwordx4 v144, s[38:39]
	s_addc_u32 s15, s39, 0
	s_add_i32 m0, s42, 0x14000
	v_mov_b32_e32 v149, 0
	global_load_lds_dwordx4 v148, s[14:15]
	s_add_i32 m0, s42, 0x16000
	s_add_u32 s36, s20, s12
	s_addc_u32 s37, s21, s13
	s_add_i32 s43, s42, 0x2000
	global_load_lds_dwordx4 v144, s[14:15]
	s_mov_b32 m0, s42
	s_add_u32 s12, s36, 0x40000
	global_load_lds_dwordx4 v150, s[36:37]
	s_mov_b32 m0, s43
	s_addc_u32 s13, s37, 0
	s_add_i32 s44, s42, 0x4000
	global_load_lds_dwordx4 v146, s[36:37]
	s_mov_b32 m0, s44
	s_add_i32 s45, s42, 0x6000
	global_load_lds_dwordx4 v150, s[12:13]
	s_mov_b32 m0, s45
	v_mov_b32_e32 v145, v149
	global_load_lds_dwordx4 v146, s[12:13]
	v_mov_b32_e32 v151, v149
	v_mov_b32_e32 v147, v149
	s_cmp_eq_u32 s5, 1
	s_mov_b32 s46, 0
	v_lshl_add_u64 v[6:7], s[38:39], 0, v[148:149]
	v_lshl_add_u64 v[4:5], s[38:39], 0, v[144:145]
	v_lshl_add_u64 v[0:1], s[36:37], 0, v[150:151]
	s_cselect_b64 s[12:13], -1, 0
	s_cmp_lg_u32 s5, 1
	v_lshl_add_u64 v[2:3], s[36:37], 0, v[146:147]
	s_cbranch_scc1 .LBB0_1746
	s_barrier
.LBB0_1746:
	s_add_u32 s14, s70, 0x3b00000
	s_addc_u32 s15, s71, 0
	s_lshl_b32 s7, s7, 5
	s_mov_b64 s[16:17], 0x80
	s_and_b32 s7, s7, 0x60
	s_add_i32 m0, s42, 0x18000
	v_lshl_add_u64 v[6:7], v[6:7], 0, s[16:17]
	s_lshl_b32 s24, s5, 13
	s_lshl_b32 s25, s7, 7
	s_waitcnt vmcnt(2)
	s_barrier
	global_load_lds_dwordx4 v[6:7], off
	v_lshl_add_u64 v[4:5], v[4:5], 0, s[16:17]
	s_add_i32 m0, s42, 0x1a000
	s_add_i32 s47, s42, 0x8000
	s_add_i32 s48, s42, 0xa000
	global_load_lds_dwordx4 v[4:5], off
	v_lshl_add_u64 v[0:1], v[0:1], 0, s[16:17]
	s_mov_b32 m0, s47
	s_add_u32 s22, s38, 0x580080
	global_load_lds_dwordx4 v[0:1], off
	v_lshl_add_u64 v[0:1], v[2:3], 0, s[16:17]
	s_mov_b32 m0, s48
	s_addc_u32 s23, s39, 0
	global_load_lds_dwordx4 v[0:1], off
	s_add_i32 m0, s42, 0x1c000
	v_lshl_add_u64 v[0:1], s[22:23], 0, v[148:149]
	global_load_lds_dwordx4 v[0:1], off
	v_lshl_add_u64 v[0:1], s[22:23], 0, v[144:145]
	s_add_i32 m0, s42, 0x1e000
	s_cmpk_lt_u32 s4, 0x100
	global_load_lds_dwordx4 v[0:1], off
	v_lshrrev_b32_e32 v1, 1, v9
	v_and_b32_e32 v1, 24, v1
	v_and_b32_e32 v0, 15, v9
	v_lshlrev_b32_e32 v2, 1, v1
	v_lshl_or_b32 v164, s5, 6, v0
	v_lshl_or_b32 v0, v0, 6, v2
	v_lshlrev_b32_e32 v2, 2, v9
	v_and_b32_e32 v2, 32, v2
	v_bitop3_b32 v3, v0, s24, v2 bitop3:0xde
	v_bitop3_b32 v165, v0, s25, v2 bitop3:0xde
	v_lshlrev_b32_e32 v0, 14, v13
	v_and_b32_e32 v0, 0xffff8000, v0
	v_or_b32_e32 v166, s7, v1
	v_lshl_add_u32 v0, v12, 11, v0
	v_and_b32_e32 v1, 1, v13
	v_lshl_or_b32 v0, v1, 6, v0
	v_lshl_add_u32 v152, v14, 1, v0
	v_lshrrev_b32_e32 v248, 11, v152
	v_and_b32_e32 v249, 0x7ff, v152
	v_and_b32_e32 v250, 15, v248
	v_lshlrev_b32_e32 v250, 2, v250
	v_bfe_u32 v251, v248, 4, 2
	v_and_or_b32 v248, v248, 64, v250
	v_or_b32_e32 v248, v248, v251
	v_lshl_or_b32 v152, v248, 11, v249
	v_lshlrev_b32_e32 v0, 14, v8
	v_and_b32_e32 v0, 0xffff8000, v0
	s_waitcnt vmcnt(6)
	v_lshl_add_u32 v0, v10, 11, v0
	v_and_b32_e32 v1, 1, v8
	s_cselect_b64 s[22:23], -1, 0
	v_lshl_or_b32 v0, v1, 6, v0
	s_add_i32 s49, 0, 0x10000
	s_add_i32 s51, 0, 0x14000
	s_sext_i32_i16 s9, s6
	v_mov_b32_e32 v153, v149
	v_lshl_add_u32 v154, v11, 1, v0
	v_lshrrev_b32_e32 v248, 11, v154
	v_and_b32_e32 v249, 0x7ff, v154
	v_and_b32_e32 v250, 15, v248
	v_lshlrev_b32_e32 v250, 2, v250
	v_bfe_u32 v251, v248, 4, 2
	v_and_or_b32 v248, v248, 64, v250
	v_or_b32_e32 v248, v248, v251
	v_lshl_or_b32 v154, v248, 11, v249
	v_mov_b32_e32 v155, v149
	v_mov_b64_e32 v[156:157], 0x2c0
	v_mov_b64_e32 v[158:159], 0x2bf
	v_add_u32_e32 v167, s49, v165
	v_add_u32_e32 v168, s51, v165
	v_add_u32_e32 v169, 0, v3
	v_mov_b32_e32 v170, 0x358637bd
	s_mov_b32 s52, 0x800000
	s_movk_i32 s53, 0x2c00
	s_barrier
	s_branch .LBB0_1749

.LBB0_1755:
	s_and_b32 s27, s12, 1
	s_add_i32 s4, s8, -32
	s_ashr_i32 s4, s4, 2
	s_add_i32 s4, s4, 1
	s_cmp_gt_i32 s8, 31
	s_cselect_b32 s4, s4, 0
	s_mul_hi_i32 s5, s4, 0x5800
	s_mulk_i32 s4, 0x5800
	s_add_u32 s4, s33, s4
	s_addc_u32 s5, s50, s5
	v_and_b32_e32 v237, 15, v164
	v_and_b32_e32 v236, 64, v164
	v_lshl_add_u32 v236, v237, 2, v236
	v_mul_u32_u24_e32 v171, 0x1600, v236
	v_lshl_add_u32 v171, v166, 1, v171
	v_lshl_add_u32 v236, s8, 8, v236
	v_lshlrev_b32_e32 v236, 2, v236
	v_lshl_or_b32 v229, s9, 7, v166
	v_lshlrev_b32_e32 v229, 2, v229
	global_load_dwordx4 v[208:211], v236, s[10:11]
	global_load_dwordx4 v[212:215], v236, s[10:11] offset:512
	global_load_dwordx4 v[200:203], v229, s[4:5]
	global_load_dwordx4 v[204:207], v229, s[4:5] offset:16
	v_add_u32_e32 v224, 0x2c00, v229
	global_load_dwordx4 v[216:219], v224, s[4:5]
	global_load_dwordx4 v[220:223], v224, s[4:5] offset:16
	v_readlane_b32 s36, v254, 5
	v_readlane_b32 s37, v254, 6
	v_readlane_b32 s38, v254, 7
	v_readlane_b32 s39, v254, 8
	s_add_u32 s36, s36, 0x10800
	s_addc_u32 s37, s37, 0
	s_add_u32 s38, s38, 0x5800
	s_addc_u32 s39, s39, 0
	s_mul_i32 s40, s8, 0x160000
	s_lshl_b32 s79, s9, 8
	s_add_i32 s40, s40, s79
	s_add_i32 s40, s40, 0x9300000
	s_add_u32 s40, s40, s70
	s_addc_u32 s41, s71, 0
	s_mov_b32 s32, 0x20800
	v_lshl_add_u32 v228, v166, 2, s32
	v_cmp_eq_u32_e64 s[54:55], 0, v237
	v_cmp_eq_u32_e64 s[56:57], 15, v237
	v_and_b32_e32 v231, 8, v237
	v_lshlrev_b32_e32 v231, 9, v231
	s_lshl_b32 s79, s27, 10
	v_add3_u32 v231, v231, v228, s79
	global_load_dwordx4 v[128:131], v229, s[36:37]
	v_add_u32_e32 v227, 0x5800, v229
	global_load_dwordx4 v[132:135], v227, s[36:37]
	v_add_u32_e32 v226, 0xb000, v229
	global_load_dwordx4 v[136:139], v226, s[36:37]
	global_load_dwordx4 v[140:143], v229, s[38:39]
	v_add_u32_e32 v226, 0x2c00, v229
	global_load_dwordx4 v[160:163], v226, s[36:37]
	v_add_u32_e32 v227, 0x8400, v229
	global_load_dwordx4 v[172:175], v227, s[36:37]
	v_add_u32_e32 v226, 0xdc00, v229
	global_load_dwordx4 v[176:179], v226, s[36:37]
	v_add_u32_e32 v227, 0x2c00, v229
	global_load_dwordx4 v[180:183], v227, s[38:39]
	s_waitcnt vmcnt(12)
	v_fmamk_f32 v208, v208, 0x3a800000, v170
	v_fmamk_f32 v209, v209, 0x3a800000, v170
	v_fmamk_f32 v210, v210, 0x3a800000, v170
	v_fmamk_f32 v211, v211, 0x3a800000, v170
	v_fmamk_f32 v212, v212, 0x3a800000, v170
	v_fmamk_f32 v213, v213, 0x3a800000, v170
	v_fmamk_f32 v214, v214, 0x3a800000, v170
	v_fmamk_f32 v215, v215, 0x3a800000, v170
	s_mov_b32 s79, 0x800000
	v_mul_f32_e32 v224, 0x4b800000, v208
	v_mul_f32_e32 v225, 0x4b800000, v209
	v_mul_f32_e32 v226, 0x4b800000, v210
	v_mul_f32_e32 v227, 0x4b800000, v211
	v_mul_f32_e32 v232, 0x4b800000, v212
	v_mul_f32_e32 v233, 0x4b800000, v213
	v_mul_f32_e32 v234, 0x4b800000, v214
	v_mul_f32_e32 v235, 0x4b800000, v215
	v_cmp_gt_f32_e32 vcc, s79, v208
	s_nop 1
	v_cndmask_b32_e32 v208, v208, v224, vcc
	v_rsq_f32_e32 v208, v208
	s_nop 0
	v_mul_f32_e32 v224, 0x45800000, v208
	v_cndmask_b32_e32 v208, v208, v224, vcc
	v_cmp_gt_f32_e32 vcc, s79, v209
	s_nop 1
	v_cndmask_b32_e32 v209, v209, v225, vcc
	v_rsq_f32_e32 v209, v209
	s_nop 0
	v_mul_f32_e32 v225, 0x45800000, v209
	v_cndmask_b32_e32 v209, v209, v225, vcc
	v_cmp_gt_f32_e32 vcc, s79, v210
	s_nop 1
	v_cndmask_b32_e32 v210, v210, v226, vcc
	v_rsq_f32_e32 v210, v210
	s_nop 0
	v_mul_f32_e32 v226, 0x45800000, v210
	v_cndmask_b32_e32 v210, v210, v226, vcc
	v_cmp_gt_f32_e32 vcc, s79, v211
	s_nop 1
	v_cndmask_b32_e32 v211, v211, v227, vcc
	v_rsq_f32_e32 v211, v211
	s_nop 0
	v_mul_f32_e32 v227, 0x45800000, v211
	v_cndmask_b32_e32 v211, v211, v227, vcc
	v_cmp_gt_f32_e32 vcc, s79, v212
	s_nop 1
	v_cndmask_b32_e32 v212, v212, v232, vcc
	v_rsq_f32_e32 v212, v212
	s_nop 0
	v_mul_f32_e32 v232, 0x45800000, v212
	v_cndmask_b32_e32 v212, v212, v232, vcc
	v_cmp_gt_f32_e32 vcc, s79, v213
	s_nop 1
	v_cndmask_b32_e32 v213, v213, v233, vcc
	v_rsq_f32_e32 v213, v213
	s_nop 0
	v_mul_f32_e32 v233, 0x45800000, v213
	v_cndmask_b32_e32 v213, v213, v233, vcc
	v_cmp_gt_f32_e32 vcc, s79, v214
	s_nop 1
	v_cndmask_b32_e32 v214, v214, v234, vcc
	v_rsq_f32_e32 v214, v214
	s_nop 0
	v_mul_f32_e32 v234, 0x45800000, v214
	v_cndmask_b32_e32 v214, v214, v234, vcc
	v_cmp_gt_f32_e32 vcc, s79, v215
	s_nop 1
	v_cndmask_b32_e32 v215, v215, v235, vcc
	v_rsq_f32_e32 v215, v215
	s_nop 0
	v_mul_f32_e32 v235, 0x45800000, v215
	v_cndmask_b32_e32 v215, v215, v235, vcc
	s_waitcnt vmcnt(8)
	v_fma_f32 v124, v124, v208, v200
	v_fma_f32 v125, v125, v208, v201
	v_fma_f32 v126, v126, v208, v202
	v_fma_f32 v127, v127, v208, v203
	v_fma_f32 v120, v120, v208, v204
	v_fma_f32 v121, v121, v208, v205
	v_fma_f32 v122, v122, v208, v206
	v_fma_f32 v123, v123, v208, v207
	v_fma_f32 v108, v108, v208, v216
	v_fma_f32 v109, v109, v208, v217
	v_fma_f32 v110, v110, v208, v218
	v_fma_f32 v111, v111, v208, v219
	v_fma_f32 v104, v104, v208, v220
	v_fma_f32 v105, v105, v208, v221
	v_fma_f32 v106, v106, v208, v222
	v_fma_f32 v107, v107, v208, v223
	v_fma_f32 v116, v116, v209, v200
	v_fma_f32 v117, v117, v209, v201
	v_fma_f32 v118, v118, v209, v202
	v_fma_f32 v119, v119, v209, v203
	v_fma_f32 v112, v112, v209, v204
	v_fma_f32 v113, v113, v209, v205
	v_fma_f32 v114, v114, v209, v206
	v_fma_f32 v115, v115, v209, v207
	v_fma_f32 v100, v100, v209, v216
	v_fma_f32 v101, v101, v209, v217
	v_fma_f32 v102, v102, v209, v218
	v_fma_f32 v103, v103, v209, v219
	v_fma_f32 v92, v92, v209, v220
	v_fma_f32 v93, v93, v209, v221
	v_fma_f32 v94, v94, v209, v222
	v_fma_f32 v95, v95, v209, v223
	v_fma_f32 v96, v96, v210, v200
	v_fma_f32 v97, v97, v210, v201
	v_fma_f32 v98, v98, v210, v202
	v_fma_f32 v99, v99, v210, v203
	v_fma_f32 v88, v88, v210, v204
	v_fma_f32 v89, v89, v210, v205
	v_fma_f32 v90, v90, v210, v206
	v_fma_f32 v91, v91, v210, v207
	v_fma_f32 v84, v84, v210, v216
	v_fma_f32 v85, v85, v210, v217
	v_fma_f32 v86, v86, v210, v218
	v_fma_f32 v87, v87, v210, v219
	v_fma_f32 v76, v76, v210, v220
	v_fma_f32 v77, v77, v210, v221
	v_fma_f32 v78, v78, v210, v222
	v_fma_f32 v79, v79, v210, v223
	v_fma_f32 v80, v80, v211, v200
	v_fma_f32 v81, v81, v211, v201
	v_fma_f32 v82, v82, v211, v202
	v_fma_f32 v83, v83, v211, v203
	v_fma_f32 v72, v72, v211, v204
	v_fma_f32 v73, v73, v211, v205
	v_fma_f32 v74, v74, v211, v206
	v_fma_f32 v75, v75, v211, v207
	v_fma_f32 v68, v68, v211, v216
	v_fma_f32 v69, v69, v211, v217
	v_fma_f32 v70, v70, v211, v218
	v_fma_f32 v71, v71, v211, v219
	v_fma_f32 v64, v64, v211, v220
	v_fma_f32 v65, v65, v211, v221
	v_fma_f32 v66, v66, v211, v222
	v_fma_f32 v67, v67, v211, v223
	v_fma_f32 v60, v60, v212, v200
	v_fma_f32 v61, v61, v212, v201
	v_fma_f32 v62, v62, v212, v202
	v_fma_f32 v63, v63, v212, v203
	v_fma_f32 v56, v56, v212, v204
	v_fma_f32 v57, v57, v212, v205
	v_fma_f32 v58, v58, v212, v206
	v_fma_f32 v59, v59, v212, v207
	v_fma_f32 v52, v52, v212, v216
	v_fma_f32 v53, v53, v212, v217
	v_fma_f32 v54, v54, v212, v218
	v_fma_f32 v55, v55, v212, v219
	v_fma_f32 v44, v44, v212, v220
	v_fma_f32 v45, v45, v212, v221
	v_fma_f32 v46, v46, v212, v222
	v_fma_f32 v47, v47, v212, v223
	v_fma_f32 v48, v48, v213, v200
	v_fma_f32 v49, v49, v213, v201
	v_fma_f32 v50, v50, v213, v202
	v_fma_f32 v51, v51, v213, v203
	v_fma_f32 v40, v40, v213, v204
	v_fma_f32 v41, v41, v213, v205
	v_fma_f32 v42, v42, v213, v206
	v_fma_f32 v43, v43, v213, v207
	v_fma_f32 v36, v36, v213, v216
	v_fma_f32 v37, v37, v213, v217
	v_fma_f32 v38, v38, v213, v218
	v_fma_f32 v39, v39, v213, v219
	v_fma_f32 v28, v28, v213, v220
	v_fma_f32 v29, v29, v213, v221
	v_fma_f32 v30, v30, v213, v222
	v_fma_f32 v31, v31, v213, v223
	v_fma_f32 v32, v32, v214, v200
	v_fma_f32 v33, v33, v214, v201
	v_fma_f32 v34, v34, v214, v202
	v_fma_f32 v35, v35, v214, v203
	v_fma_f32 v24, v24, v214, v204
	v_fma_f32 v25, v25, v214, v205
	v_fma_f32 v26, v26, v214, v206
	v_fma_f32 v27, v27, v214, v207
	v_fma_f32 v20, v20, v214, v216
	v_fma_f32 v21, v21, v214, v217
	v_fma_f32 v22, v22, v214, v218
	v_fma_f32 v23, v23, v214, v219
	v_fma_f32 v12, v12, v214, v220
	v_fma_f32 v13, v13, v214, v221
	v_fma_f32 v14, v14, v214, v222
	v_fma_f32 v15, v15, v214, v223
	v_fma_f32 v16, v16, v215, v200
	v_fma_f32 v17, v17, v215, v201
	v_fma_f32 v18, v18, v215, v202
	v_fma_f32 v19, v19, v215, v203
	v_fma_f32 v8, v8, v215, v204
	v_fma_f32 v9, v9, v215, v205
	v_fma_f32 v10, v10, v215, v206
	v_fma_f32 v11, v11, v215, v207
	v_fma_f32 v4, v4, v215, v216
	v_fma_f32 v5, v5, v215, v217
	v_fma_f32 v6, v6, v215, v218
	v_fma_f32 v7, v7, v215, v219
	v_fma_f32 v0, v0, v215, v220
	v_fma_f32 v1, v1, v215, v221
	v_fma_f32 v2, v2, v215, v222
	v_fma_f32 v3, v3, v215, v223
	v_mov_b32_e32 v212, 0
	v_mov_b32_e32 v213, 0
	v_mov_b32_e32 v214, 0
	v_mov_b32_e32 v215, 0
	s_lshl_b32 s96, s27, 12
	s_sub_i32 s96, 0x2000, s96
	s_mul_i32 s94, s27, 0x1400
	s_add_i32 s94, s94, 0xc00
	s_lshl_b32 s79, s27, 10
	s_add_i32 s95, s79, 5120
	s_add_i32 s92, s79, 1024
	s_mov_b64 s[58:59], exec
	s_mov_b64 exec, s[54:55]
	v_add_u32_e32 v250, s96, v228
	ds_write_b128 v250, v[124:127] offset:0
	ds_write_b128 v250, v[120:123] offset:16
	ds_write_b128 v250, v[108:111] offset:512
	ds_write_b128 v250, v[104:107] offset:528
	v_add_u32_e32 v250, s95, v228
	ds_write_b128 v250, v[60:63] offset:0
	ds_write_b128 v250, v[56:59] offset:16
	ds_write_b128 v250, v[52:55] offset:512
	ds_write_b128 v250, v[44:47] offset:528
	ds_write_b128 v228, v[212:215] offset:0
	ds_write_b128 v228, v[212:215] offset:16
	ds_write_b128 v228, v[212:215] offset:512
	ds_write_b128 v228, v[212:215] offset:528
	s_mov_b64 exec, s[56:57]
	v_add_u32_e32 v251, s92, v228
	ds_write_b128 v251, v[80:83] offset:0
	ds_write_b128 v251, v[72:75] offset:16
	ds_write_b128 v251, v[68:71] offset:512
	ds_write_b128 v251, v[64:67] offset:528
	v_add_u32_e32 v251, s94, v228
	ds_write_b128 v251, v[16:19] offset:0
	ds_write_b128 v251, v[8:11] offset:16
	ds_write_b128 v251, v[4:7] offset:512
	ds_write_b128 v251, v[0:3] offset:528
	ds_write_b128 v228, v[212:215] offset:7168
	ds_write_b128 v228, v[212:215] offset:7184
	ds_write_b128 v228, v[212:215] offset:7680
	ds_write_b128 v228, v[212:215] offset:7696
	s_mov_b64 exec, s[58:59]
	s_waitcnt lgkmcnt(0)
	s_barrier
	ds_read_b128 v[184:187], v231 offset:0
	ds_read_b128 v[188:191], v231 offset:512
	ds_read_b128 v[192:195], v231 offset:2048
	ds_read_b128 v[196:199], v231 offset:2560
	s_waitcnt vmcnt(0)
	v_cndmask_b32_e64 v216, 0, v128, s[54:55]
	v_cndmask_b32_e64 v220, 0, v136, s[56:57]
	v_cndmask_b32_e64 v217, 0, v129, s[54:55]
	v_cndmask_b32_e64 v221, 0, v137, s[56:57]
	v_cndmask_b32_e64 v218, 0, v130, s[54:55]
	v_cndmask_b32_e64 v222, 0, v138, s[56:57]
	v_cndmask_b32_e64 v219, 0, v131, s[54:55]
	v_cndmask_b32_e64 v223, 0, v139, s[56:57]
	v_cndmask_b32_e64 v224, 0, v160, s[54:55]
	v_cndmask_b32_e64 v232, 0, v176, s[56:57]
	v_cndmask_b32_e64 v225, 0, v161, s[54:55]
	v_cndmask_b32_e64 v233, 0, v177, s[56:57]
	v_cndmask_b32_e64 v226, 0, v162, s[54:55]
	v_cndmask_b32_e64 v234, 0, v178, s[56:57]
	v_cndmask_b32_e64 v227, 0, v163, s[54:55]
	v_cndmask_b32_e64 v235, 0, v179, s[56:57]
	s_waitcnt lgkmcnt(0)
	s_nop 1
	v_fma_f32 v200, v132, v124, v140
	v_fma_f32 v201, v133, v125, v141
	v_fma_f32 v202, v134, v126, v142
	v_fma_f32 v203, v135, v127, v143
	v_fmac_f32_dpp v200, v80, v128 row_shr:1 row_mask:0xf bank_mask:0xf
	v_fmac_f32_dpp v201, v81, v129 row_shr:1 row_mask:0xf bank_mask:0xf
	v_fmac_f32_dpp v202, v82, v130 row_shr:1 row_mask:0xf bank_mask:0xf
	v_fmac_f32_dpp v203, v83, v131 row_shr:1 row_mask:0xf bank_mask:0xf
	v_fmac_f32_e32 v200, v184, v216
	v_fmac_f32_e32 v201, v185, v217
	v_fmac_f32_e32 v202, v186, v218
	v_fmac_f32_e32 v203, v187, v219
	v_fmac_f32_e32 v200, v116, v136
	v_fmac_f32_e32 v201, v117, v137
	v_fmac_f32_e32 v202, v118, v138
	v_fmac_f32_e32 v203, v119, v139
	v_fma_f32 v204, v172, v108, v180
	v_fma_f32 v205, v173, v109, v181
	v_fma_f32 v206, v174, v110, v182
	v_fma_f32 v207, v175, v111, v183
	v_fmac_f32_dpp v204, v68, v160 row_shr:1 row_mask:0xf bank_mask:0xf
	v_fmac_f32_dpp v205, v69, v161 row_shr:1 row_mask:0xf bank_mask:0xf
	v_fmac_f32_dpp v206, v70, v162 row_shr:1 row_mask:0xf bank_mask:0xf
	v_fmac_f32_dpp v207, v71, v163 row_shr:1 row_mask:0xf bank_mask:0xf
	v_fmac_f32_e32 v204, v188, v224
	v_fmac_f32_e32 v205, v189, v225
	v_fmac_f32_e32 v206, v190, v226
	v_fmac_f32_e32 v207, v191, v227
	v_fmac_f32_e32 v204, v100, v176
	v_fmac_f32_e32 v205, v101, v177
	v_fmac_f32_e32 v206, v102, v178
	v_fmac_f32_e32 v207, v103, v179
	v_mul_f32_e32 v208, 0xbfb8aa3b, v200
	v_mul_f32_e32 v209, 0xbfb8aa3b, v201
	v_mul_f32_e32 v210, 0xbfb8aa3b, v202
	v_mul_f32_e32 v211, 0xbfb8aa3b, v203
	v_exp_f32_e32 v208, v208
	v_exp_f32_e32 v209, v209
	v_exp_f32_e32 v210, v210
	v_exp_f32_e32 v211, v211
	v_add_f32_e32 v208, 1.0, v208
	v_add_f32_e32 v209, 1.0, v209
	v_add_f32_e32 v210, 1.0, v210
	v_add_f32_e32 v211, 1.0, v211
	v_rcp_f32_e32 v208, v208
	v_rcp_f32_e32 v209, v209
	v_rcp_f32_e32 v210, v210
	v_rcp_f32_e32 v211, v211
	v_mul_f32_e32 v200, v200, v208
	v_mul_f32_e32 v201, v201, v209
	v_mul_f32_e32 v202, v202, v210
	v_mul_f32_e32 v203, v203, v211
	v_mul_f32_e32 v200, v200, v204
	v_mul_f32_e32 v201, v201, v205
	v_mul_f32_e32 v202, v202, v206
	v_mul_f32_e32 v203, v203, v207
	v_cvt_pk_bf16_f32 v236, v200, v201
	v_cvt_pk_bf16_f32 v237, v202, v203
	v_fma_f32 v200, v132, v116, v140
	v_fma_f32 v201, v133, v117, v141
	v_fma_f32 v202, v134, v118, v142
	v_fma_f32 v203, v135, v119, v143
	v_fmac_f32_e32 v200, v124, v128
	v_fmac_f32_e32 v201, v125, v129
	v_fmac_f32_e32 v202, v126, v130
	v_fmac_f32_e32 v203, v127, v131
	v_fmac_f32_e32 v200, v96, v136
	v_fmac_f32_e32 v201, v97, v137
	v_fmac_f32_e32 v202, v98, v138
	v_fmac_f32_e32 v203, v99, v139
	v_fma_f32 v204, v172, v100, v180
	v_fma_f32 v205, v173, v101, v181
	v_fma_f32 v206, v174, v102, v182
	v_fma_f32 v207, v175, v103, v183
	v_fmac_f32_e32 v204, v108, v160
	v_fmac_f32_e32 v205, v109, v161
	v_fmac_f32_e32 v206, v110, v162
	v_fmac_f32_e32 v207, v111, v163
	v_fmac_f32_e32 v204, v84, v176
	v_fmac_f32_e32 v205, v85, v177
	v_fmac_f32_e32 v206, v86, v178
	v_fmac_f32_e32 v207, v87, v179
	v_mul_f32_e32 v208, 0xbfb8aa3b, v200
	v_mul_f32_e32 v209, 0xbfb8aa3b, v201
	v_mul_f32_e32 v210, 0xbfb8aa3b, v202
	v_mul_f32_e32 v211, 0xbfb8aa3b, v203
	v_exp_f32_e32 v208, v208
	v_exp_f32_e32 v209, v209
	v_exp_f32_e32 v210, v210
	v_exp_f32_e32 v211, v211
	v_add_f32_e32 v208, 1.0, v208
	v_add_f32_e32 v209, 1.0, v209
	v_add_f32_e32 v210, 1.0, v210
	v_add_f32_e32 v211, 1.0, v211
	v_rcp_f32_e32 v208, v208
	v_rcp_f32_e32 v209, v209
	v_rcp_f32_e32 v210, v210
	v_rcp_f32_e32 v211, v211
	v_mul_f32_e32 v200, v200, v208
	v_mul_f32_e32 v201, v201, v209
	v_mul_f32_e32 v202, v202, v210
	v_mul_f32_e32 v203, v203, v211
	v_mul_f32_e32 v200, v200, v204
	v_mul_f32_e32 v201, v201, v205
	v_mul_f32_e32 v202, v202, v206
	v_mul_f32_e32 v203, v203, v207
	v_cvt_pk_bf16_f32 v238, v200, v201
	v_cvt_pk_bf16_f32 v239, v202, v203
	v_fma_f32 v200, v132, v96, v140
	v_fma_f32 v201, v133, v97, v141
	v_fma_f32 v202, v134, v98, v142
	v_fma_f32 v203, v135, v99, v143
	v_fmac_f32_e32 v200, v116, v128
	v_fmac_f32_e32 v201, v117, v129
	v_fmac_f32_e32 v202, v118, v130
	v_fmac_f32_e32 v203, v119, v131
	v_fmac_f32_e32 v200, v80, v136
	v_fmac_f32_e32 v201, v81, v137
	v_fmac_f32_e32 v202, v82, v138
	v_fmac_f32_e32 v203, v83, v139
	v_fma_f32 v204, v172, v84, v180
	v_fma_f32 v205, v173, v85, v181
	v_fma_f32 v206, v174, v86, v182
	v_fma_f32 v207, v175, v87, v183
	v_fmac_f32_e32 v204, v100, v160
	v_fmac_f32_e32 v205, v101, v161
	v_fmac_f32_e32 v206, v102, v162
	v_fmac_f32_e32 v207, v103, v163
	v_fmac_f32_e32 v204, v68, v176
	v_fmac_f32_e32 v205, v69, v177
	v_fmac_f32_e32 v206, v70, v178
	v_fmac_f32_e32 v207, v71, v179
	v_mul_f32_e32 v208, 0xbfb8aa3b, v200
	v_mul_f32_e32 v209, 0xbfb8aa3b, v201
	v_mul_f32_e32 v210, 0xbfb8aa3b, v202
	v_mul_f32_e32 v211, 0xbfb8aa3b, v203
	v_exp_f32_e32 v208, v208
	v_exp_f32_e32 v209, v209
	v_exp_f32_e32 v210, v210
	v_exp_f32_e32 v211, v211
	v_add_f32_e32 v208, 1.0, v208
	v_add_f32_e32 v209, 1.0, v209
	v_add_f32_e32 v210, 1.0, v210
	v_add_f32_e32 v211, 1.0, v211
	v_rcp_f32_e32 v208, v208
	v_rcp_f32_e32 v209, v209
	v_rcp_f32_e32 v210, v210
	v_rcp_f32_e32 v211, v211
	v_mul_f32_e32 v200, v200, v208
	v_mul_f32_e32 v201, v201, v209
	v_mul_f32_e32 v202, v202, v210
	v_mul_f32_e32 v203, v203, v211
	v_mul_f32_e32 v200, v200, v204
	v_mul_f32_e32 v201, v201, v205
	v_mul_f32_e32 v202, v202, v206
	v_mul_f32_e32 v203, v203, v207
	v_cvt_pk_bf16_f32 v240, v200, v201
	v_cvt_pk_bf16_f32 v241, v202, v203
	v_fma_f32 v200, v132, v80, v140
	v_fma_f32 v201, v133, v81, v141
	v_fma_f32 v202, v134, v82, v142
	v_fma_f32 v203, v135, v83, v143
	v_fmac_f32_e32 v200, v96, v128
	v_fmac_f32_e32 v201, v97, v129
	v_fmac_f32_e32 v202, v98, v130
	v_fmac_f32_e32 v203, v99, v131
	v_fmac_f32_dpp v200, v124, v136 row_shl:1 row_mask:0xf bank_mask:0xf
	v_fmac_f32_dpp v201, v125, v137 row_shl:1 row_mask:0xf bank_mask:0xf
	v_fmac_f32_dpp v202, v126, v138 row_shl:1 row_mask:0xf bank_mask:0xf
	v_fmac_f32_dpp v203, v127, v139 row_shl:1 row_mask:0xf bank_mask:0xf
	v_fmac_f32_e32 v200, v184, v220
	v_fmac_f32_e32 v201, v185, v221
	v_fmac_f32_e32 v202, v186, v222
	v_fmac_f32_e32 v203, v187, v223
	v_fma_f32 v204, v172, v68, v180
	v_fma_f32 v205, v173, v69, v181
	v_fma_f32 v206, v174, v70, v182
	v_fma_f32 v207, v175, v71, v183
	v_fmac_f32_e32 v204, v84, v160
	v_fmac_f32_e32 v205, v85, v161
	v_fmac_f32_e32 v206, v86, v162
	v_fmac_f32_e32 v207, v87, v163
	v_fmac_f32_dpp v204, v108, v176 row_shl:1 row_mask:0xf bank_mask:0xf
	v_fmac_f32_dpp v205, v109, v177 row_shl:1 row_mask:0xf bank_mask:0xf
	v_fmac_f32_dpp v206, v110, v178 row_shl:1 row_mask:0xf bank_mask:0xf
	v_fmac_f32_dpp v207, v111, v179 row_shl:1 row_mask:0xf bank_mask:0xf
	v_fmac_f32_e32 v204, v188, v232
	v_fmac_f32_e32 v205, v189, v233
	v_fmac_f32_e32 v206, v190, v234
	v_fmac_f32_e32 v207, v191, v235
	v_mul_f32_e32 v208, 0xbfb8aa3b, v200
	v_mul_f32_e32 v209, 0xbfb8aa3b, v201
	v_mul_f32_e32 v210, 0xbfb8aa3b, v202
	v_mul_f32_e32 v211, 0xbfb8aa3b, v203
	v_exp_f32_e32 v208, v208
	v_exp_f32_e32 v209, v209
	v_exp_f32_e32 v210, v210
	v_exp_f32_e32 v211, v211
	v_add_f32_e32 v208, 1.0, v208
	v_add_f32_e32 v209, 1.0, v209
	v_add_f32_e32 v210, 1.0, v210
	v_add_f32_e32 v211, 1.0, v211
	v_rcp_f32_e32 v208, v208
	v_rcp_f32_e32 v209, v209
	v_rcp_f32_e32 v210, v210
	v_rcp_f32_e32 v211, v211
	v_mul_f32_e32 v200, v200, v208
	v_mul_f32_e32 v201, v201, v209
	v_mul_f32_e32 v202, v202, v210
	v_mul_f32_e32 v203, v203, v211
	v_mul_f32_e32 v200, v200, v204
	v_mul_f32_e32 v201, v201, v205
	v_mul_f32_e32 v202, v202, v206
	v_mul_f32_e32 v203, v203, v207
	v_cvt_pk_bf16_f32 v242, v200, v201
	v_cvt_pk_bf16_f32 v243, v202, v203
	v_fma_f32 v200, v132, v60, v140
	v_fma_f32 v201, v133, v61, v141
	v_fma_f32 v202, v134, v62, v142
	v_fma_f32 v203, v135, v63, v143
	v_fmac_f32_dpp v200, v16, v128 row_shr:1 row_mask:0xf bank_mask:0xf
	v_fmac_f32_dpp v201, v17, v129 row_shr:1 row_mask:0xf bank_mask:0xf
	v_fmac_f32_dpp v202, v18, v130 row_shr:1 row_mask:0xf bank_mask:0xf
	v_fmac_f32_dpp v203, v19, v131 row_shr:1 row_mask:0xf bank_mask:0xf
	v_fmac_f32_e32 v200, v192, v216
	v_fmac_f32_e32 v201, v193, v217
	v_fmac_f32_e32 v202, v194, v218
	v_fmac_f32_e32 v203, v195, v219
	v_fmac_f32_e32 v200, v48, v136
	v_fmac_f32_e32 v201, v49, v137
	v_fmac_f32_e32 v202, v50, v138
	v_fmac_f32_e32 v203, v51, v139
	v_fma_f32 v204, v172, v52, v180
	v_fma_f32 v205, v173, v53, v181
	v_fma_f32 v206, v174, v54, v182
	v_fma_f32 v207, v175, v55, v183
	v_fmac_f32_dpp v204, v4, v160 row_shr:1 row_mask:0xf bank_mask:0xf
	v_fmac_f32_dpp v205, v5, v161 row_shr:1 row_mask:0xf bank_mask:0xf
	v_fmac_f32_dpp v206, v6, v162 row_shr:1 row_mask:0xf bank_mask:0xf
	v_fmac_f32_dpp v207, v7, v163 row_shr:1 row_mask:0xf bank_mask:0xf
	v_fmac_f32_e32 v204, v196, v224
	v_fmac_f32_e32 v205, v197, v225
	v_fmac_f32_e32 v206, v198, v226
	v_fmac_f32_e32 v207, v199, v227
	v_fmac_f32_e32 v204, v36, v176
	v_fmac_f32_e32 v205, v37, v177
	v_fmac_f32_e32 v206, v38, v178
	v_fmac_f32_e32 v207, v39, v179
	v_mul_f32_e32 v208, 0xbfb8aa3b, v200
	v_mul_f32_e32 v209, 0xbfb8aa3b, v201
	v_mul_f32_e32 v210, 0xbfb8aa3b, v202
	v_mul_f32_e32 v211, 0xbfb8aa3b, v203
	v_exp_f32_e32 v208, v208
	v_exp_f32_e32 v209, v209
	v_exp_f32_e32 v210, v210
	v_exp_f32_e32 v211, v211
	v_add_f32_e32 v208, 1.0, v208
	v_add_f32_e32 v209, 1.0, v209
	v_add_f32_e32 v210, 1.0, v210
	v_add_f32_e32 v211, 1.0, v211
	v_rcp_f32_e32 v208, v208
	v_rcp_f32_e32 v209, v209
	v_rcp_f32_e32 v210, v210
	v_rcp_f32_e32 v211, v211
	v_mul_f32_e32 v200, v200, v208
	v_mul_f32_e32 v201, v201, v209
	v_mul_f32_e32 v202, v202, v210
	v_mul_f32_e32 v203, v203, v211
	v_mul_f32_e32 v200, v200, v204
	v_mul_f32_e32 v201, v201, v205
	v_mul_f32_e32 v202, v202, v206
	v_mul_f32_e32 v203, v203, v207
	v_cvt_pk_bf16_f32 v244, v200, v201
	v_cvt_pk_bf16_f32 v245, v202, v203
	v_fma_f32 v200, v132, v48, v140
	v_fma_f32 v201, v133, v49, v141
	v_fma_f32 v202, v134, v50, v142
	v_fma_f32 v203, v135, v51, v143
	v_fmac_f32_e32 v200, v60, v128
	v_fmac_f32_e32 v201, v61, v129
	v_fmac_f32_e32 v202, v62, v130
	v_fmac_f32_e32 v203, v63, v131
	v_fmac_f32_e32 v200, v32, v136
	v_fmac_f32_e32 v201, v33, v137
	v_fmac_f32_e32 v202, v34, v138
	v_fmac_f32_e32 v203, v35, v139
	v_fma_f32 v204, v172, v36, v180
	v_fma_f32 v205, v173, v37, v181
	v_fma_f32 v206, v174, v38, v182
	v_fma_f32 v207, v175, v39, v183
	v_fmac_f32_e32 v204, v52, v160
	v_fmac_f32_e32 v205, v53, v161
	v_fmac_f32_e32 v206, v54, v162
	v_fmac_f32_e32 v207, v55, v163
	v_fmac_f32_e32 v204, v20, v176
	v_fmac_f32_e32 v205, v21, v177
	v_fmac_f32_e32 v206, v22, v178
	v_fmac_f32_e32 v207, v23, v179
	v_mul_f32_e32 v208, 0xbfb8aa3b, v200
	v_mul_f32_e32 v209, 0xbfb8aa3b, v201
	v_mul_f32_e32 v210, 0xbfb8aa3b, v202
	v_mul_f32_e32 v211, 0xbfb8aa3b, v203
	v_exp_f32_e32 v208, v208
	v_exp_f32_e32 v209, v209
	v_exp_f32_e32 v210, v210
	v_exp_f32_e32 v211, v211
	v_add_f32_e32 v208, 1.0, v208
	v_add_f32_e32 v209, 1.0, v209
	v_add_f32_e32 v210, 1.0, v210
	v_add_f32_e32 v211, 1.0, v211
	v_rcp_f32_e32 v208, v208
	v_rcp_f32_e32 v209, v209
	v_rcp_f32_e32 v210, v210
	v_rcp_f32_e32 v211, v211
	v_mul_f32_e32 v200, v200, v208
	v_mul_f32_e32 v201, v201, v209
	v_mul_f32_e32 v202, v202, v210
	v_mul_f32_e32 v203, v203, v211
	v_mul_f32_e32 v200, v200, v204
	v_mul_f32_e32 v201, v201, v205
	v_mul_f32_e32 v202, v202, v206
	v_mul_f32_e32 v203, v203, v207
	v_cvt_pk_bf16_f32 v246, v200, v201
	v_cvt_pk_bf16_f32 v247, v202, v203
	v_fma_f32 v200, v132, v32, v140
	v_fma_f32 v201, v133, v33, v141
	v_fma_f32 v202, v134, v34, v142
	v_fma_f32 v203, v135, v35, v143
	v_fmac_f32_e32 v200, v48, v128
	v_fmac_f32_e32 v201, v49, v129
	v_fmac_f32_e32 v202, v50, v130
	v_fmac_f32_e32 v203, v51, v131
	v_fmac_f32_e32 v200, v16, v136
	v_fmac_f32_e32 v201, v17, v137
	v_fmac_f32_e32 v202, v18, v138
	v_fmac_f32_e32 v203, v19, v139
	v_fma_f32 v204, v172, v20, v180
	v_fma_f32 v205, v173, v21, v181
	v_fma_f32 v206, v174, v22, v182
	v_fma_f32 v207, v175, v23, v183
	v_fmac_f32_e32 v204, v36, v160
	v_fmac_f32_e32 v205, v37, v161
	v_fmac_f32_e32 v206, v38, v162
	v_fmac_f32_e32 v207, v39, v163
	v_fmac_f32_e32 v204, v4, v176
	v_fmac_f32_e32 v205, v5, v177
	v_fmac_f32_e32 v206, v6, v178
	v_fmac_f32_e32 v207, v7, v179
	v_mul_f32_e32 v208, 0xbfb8aa3b, v200
	v_mul_f32_e32 v209, 0xbfb8aa3b, v201
	v_mul_f32_e32 v210, 0xbfb8aa3b, v202
	v_mul_f32_e32 v211, 0xbfb8aa3b, v203
	v_exp_f32_e32 v208, v208
	v_exp_f32_e32 v209, v209
	v_exp_f32_e32 v210, v210
	v_exp_f32_e32 v211, v211
	v_add_f32_e32 v208, 1.0, v208
	v_add_f32_e32 v209, 1.0, v209
	v_add_f32_e32 v210, 1.0, v210
	v_add_f32_e32 v211, 1.0, v211
	v_rcp_f32_e32 v208, v208
	v_rcp_f32_e32 v209, v209
	v_rcp_f32_e32 v210, v210
	v_rcp_f32_e32 v211, v211
	v_mul_f32_e32 v200, v200, v208
	v_mul_f32_e32 v201, v201, v209
	v_mul_f32_e32 v202, v202, v210
	v_mul_f32_e32 v203, v203, v211
	v_mul_f32_e32 v200, v200, v204
	v_mul_f32_e32 v201, v201, v205
	v_mul_f32_e32 v202, v202, v206
	v_mul_f32_e32 v203, v203, v207
	v_cvt_pk_bf16_f32 v248, v200, v201
	v_cvt_pk_bf16_f32 v249, v202, v203
	v_fma_f32 v200, v132, v16, v140
	v_fma_f32 v201, v133, v17, v141
	v_fma_f32 v202, v134, v18, v142
	v_fma_f32 v203, v135, v19, v143
	v_fmac_f32_e32 v200, v32, v128
	v_fmac_f32_e32 v201, v33, v129
	v_fmac_f32_e32 v202, v34, v130
	v_fmac_f32_e32 v203, v35, v131
	v_fmac_f32_dpp v200, v60, v136 row_shl:1 row_mask:0xf bank_mask:0xf
	v_fmac_f32_dpp v201, v61, v137 row_shl:1 row_mask:0xf bank_mask:0xf
	v_fmac_f32_dpp v202, v62, v138 row_shl:1 row_mask:0xf bank_mask:0xf
	v_fmac_f32_dpp v203, v63, v139 row_shl:1 row_mask:0xf bank_mask:0xf
	v_fmac_f32_e32 v200, v192, v220
	v_fmac_f32_e32 v201, v193, v221
	v_fmac_f32_e32 v202, v194, v222
	v_fmac_f32_e32 v203, v195, v223
	v_fma_f32 v204, v172, v4, v180
	v_fma_f32 v205, v173, v5, v181
	v_fma_f32 v206, v174, v6, v182
	v_fma_f32 v207, v175, v7, v183
	v_fmac_f32_e32 v204, v20, v160
	v_fmac_f32_e32 v205, v21, v161
	v_fmac_f32_e32 v206, v22, v162
	v_fmac_f32_e32 v207, v23, v163
	v_fmac_f32_dpp v204, v52, v176 row_shl:1 row_mask:0xf bank_mask:0xf
	v_fmac_f32_dpp v205, v53, v177 row_shl:1 row_mask:0xf bank_mask:0xf
	v_fmac_f32_dpp v206, v54, v178 row_shl:1 row_mask:0xf bank_mask:0xf
	v_fmac_f32_dpp v207, v55, v179 row_shl:1 row_mask:0xf bank_mask:0xf
	v_fmac_f32_e32 v204, v196, v232
	v_fmac_f32_e32 v205, v197, v233
	v_fmac_f32_e32 v206, v198, v234
	v_fmac_f32_e32 v207, v199, v235
	v_mul_f32_e32 v208, 0xbfb8aa3b, v200
	v_mul_f32_e32 v209, 0xbfb8aa3b, v201
	v_mul_f32_e32 v210, 0xbfb8aa3b, v202
	v_mul_f32_e32 v211, 0xbfb8aa3b, v203
	v_exp_f32_e32 v208, v208
	v_exp_f32_e32 v209, v209
	v_exp_f32_e32 v210, v210
	v_exp_f32_e32 v211, v211
	v_add_f32_e32 v208, 1.0, v208
	v_add_f32_e32 v209, 1.0, v209
	v_add_f32_e32 v210, 1.0, v210
	v_add_f32_e32 v211, 1.0, v211
	v_rcp_f32_e32 v208, v208
	v_rcp_f32_e32 v209, v209
	v_rcp_f32_e32 v210, v210
	v_rcp_f32_e32 v211, v211
	v_mul_f32_e32 v200, v200, v208
	v_mul_f32_e32 v201, v201, v209
	v_mul_f32_e32 v202, v202, v210
	v_mul_f32_e32 v203, v203, v211
	v_mul_f32_e32 v200, v200, v204
	v_mul_f32_e32 v201, v201, v205
	v_mul_f32_e32 v202, v202, v206
	v_mul_f32_e32 v203, v203, v207
	v_cvt_pk_bf16_f32 v250, v200, v201
	v_cvt_pk_bf16_f32 v251, v202, v203
	global_load_dwordx4 v[128:131], v229, s[36:37] offset:16
	v_add_u32_e32 v211, 0x5800, v229
	global_load_dwordx4 v[132:135], v211, s[36:37] offset:16
	v_add_u32_e32 v210, 0xb000, v229
	global_load_dwordx4 v[136:139], v210, s[36:37] offset:16
	global_load_dwordx4 v[140:143], v229, s[38:39] offset:16
	v_add_u32_e32 v210, 0x2c00, v229
	global_load_dwordx4 v[160:163], v210, s[36:37] offset:16
	v_add_u32_e32 v211, 0x8400, v229
	global_load_dwordx4 v[172:175], v211, s[36:37] offset:16
	v_add_u32_e32 v210, 0xdc00, v229
	global_load_dwordx4 v[176:179], v210, s[36:37] offset:16
	v_add_u32_e32 v211, 0x2c00, v229
	global_load_dwordx4 v[180:183], v211, s[38:39] offset:16
	v_mov_b32_e32 v124, v236
	v_mov_b32_e32 v125, v237
	v_mov_b32_e32 v116, v238
	v_mov_b32_e32 v117, v239
	v_mov_b32_e32 v96, v240
	v_mov_b32_e32 v97, v241
	v_mov_b32_e32 v80, v242
	v_mov_b32_e32 v81, v243
	v_mov_b32_e32 v60, v244
	v_mov_b32_e32 v61, v245
	v_mov_b32_e32 v48, v246
	v_mov_b32_e32 v49, v247
	v_mov_b32_e32 v32, v248
	v_mov_b32_e32 v33, v249
	v_mov_b32_e32 v16, v250
	v_mov_b32_e32 v17, v251
	ds_read_b128 v[184:187], v231 offset:16
	ds_read_b128 v[188:191], v231 offset:528
	ds_read_b128 v[192:195], v231 offset:2064
	ds_read_b128 v[196:199], v231 offset:2576
	s_waitcnt vmcnt(0)
	v_cndmask_b32_e64 v216, 0, v128, s[54:55]
	v_cndmask_b32_e64 v220, 0, v136, s[56:57]
	v_cndmask_b32_e64 v217, 0, v129, s[54:55]
	v_cndmask_b32_e64 v221, 0, v137, s[56:57]
	v_cndmask_b32_e64 v218, 0, v130, s[54:55]
	v_cndmask_b32_e64 v222, 0, v138, s[56:57]
	v_cndmask_b32_e64 v219, 0, v131, s[54:55]
	v_cndmask_b32_e64 v223, 0, v139, s[56:57]
	v_cndmask_b32_e64 v224, 0, v160, s[54:55]
	v_cndmask_b32_e64 v232, 0, v176, s[56:57]
	v_cndmask_b32_e64 v225, 0, v161, s[54:55]
	v_cndmask_b32_e64 v233, 0, v177, s[56:57]
	v_cndmask_b32_e64 v226, 0, v162, s[54:55]
	v_cndmask_b32_e64 v234, 0, v178, s[56:57]
	v_cndmask_b32_e64 v227, 0, v163, s[54:55]
	v_cndmask_b32_e64 v235, 0, v179, s[56:57]
	s_waitcnt lgkmcnt(0)
	s_nop 1
	v_fma_f32 v200, v132, v120, v140
	v_fma_f32 v201, v133, v121, v141
	v_fma_f32 v202, v134, v122, v142
	v_fma_f32 v203, v135, v123, v143
	v_fmac_f32_dpp v200, v72, v128 row_shr:1 row_mask:0xf bank_mask:0xf
	v_fmac_f32_dpp v201, v73, v129 row_shr:1 row_mask:0xf bank_mask:0xf
	v_fmac_f32_dpp v202, v74, v130 row_shr:1 row_mask:0xf bank_mask:0xf
	v_fmac_f32_dpp v203, v75, v131 row_shr:1 row_mask:0xf bank_mask:0xf
	v_fmac_f32_e32 v200, v184, v216
	v_fmac_f32_e32 v201, v185, v217
	v_fmac_f32_e32 v202, v186, v218
	v_fmac_f32_e32 v203, v187, v219
	v_fmac_f32_e32 v200, v112, v136
	v_fmac_f32_e32 v201, v113, v137
	v_fmac_f32_e32 v202, v114, v138
	v_fmac_f32_e32 v203, v115, v139
	v_fma_f32 v204, v172, v104, v180
	v_fma_f32 v205, v173, v105, v181
	v_fma_f32 v206, v174, v106, v182
	v_fma_f32 v207, v175, v107, v183
	v_fmac_f32_dpp v204, v64, v160 row_shr:1 row_mask:0xf bank_mask:0xf
	v_fmac_f32_dpp v205, v65, v161 row_shr:1 row_mask:0xf bank_mask:0xf
	v_fmac_f32_dpp v206, v66, v162 row_shr:1 row_mask:0xf bank_mask:0xf
	v_fmac_f32_dpp v207, v67, v163 row_shr:1 row_mask:0xf bank_mask:0xf
	v_fmac_f32_e32 v204, v188, v224
	v_fmac_f32_e32 v205, v189, v225
	v_fmac_f32_e32 v206, v190, v226
	v_fmac_f32_e32 v207, v191, v227
	v_fmac_f32_e32 v204, v92, v176
	v_fmac_f32_e32 v205, v93, v177
	v_fmac_f32_e32 v206, v94, v178
	v_fmac_f32_e32 v207, v95, v179
	v_mul_f32_e32 v208, 0xbfb8aa3b, v200
	v_mul_f32_e32 v209, 0xbfb8aa3b, v201
	v_mul_f32_e32 v210, 0xbfb8aa3b, v202
	v_mul_f32_e32 v211, 0xbfb8aa3b, v203
	v_exp_f32_e32 v208, v208
	v_exp_f32_e32 v209, v209
	v_exp_f32_e32 v210, v210
	v_exp_f32_e32 v211, v211
	v_add_f32_e32 v208, 1.0, v208
	v_add_f32_e32 v209, 1.0, v209
	v_add_f32_e32 v210, 1.0, v210
	v_add_f32_e32 v211, 1.0, v211
	v_rcp_f32_e32 v208, v208
	v_rcp_f32_e32 v209, v209
	v_rcp_f32_e32 v210, v210
	v_rcp_f32_e32 v211, v211
	v_mul_f32_e32 v200, v200, v208
	v_mul_f32_e32 v201, v201, v209
	v_mul_f32_e32 v202, v202, v210
	v_mul_f32_e32 v203, v203, v211
	v_mul_f32_e32 v200, v200, v204
	v_mul_f32_e32 v201, v201, v205
	v_mul_f32_e32 v202, v202, v206
	v_mul_f32_e32 v203, v203, v207
	v_cvt_pk_bf16_f32 v126, v200, v201
	v_cvt_pk_bf16_f32 v127, v202, v203
	v_fma_f32 v200, v132, v112, v140
	v_fma_f32 v201, v133, v113, v141
	v_fma_f32 v202, v134, v114, v142
	v_fma_f32 v203, v135, v115, v143
	v_fmac_f32_e32 v200, v120, v128
	v_fmac_f32_e32 v201, v121, v129
	v_fmac_f32_e32 v202, v122, v130
	v_fmac_f32_e32 v203, v123, v131
	v_fmac_f32_e32 v200, v88, v136
	v_fmac_f32_e32 v201, v89, v137
	v_fmac_f32_e32 v202, v90, v138
	v_fmac_f32_e32 v203, v91, v139
	v_fma_f32 v204, v172, v92, v180
	v_fma_f32 v205, v173, v93, v181
	v_fma_f32 v206, v174, v94, v182
	v_fma_f32 v207, v175, v95, v183
	v_fmac_f32_e32 v204, v104, v160
	v_fmac_f32_e32 v205, v105, v161
	v_fmac_f32_e32 v206, v106, v162
	v_fmac_f32_e32 v207, v107, v163
	v_fmac_f32_e32 v204, v76, v176
	v_fmac_f32_e32 v205, v77, v177
	v_fmac_f32_e32 v206, v78, v178
	v_fmac_f32_e32 v207, v79, v179
	v_mul_f32_e32 v208, 0xbfb8aa3b, v200
	v_mul_f32_e32 v209, 0xbfb8aa3b, v201
	v_mul_f32_e32 v210, 0xbfb8aa3b, v202
	v_mul_f32_e32 v211, 0xbfb8aa3b, v203
	v_exp_f32_e32 v208, v208
	v_exp_f32_e32 v209, v209
	v_exp_f32_e32 v210, v210
	v_exp_f32_e32 v211, v211
	v_add_f32_e32 v208, 1.0, v208
	v_add_f32_e32 v209, 1.0, v209
	v_add_f32_e32 v210, 1.0, v210
	v_add_f32_e32 v211, 1.0, v211
	v_rcp_f32_e32 v208, v208
	v_rcp_f32_e32 v209, v209
	v_rcp_f32_e32 v210, v210
	v_rcp_f32_e32 v211, v211
	v_mul_f32_e32 v200, v200, v208
	v_mul_f32_e32 v201, v201, v209
	v_mul_f32_e32 v202, v202, v210
	v_mul_f32_e32 v203, v203, v211
	v_mul_f32_e32 v200, v200, v204
	v_mul_f32_e32 v201, v201, v205
	v_mul_f32_e32 v202, v202, v206
	v_mul_f32_e32 v203, v203, v207
	v_cvt_pk_bf16_f32 v118, v200, v201
	v_cvt_pk_bf16_f32 v119, v202, v203
	v_fma_f32 v200, v132, v88, v140
	v_fma_f32 v201, v133, v89, v141
	v_fma_f32 v202, v134, v90, v142
	v_fma_f32 v203, v135, v91, v143
	v_fmac_f32_e32 v200, v112, v128
	v_fmac_f32_e32 v201, v113, v129
	v_fmac_f32_e32 v202, v114, v130
	v_fmac_f32_e32 v203, v115, v131
	v_fmac_f32_e32 v200, v72, v136
	v_fmac_f32_e32 v201, v73, v137
	v_fmac_f32_e32 v202, v74, v138
	v_fmac_f32_e32 v203, v75, v139
	v_fma_f32 v204, v172, v76, v180
	v_fma_f32 v205, v173, v77, v181
	v_fma_f32 v206, v174, v78, v182
	v_fma_f32 v207, v175, v79, v183
	v_fmac_f32_e32 v204, v92, v160
	v_fmac_f32_e32 v205, v93, v161
	v_fmac_f32_e32 v206, v94, v162
	v_fmac_f32_e32 v207, v95, v163
	v_fmac_f32_e32 v204, v64, v176
	v_fmac_f32_e32 v205, v65, v177
	v_fmac_f32_e32 v206, v66, v178
	v_fmac_f32_e32 v207, v67, v179
	v_mul_f32_e32 v208, 0xbfb8aa3b, v200
	v_mul_f32_e32 v209, 0xbfb8aa3b, v201
	v_mul_f32_e32 v210, 0xbfb8aa3b, v202
	v_mul_f32_e32 v211, 0xbfb8aa3b, v203
	v_exp_f32_e32 v208, v208
	v_exp_f32_e32 v209, v209
	v_exp_f32_e32 v210, v210
	v_exp_f32_e32 v211, v211
	v_add_f32_e32 v208, 1.0, v208
	v_add_f32_e32 v209, 1.0, v209
	v_add_f32_e32 v210, 1.0, v210
	v_add_f32_e32 v211, 1.0, v211
	v_rcp_f32_e32 v208, v208
	v_rcp_f32_e32 v209, v209
	v_rcp_f32_e32 v210, v210
	v_rcp_f32_e32 v211, v211
	v_mul_f32_e32 v200, v200, v208
	v_mul_f32_e32 v201, v201, v209
	v_mul_f32_e32 v202, v202, v210
	v_mul_f32_e32 v203, v203, v211
	v_mul_f32_e32 v200, v200, v204
	v_mul_f32_e32 v201, v201, v205
	v_mul_f32_e32 v202, v202, v206
	v_mul_f32_e32 v203, v203, v207
	v_cvt_pk_bf16_f32 v98, v200, v201
	v_cvt_pk_bf16_f32 v99, v202, v203
	v_fma_f32 v200, v132, v72, v140
	v_fma_f32 v201, v133, v73, v141
	v_fma_f32 v202, v134, v74, v142
	v_fma_f32 v203, v135, v75, v143
	v_fmac_f32_e32 v200, v88, v128
	v_fmac_f32_e32 v201, v89, v129
	v_fmac_f32_e32 v202, v90, v130
	v_fmac_f32_e32 v203, v91, v131
	v_fmac_f32_dpp v200, v120, v136 row_shl:1 row_mask:0xf bank_mask:0xf
	v_fmac_f32_dpp v201, v121, v137 row_shl:1 row_mask:0xf bank_mask:0xf
	v_fmac_f32_dpp v202, v122, v138 row_shl:1 row_mask:0xf bank_mask:0xf
	v_fmac_f32_dpp v203, v123, v139 row_shl:1 row_mask:0xf bank_mask:0xf
	v_fmac_f32_e32 v200, v184, v220
	v_fmac_f32_e32 v201, v185, v221
	v_fmac_f32_e32 v202, v186, v222
	v_fmac_f32_e32 v203, v187, v223
	v_fma_f32 v204, v172, v64, v180
	v_fma_f32 v205, v173, v65, v181
	v_fma_f32 v206, v174, v66, v182
	v_fma_f32 v207, v175, v67, v183
	v_fmac_f32_e32 v204, v76, v160
	v_fmac_f32_e32 v205, v77, v161
	v_fmac_f32_e32 v206, v78, v162
	v_fmac_f32_e32 v207, v79, v163
	v_fmac_f32_dpp v204, v104, v176 row_shl:1 row_mask:0xf bank_mask:0xf
	v_fmac_f32_dpp v205, v105, v177 row_shl:1 row_mask:0xf bank_mask:0xf
	v_fmac_f32_dpp v206, v106, v178 row_shl:1 row_mask:0xf bank_mask:0xf
	v_fmac_f32_dpp v207, v107, v179 row_shl:1 row_mask:0xf bank_mask:0xf
	v_fmac_f32_e32 v204, v188, v232
	v_fmac_f32_e32 v205, v189, v233
	v_fmac_f32_e32 v206, v190, v234
	v_fmac_f32_e32 v207, v191, v235
	v_mul_f32_e32 v208, 0xbfb8aa3b, v200
	v_mul_f32_e32 v209, 0xbfb8aa3b, v201
	v_mul_f32_e32 v210, 0xbfb8aa3b, v202
	v_mul_f32_e32 v211, 0xbfb8aa3b, v203
	v_exp_f32_e32 v208, v208
	v_exp_f32_e32 v209, v209
	v_exp_f32_e32 v210, v210
	v_exp_f32_e32 v211, v211
	v_add_f32_e32 v208, 1.0, v208
	v_add_f32_e32 v209, 1.0, v209
	v_add_f32_e32 v210, 1.0, v210
	v_add_f32_e32 v211, 1.0, v211
	v_rcp_f32_e32 v208, v208
	v_rcp_f32_e32 v209, v209
	v_rcp_f32_e32 v210, v210
	v_rcp_f32_e32 v211, v211
	v_mul_f32_e32 v200, v200, v208
	v_mul_f32_e32 v201, v201, v209
	v_mul_f32_e32 v202, v202, v210
	v_mul_f32_e32 v203, v203, v211
	v_mul_f32_e32 v200, v200, v204
	v_mul_f32_e32 v201, v201, v205
	v_mul_f32_e32 v202, v202, v206
	v_mul_f32_e32 v203, v203, v207
	v_cvt_pk_bf16_f32 v82, v200, v201
	v_cvt_pk_bf16_f32 v83, v202, v203
	v_fma_f32 v200, v132, v56, v140
	v_fma_f32 v201, v133, v57, v141
	v_fma_f32 v202, v134, v58, v142
	v_fma_f32 v203, v135, v59, v143
	v_fmac_f32_dpp v200, v8, v128 row_shr:1 row_mask:0xf bank_mask:0xf
	v_fmac_f32_dpp v201, v9, v129 row_shr:1 row_mask:0xf bank_mask:0xf
	v_fmac_f32_dpp v202, v10, v130 row_shr:1 row_mask:0xf bank_mask:0xf
	v_fmac_f32_dpp v203, v11, v131 row_shr:1 row_mask:0xf bank_mask:0xf
	v_fmac_f32_e32 v200, v192, v216
	v_fmac_f32_e32 v201, v193, v217
	v_fmac_f32_e32 v202, v194, v218
	v_fmac_f32_e32 v203, v195, v219
	v_fmac_f32_e32 v200, v40, v136
	v_fmac_f32_e32 v201, v41, v137
	v_fmac_f32_e32 v202, v42, v138
	v_fmac_f32_e32 v203, v43, v139
	v_fma_f32 v204, v172, v44, v180
	v_fma_f32 v205, v173, v45, v181
	v_fma_f32 v206, v174, v46, v182
	v_fma_f32 v207, v175, v47, v183
	v_fmac_f32_dpp v204, v0, v160 row_shr:1 row_mask:0xf bank_mask:0xf
	v_fmac_f32_dpp v205, v1, v161 row_shr:1 row_mask:0xf bank_mask:0xf
	v_fmac_f32_dpp v206, v2, v162 row_shr:1 row_mask:0xf bank_mask:0xf
	v_fmac_f32_dpp v207, v3, v163 row_shr:1 row_mask:0xf bank_mask:0xf
	v_fmac_f32_e32 v204, v196, v224
	v_fmac_f32_e32 v205, v197, v225
	v_fmac_f32_e32 v206, v198, v226
	v_fmac_f32_e32 v207, v199, v227
	v_fmac_f32_e32 v204, v28, v176
	v_fmac_f32_e32 v205, v29, v177
	v_fmac_f32_e32 v206, v30, v178
	v_fmac_f32_e32 v207, v31, v179
	v_mul_f32_e32 v208, 0xbfb8aa3b, v200
	v_mul_f32_e32 v209, 0xbfb8aa3b, v201
	v_mul_f32_e32 v210, 0xbfb8aa3b, v202
	v_mul_f32_e32 v211, 0xbfb8aa3b, v203
	v_exp_f32_e32 v208, v208
	v_exp_f32_e32 v209, v209
	v_exp_f32_e32 v210, v210
	v_exp_f32_e32 v211, v211
	v_add_f32_e32 v208, 1.0, v208
	v_add_f32_e32 v209, 1.0, v209
	v_add_f32_e32 v210, 1.0, v210
	v_add_f32_e32 v211, 1.0, v211
	v_rcp_f32_e32 v208, v208
	v_rcp_f32_e32 v209, v209
	v_rcp_f32_e32 v210, v210
	v_rcp_f32_e32 v211, v211
	v_mul_f32_e32 v200, v200, v208
	v_mul_f32_e32 v201, v201, v209
	v_mul_f32_e32 v202, v202, v210
	v_mul_f32_e32 v203, v203, v211
	v_mul_f32_e32 v200, v200, v204
	v_mul_f32_e32 v201, v201, v205
	v_mul_f32_e32 v202, v202, v206
	v_mul_f32_e32 v203, v203, v207
	v_cvt_pk_bf16_f32 v62, v200, v201
	v_cvt_pk_bf16_f32 v63, v202, v203
	v_fma_f32 v200, v132, v40, v140
	v_fma_f32 v201, v133, v41, v141
	v_fma_f32 v202, v134, v42, v142
	v_fma_f32 v203, v135, v43, v143
	v_fmac_f32_e32 v200, v56, v128
	v_fmac_f32_e32 v201, v57, v129
	v_fmac_f32_e32 v202, v58, v130
	v_fmac_f32_e32 v203, v59, v131
	v_fmac_f32_e32 v200, v24, v136
	v_fmac_f32_e32 v201, v25, v137
	v_fmac_f32_e32 v202, v26, v138
	v_fmac_f32_e32 v203, v27, v139
	v_fma_f32 v204, v172, v28, v180
	v_fma_f32 v205, v173, v29, v181
	v_fma_f32 v206, v174, v30, v182
	v_fma_f32 v207, v175, v31, v183
	v_fmac_f32_e32 v204, v44, v160
	v_fmac_f32_e32 v205, v45, v161
	v_fmac_f32_e32 v206, v46, v162
	v_fmac_f32_e32 v207, v47, v163
	v_fmac_f32_e32 v204, v12, v176
	v_fmac_f32_e32 v205, v13, v177
	v_fmac_f32_e32 v206, v14, v178
	v_fmac_f32_e32 v207, v15, v179
	v_mul_f32_e32 v208, 0xbfb8aa3b, v200
	v_mul_f32_e32 v209, 0xbfb8aa3b, v201
	v_mul_f32_e32 v210, 0xbfb8aa3b, v202
	v_mul_f32_e32 v211, 0xbfb8aa3b, v203
	v_exp_f32_e32 v208, v208
	v_exp_f32_e32 v209, v209
	v_exp_f32_e32 v210, v210
	v_exp_f32_e32 v211, v211
	v_add_f32_e32 v208, 1.0, v208
	v_add_f32_e32 v209, 1.0, v209
	v_add_f32_e32 v210, 1.0, v210
	v_add_f32_e32 v211, 1.0, v211
	v_rcp_f32_e32 v208, v208
	v_rcp_f32_e32 v209, v209
	v_rcp_f32_e32 v210, v210
	v_rcp_f32_e32 v211, v211
	v_mul_f32_e32 v200, v200, v208
	v_mul_f32_e32 v201, v201, v209
	v_mul_f32_e32 v202, v202, v210
	v_mul_f32_e32 v203, v203, v211
	v_mul_f32_e32 v200, v200, v204
	v_mul_f32_e32 v201, v201, v205
	v_mul_f32_e32 v202, v202, v206
	v_mul_f32_e32 v203, v203, v207
	v_cvt_pk_bf16_f32 v50, v200, v201
	v_cvt_pk_bf16_f32 v51, v202, v203
	v_fma_f32 v200, v132, v24, v140
	v_fma_f32 v201, v133, v25, v141
	v_fma_f32 v202, v134, v26, v142
	v_fma_f32 v203, v135, v27, v143
	v_fmac_f32_e32 v200, v40, v128
	v_fmac_f32_e32 v201, v41, v129
	v_fmac_f32_e32 v202, v42, v130
	v_fmac_f32_e32 v203, v43, v131
	v_fmac_f32_e32 v200, v8, v136
	v_fmac_f32_e32 v201, v9, v137
	v_fmac_f32_e32 v202, v10, v138
	v_fmac_f32_e32 v203, v11, v139
	v_fma_f32 v204, v172, v12, v180
	v_fma_f32 v205, v173, v13, v181
	v_fma_f32 v206, v174, v14, v182
	v_fma_f32 v207, v175, v15, v183
	v_fmac_f32_e32 v204, v28, v160
	v_fmac_f32_e32 v205, v29, v161
	v_fmac_f32_e32 v206, v30, v162
	v_fmac_f32_e32 v207, v31, v163
	v_fmac_f32_e32 v204, v0, v176
	v_fmac_f32_e32 v205, v1, v177
	v_fmac_f32_e32 v206, v2, v178
	v_fmac_f32_e32 v207, v3, v179
	v_mul_f32_e32 v208, 0xbfb8aa3b, v200
	v_mul_f32_e32 v209, 0xbfb8aa3b, v201
	v_mul_f32_e32 v210, 0xbfb8aa3b, v202
	v_mul_f32_e32 v211, 0xbfb8aa3b, v203
	v_exp_f32_e32 v208, v208
	v_exp_f32_e32 v209, v209
	v_exp_f32_e32 v210, v210
	v_exp_f32_e32 v211, v211
	v_add_f32_e32 v208, 1.0, v208
	v_add_f32_e32 v209, 1.0, v209
	v_add_f32_e32 v210, 1.0, v210
	v_add_f32_e32 v211, 1.0, v211
	v_rcp_f32_e32 v208, v208
	v_rcp_f32_e32 v209, v209
	v_rcp_f32_e32 v210, v210
	v_rcp_f32_e32 v211, v211
	v_mul_f32_e32 v200, v200, v208
	v_mul_f32_e32 v201, v201, v209
	v_mul_f32_e32 v202, v202, v210
	v_mul_f32_e32 v203, v203, v211
	v_mul_f32_e32 v200, v200, v204
	v_mul_f32_e32 v201, v201, v205
	v_mul_f32_e32 v202, v202, v206
	v_mul_f32_e32 v203, v203, v207
	v_cvt_pk_bf16_f32 v34, v200, v201
	v_cvt_pk_bf16_f32 v35, v202, v203
	v_fma_f32 v200, v132, v8, v140
	v_fma_f32 v201, v133, v9, v141
	v_fma_f32 v202, v134, v10, v142
	v_fma_f32 v203, v135, v11, v143
	v_fmac_f32_e32 v200, v24, v128
	v_fmac_f32_e32 v201, v25, v129
	v_fmac_f32_e32 v202, v26, v130
	v_fmac_f32_e32 v203, v27, v131
	v_fmac_f32_dpp v200, v56, v136 row_shl:1 row_mask:0xf bank_mask:0xf
	v_fmac_f32_dpp v201, v57, v137 row_shl:1 row_mask:0xf bank_mask:0xf
	v_fmac_f32_dpp v202, v58, v138 row_shl:1 row_mask:0xf bank_mask:0xf
	v_fmac_f32_dpp v203, v59, v139 row_shl:1 row_mask:0xf bank_mask:0xf
	v_fmac_f32_e32 v200, v192, v220
	v_fmac_f32_e32 v201, v193, v221
	v_fmac_f32_e32 v202, v194, v222
	v_fmac_f32_e32 v203, v195, v223
	v_fma_f32 v204, v172, v0, v180
	v_fma_f32 v205, v173, v1, v181
	v_fma_f32 v206, v174, v2, v182
	v_fma_f32 v207, v175, v3, v183
	v_fmac_f32_e32 v204, v12, v160
	v_fmac_f32_e32 v205, v13, v161
	v_fmac_f32_e32 v206, v14, v162
	v_fmac_f32_e32 v207, v15, v163
	v_fmac_f32_dpp v204, v44, v176 row_shl:1 row_mask:0xf bank_mask:0xf
	v_fmac_f32_dpp v205, v45, v177 row_shl:1 row_mask:0xf bank_mask:0xf
	v_fmac_f32_dpp v206, v46, v178 row_shl:1 row_mask:0xf bank_mask:0xf
	v_fmac_f32_dpp v207, v47, v179 row_shl:1 row_mask:0xf bank_mask:0xf
	v_fmac_f32_e32 v204, v196, v232
	v_fmac_f32_e32 v205, v197, v233
	v_fmac_f32_e32 v206, v198, v234
	v_fmac_f32_e32 v207, v199, v235
	v_mul_f32_e32 v208, 0xbfb8aa3b, v200
	v_mul_f32_e32 v209, 0xbfb8aa3b, v201
	v_mul_f32_e32 v210, 0xbfb8aa3b, v202
	v_mul_f32_e32 v211, 0xbfb8aa3b, v203
	v_exp_f32_e32 v208, v208
	v_exp_f32_e32 v209, v209
	v_exp_f32_e32 v210, v210
	v_exp_f32_e32 v211, v211
	v_add_f32_e32 v208, 1.0, v208
	v_add_f32_e32 v209, 1.0, v209
	v_add_f32_e32 v210, 1.0, v210
	v_add_f32_e32 v211, 1.0, v211
	v_rcp_f32_e32 v208, v208
	v_rcp_f32_e32 v209, v209
	v_rcp_f32_e32 v210, v210
	v_rcp_f32_e32 v211, v211
	v_mul_f32_e32 v200, v200, v208
	v_mul_f32_e32 v201, v201, v209
	v_mul_f32_e32 v202, v202, v210
	v_mul_f32_e32 v203, v203, v211
	v_mul_f32_e32 v200, v200, v204
	v_mul_f32_e32 v201, v201, v205
	v_mul_f32_e32 v202, v202, v206
	v_mul_f32_e32 v203, v203, v207
	v_cvt_pk_bf16_f32 v18, v200, v201
	v_cvt_pk_bf16_f32 v19, v202, v203
	global_store_dwordx4 v171, v[124:127], s[40:41]
	v_add_u32_e32 v250, 0x1600, v171
	global_store_dwordx4 v250, v[116:119], s[40:41]
	s_nop 0
	v_add_u32_e32 v250, 0x2c00, v171
	global_store_dwordx4 v250, v[96:99], s[40:41]
	s_nop 0
	v_add_u32_e32 v250, 0x4200, v171
	global_store_dwordx4 v250, v[80:83], s[40:41]
	s_nop 0
	v_add_u32_e32 v250, 0xb0000, v171
	global_store_dwordx4 v250, v[60:63], s[40:41]
	s_nop 0
	v_add_u32_e32 v250, 0xb1600, v171
	global_store_dwordx4 v250, v[48:51], s[40:41]
	s_nop 0
	v_add_u32_e32 v250, 0xb2c00, v171
	global_store_dwordx4 v250, v[32:35], s[40:41]
	s_nop 0
	v_add_u32_e32 v250, 0xb4200, v171
	global_store_dwordx4 v250, v[16:19], s[40:41]
	s_nop 0
	s_andn2_b64 vcc, exec, s[6:7]
	s_mov_b64 s[4:5], -1
	s_cbranch_vccnz .LBB0_1748
	s_andn2_b64 vcc, exec, s[12:13]
	s_cbranch_vccnz .LBB0_1747
	s_barrier
	s_branch .LBB0_1747

.LBB0_1867:
	s_cmp_gt_i32 s72, 20
	s_cselect_b64 s[4:5], -1, 0
	s_cmp_lt_i32 s73, 21
	s_cselect_b64 s[6:7], -1, 0
	s_or_b64 s[4:5], s[4:5], s[6:7]
	s_and_b64 vcc, exec, s[4:5]
	s_cbranch_vccnz .LBB0_1934
	v_readlane_b32 s4, v255, 2
	v_mov_b32_e32 v9, v230
	v_readlane_b32 s5, v255, 3
	s_and_b64 vcc, exec, s[4:5]
	v_readfirstlane_b32 s5, v9
	s_cbranch_vccnz .LBB0_1884
	v_lshlrev_b32_e32 v0, 4, v9
	s_waitcnt lgkmcnt(0)
	v_add_u32_e32 v1, 0x2000, v0
	v_ashrrev_i32_e32 v2, 31, v1
	v_lshrrev_b32_e32 v2, 22, v2
	v_add_u32_e32 v2, v1, v2
	v_ashrrev_i32_e32 v8, 10, v2
	v_mul_i32_i24_e32 v2, 0x400, v8
	v_sub_u32_e32 v1, v1, v2
	v_lshrrev_b32_e32 v2, 4, v1
	v_bitop3_b32 v1, v2, v1, 32 bitop3:0x6c
	v_ashrrev_i32_e32 v2, 31, v1
	v_lshrrev_b32_e32 v2, 26, v2
	v_add_u32_e32 v2, v1, v2
	v_lshlrev_b32_e32 v3, 3, v8
	v_ashrrev_i32_e32 v10, 6, v2
	v_and_b32_e32 v3, -16, v3
	v_add_u32_e32 v3, v10, v3
	v_and_b32_e32 v4, 3, v10
	s_mov_b32 s4, 0x1fffe0
	v_lshrrev_b32_e32 v5, 2, v3
	v_lshlrev_b32_e32 v6, 1, v3
	v_and_b32_e32 v2, 0xc0, v2
	v_and_or_b32 v4, v3, s4, v4
	v_and_b32_e32 v5, 4, v5
	v_and_b32_e32 v6, 24, v6
	v_sub_u32_e32 v1, v1, v2
	v_mov_b32_e32 v2, 1
	v_or3_b32 v4, v4, v5, v6
	v_lshlrev_b32_e32 v5, 5, v8
	v_ashrrev_i16_sdwa v1, v2, sext(v1) dst_sel:DWORD dst_unused:UNUSED_PAD src0_sel:DWORD src1_sel:BYTE_0
	v_and_b32_e32 v5, 32, v5
	v_bfe_i32 v11, v1, 0, 16
	v_add_lshl_u32 v1, v5, v11, 1
	v_lshl_add_u32 v144, v4, 11, v1
	v_lshl_add_u32 v146, v3, 11, v1
	v_lshrrev_b32_e32 v248, 11, v146
	v_and_b32_e32 v249, 0x7ff, v146
	v_and_b32_e32 v250, 15, v248
	v_lshlrev_b32_e32 v250, 2, v250
	v_bfe_u32 v251, v248, 4, 2
	v_and_or_b32 v248, v248, 64, v250
	v_or_b32_e32 v248, v248, v251
	v_lshl_or_b32 v146, v248, 11, v249
	v_bfe_i32 v1, v9, 27, 1
	v_lshrrev_b32_e32 v1, 22, v1
	v_add_u32_e32 v1, v0, v1
	v_and_b32_e32 v1, 0xfffffc00, v1
	v_sub_u32_e32 v0, v0, v1
	v_lshrrev_b32_e32 v1, 4, v0
	v_ashrrev_i32_e32 v3, 31, v9
	v_bitop3_b32 v0, v1, v0, 32 bitop3:0x6c
	v_lshrrev_b32_e32 v3, 26, v3
	v_ashrrev_i32_e32 v1, 31, v0
	v_add_u32_e32 v3, v9, v3
	s_add_u32 s20, s70, 0x4b00000
	v_lshrrev_b32_e32 v1, 26, v1
	v_ashrrev_i32_e32 v13, 6, v3
	s_addc_u32 s21, s71, 0
	s_ashr_i32 s14, s5, 6
	v_add_u32_e32 v1, v0, v1
	v_lshlrev_b32_e32 v3, 3, v13
	v_readlane_b32 s6, v254, 62
	s_ashr_i32 s16, s5, 8
	s_lshl_b32 s38, s14, 10
	v_ashrrev_i32_e32 v12, 6, v1
	v_and_b32_e32 v3, -16, v3
	v_readlane_b32 s7, v254, 63
	v_add_u32_e32 v3, v12, v3
	v_and_b32_e32 v4, 3, v12
	s_movk_i32 s39, 0x59
	s_and_b64 s[6:7], s[6:7], exec
	v_and_or_b32 v4, v3, s4, v4
	s_cselect_b32 s4, s39, 0x58
	v_readlane_b32 s6, v254, 51
	s_mul_i32 s4, s4, s6
	v_readlane_b32 s6, v254, 61
	s_add_i32 s4, s4, s6
	s_mul_hi_i32 s6, s4, 0x2e8ba2e9
	s_lshr_b32 s7, s6, 31
	s_ashr_i32 s6, s6, 5
	s_add_i32 s6, s6, s7
	s_lshl_b32 s7, s6, 3
	s_mulk_i32 s6, 0xb0
	s_sub_i32 s6, s4, s6
	s_bfe_u32 s4, s6, 0x3001c
	s_add_i32 s8, s6, s4
	s_sext_i32_i16 s4, s8
	s_and_b32 s8, s8, 0xfff8
	s_sub_i32 s6, s6, s8
	s_sext_i32_i16 s6, s6
	v_lshrrev_b32_e32 v5, 2, v3
	v_lshlrev_b32_e32 v6, 1, v3
	v_and_b32_e32 v1, 0xc0, v1
	s_lshr_b32 s4, s4, 3
	s_add_i32 s6, s7, s6
	v_and_b32_e32 v5, 4, v5
	v_and_b32_e32 v6, 24, v6
	v_sub_u32_e32 v0, v0, v1
	s_ashr_i32 s7, s6, 31
	s_bfe_i64 s[10:11], s[4:5], 0x100000
	v_or3_b32 v4, v4, v5, v6
	v_lshlrev_b32_e32 v5, 5, v13
	v_ashrrev_i16_sdwa v0, v2, sext(v0) dst_sel:DWORD dst_unused:UNUSED_PAD src0_sel:DWORD src1_sel:BYTE_0
	s_lshl_b64 s[8:9], s[6:7], 19
	s_lshl_b64 s[10:11], s[10:11], 18
	v_and_b32_e32 v5, 32, v5
	v_bfe_i32 v14, v0, 0, 16
	s_add_u32 s34, s0, s10
	v_add_lshl_u32 v0, v5, v14, 1
	s_addc_u32 s35, s1, s11
	s_add_i32 s40, s38, 0
	v_lshl_add_u32 v148, v4, 11, v0
	s_add_i32 m0, s40, 0x10000
	v_lshl_add_u32 v150, v3, 11, v0
	v_lshrrev_b32_e32 v248, 11, v150
	v_and_b32_e32 v249, 0x7ff, v150
	v_and_b32_e32 v250, 15, v248
	v_lshlrev_b32_e32 v250, 2, v250
	v_bfe_u32 v251, v248, 4, 2
	v_and_or_b32 v248, v248, 64, v250
	v_or_b32_e32 v248, v248, v251
	v_lshl_or_b32 v150, v248, 11, v249
	global_load_lds_dwordx4 v148, s[34:35]
	s_add_i32 m0, s40, 0x12000
	s_add_u32 s10, s34, 0x580000
	global_load_lds_dwordx4 v144, s[34:35]
	s_addc_u32 s11, s35, 0
	s_add_i32 m0, s40, 0x14000
	v_mov_b32_e32 v149, 0
	global_load_lds_dwordx4 v148, s[10:11]
	s_add_i32 m0, s40, 0x16000
	s_add_u32 s30, s20, s8
	s_addc_u32 s31, s21, s9
	s_add_i32 s41, s40, 0x2000
	global_load_lds_dwordx4 v144, s[10:11]
	s_mov_b32 m0, s40
	s_add_u32 s8, s30, 0x40000
	global_load_lds_dwordx4 v150, s[30:31]
	s_mov_b32 m0, s41
	s_addc_u32 s9, s31, 0
	s_add_i32 s42, s40, 0x4000
	global_load_lds_dwordx4 v146, s[30:31]
	s_mov_b32 m0, s42
	s_add_i32 s43, s40, 0x6000
	global_load_lds_dwordx4 v150, s[8:9]
	s_mov_b32 m0, s43
	v_mov_b32_e32 v145, v149
	global_load_lds_dwordx4 v146, s[8:9]
	v_mov_b32_e32 v151, v149
	v_mov_b32_e32 v147, v149
	s_cmp_eq_u32 s16, 1
	s_mov_b32 s44, 0
	v_lshl_add_u64 v[6:7], s[34:35], 0, v[148:149]
	v_lshl_add_u64 v[4:5], s[34:35], 0, v[144:145]
	v_lshl_add_u64 v[0:1], s[30:31], 0, v[150:151]
	s_cselect_b64 s[8:9], -1, 0
	s_cmp_lg_u32 s16, 1
	v_lshl_add_u64 v[2:3], s[30:31], 0, v[146:147]
	s_cbranch_scc1 .LBB0_1871
	s_barrier
.LBB0_1871:
	s_add_u32 s10, s70, 0x128000
	s_addc_u32 s11, s71, 0
	s_add_u32 s12, s70, 0x3b00000
	s_addc_u32 s13, s71, 0
	s_lshl_b32 s7, s14, 5
	s_mov_b64 s[14:15], 0x80
	s_and_b32 s24, s7, 0x60
	s_add_i32 m0, s40, 0x18000
	v_lshl_add_u64 v[6:7], v[6:7], 0, s[14:15]
	s_lshl_b32 s17, s16, 13
	s_lshl_b32 s25, s24, 7
	s_waitcnt vmcnt(2)
	s_barrier
	global_load_lds_dwordx4 v[6:7], off
	v_lshl_add_u64 v[4:5], v[4:5], 0, s[14:15]
	s_add_i32 m0, s40, 0x1a000
	s_add_i32 s45, s40, 0x8000
	s_add_i32 s46, s40, 0xa000
	global_load_lds_dwordx4 v[4:5], off
	v_lshl_add_u64 v[0:1], v[0:1], 0, s[14:15]
	s_mov_b32 m0, s45
	s_add_u32 s22, s34, 0x580080
	global_load_lds_dwordx4 v[0:1], off
	v_lshl_add_u64 v[0:1], v[2:3], 0, s[14:15]
	s_mov_b32 m0, s46
	s_addc_u32 s23, s35, 0
	global_load_lds_dwordx4 v[0:1], off
	s_add_i32 m0, s40, 0x1c000
	v_lshl_add_u64 v[0:1], s[22:23], 0, v[148:149]
	global_load_lds_dwordx4 v[0:1], off
	v_lshl_add_u64 v[0:1], s[22:23], 0, v[144:145]
	s_add_i32 m0, s40, 0x1e000
	s_cmpk_lt_u32 s5, 0x100
	global_load_lds_dwordx4 v[0:1], off
	v_lshrrev_b32_e32 v1, 1, v9
	v_and_b32_e32 v1, 24, v1
	v_and_b32_e32 v0, 15, v9
	v_lshlrev_b32_e32 v2, 1, v1
	v_lshl_or_b32 v164, s16, 6, v0
	v_lshl_or_b32 v0, v0, 6, v2
	v_lshlrev_b32_e32 v2, 2, v9
	v_and_b32_e32 v2, 32, v2
	v_bitop3_b32 v3, v0, s17, v2 bitop3:0xde
	v_bitop3_b32 v165, v0, s25, v2 bitop3:0xde
	v_lshlrev_b32_e32 v0, 14, v13
	v_and_b32_e32 v0, 0xffff8000, v0
	v_or_b32_e32 v166, s24, v1
	v_lshl_add_u32 v0, v12, 11, v0
	v_and_b32_e32 v1, 1, v13
	v_lshl_or_b32 v0, v1, 6, v0
	v_lshl_add_u32 v152, v14, 1, v0
	v_lshrrev_b32_e32 v248, 11, v152
	v_and_b32_e32 v249, 0x7ff, v152
	v_and_b32_e32 v250, 15, v248
	v_lshlrev_b32_e32 v250, 2, v250
	v_bfe_u32 v251, v248, 4, 2
	v_and_or_b32 v248, v248, 64, v250
	v_or_b32_e32 v248, v248, v251
	v_lshl_or_b32 v152, v248, 11, v249
	v_lshlrev_b32_e32 v0, 14, v8
	v_and_b32_e32 v0, 0xffff8000, v0
	s_waitcnt vmcnt(6)
	v_lshl_add_u32 v0, v10, 11, v0
	v_and_b32_e32 v1, 1, v8
	s_cselect_b64 s[16:17], -1, 0
	v_lshl_or_b32 v0, v1, 6, v0
	s_add_i32 s47, 0, 0x10000
	s_add_i32 s48, 0, 0x14000
	s_sext_i32_i16 s7, s4
	v_mov_b32_e32 v153, v149
	v_lshl_add_u32 v154, v11, 1, v0
	v_lshrrev_b32_e32 v248, 11, v154
	v_and_b32_e32 v249, 0x7ff, v154
	v_and_b32_e32 v250, 15, v248
	v_lshlrev_b32_e32 v250, 2, v250
	v_bfe_u32 v251, v248, 4, 2
	v_and_or_b32 v248, v248, 64, v250
	v_or_b32_e32 v248, v248, v251
	v_lshl_or_b32 v154, v248, 11, v249
	v_mov_b32_e32 v155, v149
	v_mov_b64_e32 v[156:157], 0x2c0
	v_mov_b64_e32 v[158:159], 0x2bf
	v_add_u32_e32 v167, s47, v165
	v_add_u32_e32 v168, s48, v165
	v_add_u32_e32 v169, 0, v3
	v_mov_b32_e32 v170, 0x358637bd
	s_mov_b32 s49, 0x800000
	s_movk_i32 s51, 0x2c00
	s_barrier
	s_branch .LBB0_1874

.LBB0_1880:
	s_and_b32 s23, s8, 1
	s_add_i32 s30, s6, 0
	s_ashr_i32 s30, s30, 2
	s_add_i32 s30, s30, 1
	s_cmp_gt_i32 s6, -1
	s_cselect_b32 s30, s30, 0
	s_mul_hi_i32 s31, s30, 0x5800
	s_mulk_i32 s30, 0x5800
	s_add_u32 s30, s33, s30
	s_addc_u32 s31, s50, s31
	v_and_b32_e32 v237, 15, v164
	v_and_b32_e32 v236, 64, v164
	v_lshl_add_u32 v236, v237, 2, v236
	v_mul_u32_u24_e32 v171, 0x1600, v236
	v_lshl_add_u32 v171, v166, 1, v171
	v_lshl_add_u32 v236, s6, 8, v236
	v_lshlrev_b32_e32 v236, 2, v236
	v_lshl_or_b32 v229, s7, 7, v166
	v_lshlrev_b32_e32 v229, 2, v229
	global_load_dwordx4 v[208:211], v236, s[10:11]
	global_load_dwordx4 v[212:215], v236, s[10:11] offset:512
	global_load_dwordx4 v[200:203], v229, s[30:31]
	global_load_dwordx4 v[204:207], v229, s[30:31] offset:16
	v_add_u32_e32 v224, 0x2c00, v229
	global_load_dwordx4 v[216:219], v224, s[30:31]
	global_load_dwordx4 v[220:223], v224, s[30:31] offset:16
	v_readlane_b32 s34, v254, 5
	v_readlane_b32 s35, v254, 6
	v_readlane_b32 s36, v254, 7
	v_readlane_b32 s37, v254, 8
	s_add_u32 s34, s34, 0x10800
	s_addc_u32 s35, s35, 0
	s_add_u32 s36, s36, 0x5800
	s_addc_u32 s37, s37, 0
	s_mul_i32 s52, s6, 0x160000
	s_lshl_b32 s79, s7, 8
	s_add_i32 s52, s52, s79
	s_add_i32 s52, s52, 0xbf00000
	s_add_u32 s52, s52, s70
	s_addc_u32 s53, s71, 0
	s_mov_b32 s32, 0x20800
	v_lshl_add_u32 v228, v166, 2, s32
	v_cmp_eq_u32_e64 s[54:55], 0, v237
	v_cmp_eq_u32_e64 s[56:57], 15, v237
	v_and_b32_e32 v231, 8, v237
	v_lshlrev_b32_e32 v231, 9, v231
	s_lshl_b32 s79, s23, 10
	v_add3_u32 v231, v231, v228, s79
	global_load_dwordx4 v[128:131], v229, s[34:35]
	v_add_u32_e32 v227, 0x5800, v229
	global_load_dwordx4 v[132:135], v227, s[34:35]
	v_add_u32_e32 v226, 0xb000, v229
	global_load_dwordx4 v[136:139], v226, s[34:35]
	global_load_dwordx4 v[140:143], v229, s[36:37]
	v_add_u32_e32 v226, 0x2c00, v229
	global_load_dwordx4 v[160:163], v226, s[34:35]
	v_add_u32_e32 v227, 0x8400, v229
	global_load_dwordx4 v[172:175], v227, s[34:35]
	v_add_u32_e32 v226, 0xdc00, v229
	global_load_dwordx4 v[176:179], v226, s[34:35]
	v_add_u32_e32 v227, 0x2c00, v229
	global_load_dwordx4 v[180:183], v227, s[36:37]
	s_waitcnt vmcnt(12)
	v_fmamk_f32 v208, v208, 0x3a800000, v170
	v_fmamk_f32 v209, v209, 0x3a800000, v170
	v_fmamk_f32 v210, v210, 0x3a800000, v170
	v_fmamk_f32 v211, v211, 0x3a800000, v170
	v_fmamk_f32 v212, v212, 0x3a800000, v170
	v_fmamk_f32 v213, v213, 0x3a800000, v170
	v_fmamk_f32 v214, v214, 0x3a800000, v170
	v_fmamk_f32 v215, v215, 0x3a800000, v170
	s_mov_b32 s79, 0x800000
	v_mul_f32_e32 v224, 0x4b800000, v208
	v_mul_f32_e32 v225, 0x4b800000, v209
	v_mul_f32_e32 v226, 0x4b800000, v210
	v_mul_f32_e32 v227, 0x4b800000, v211
	v_mul_f32_e32 v232, 0x4b800000, v212
	v_mul_f32_e32 v233, 0x4b800000, v213
	v_mul_f32_e32 v234, 0x4b800000, v214
	v_mul_f32_e32 v235, 0x4b800000, v215
	v_cmp_gt_f32_e32 vcc, s79, v208
	s_nop 1
	v_cndmask_b32_e32 v208, v208, v224, vcc
	v_rsq_f32_e32 v208, v208
	s_nop 0
	v_mul_f32_e32 v224, 0x45800000, v208
	v_cndmask_b32_e32 v208, v208, v224, vcc
	v_cmp_gt_f32_e32 vcc, s79, v209
	s_nop 1
	v_cndmask_b32_e32 v209, v209, v225, vcc
	v_rsq_f32_e32 v209, v209
	s_nop 0
	v_mul_f32_e32 v225, 0x45800000, v209
	v_cndmask_b32_e32 v209, v209, v225, vcc
	v_cmp_gt_f32_e32 vcc, s79, v210
	s_nop 1
	v_cndmask_b32_e32 v210, v210, v226, vcc
	v_rsq_f32_e32 v210, v210
	s_nop 0
	v_mul_f32_e32 v226, 0x45800000, v210
	v_cndmask_b32_e32 v210, v210, v226, vcc
	v_cmp_gt_f32_e32 vcc, s79, v211
	s_nop 1
	v_cndmask_b32_e32 v211, v211, v227, vcc
	v_rsq_f32_e32 v211, v211
	s_nop 0
	v_mul_f32_e32 v227, 0x45800000, v211
	v_cndmask_b32_e32 v211, v211, v227, vcc
	v_cmp_gt_f32_e32 vcc, s79, v212
	s_nop 1
	v_cndmask_b32_e32 v212, v212, v232, vcc
	v_rsq_f32_e32 v212, v212
	s_nop 0
	v_mul_f32_e32 v232, 0x45800000, v212
	v_cndmask_b32_e32 v212, v212, v232, vcc
	v_cmp_gt_f32_e32 vcc, s79, v213
	s_nop 1
	v_cndmask_b32_e32 v213, v213, v233, vcc
	v_rsq_f32_e32 v213, v213
	s_nop 0
	v_mul_f32_e32 v233, 0x45800000, v213
	v_cndmask_b32_e32 v213, v213, v233, vcc
	v_cmp_gt_f32_e32 vcc, s79, v214
	s_nop 1
	v_cndmask_b32_e32 v214, v214, v234, vcc
	v_rsq_f32_e32 v214, v214
	s_nop 0
	v_mul_f32_e32 v234, 0x45800000, v214
	v_cndmask_b32_e32 v214, v214, v234, vcc
	v_cmp_gt_f32_e32 vcc, s79, v215
	s_nop 1
	v_cndmask_b32_e32 v215, v215, v235, vcc
	v_rsq_f32_e32 v215, v215
	s_nop 0
	v_mul_f32_e32 v235, 0x45800000, v215
	v_cndmask_b32_e32 v215, v215, v235, vcc
	s_waitcnt vmcnt(8)
	v_fma_f32 v124, v124, v208, v200
	v_fma_f32 v125, v125, v208, v201
	v_fma_f32 v126, v126, v208, v202
	v_fma_f32 v127, v127, v208, v203
	v_fma_f32 v120, v120, v208, v204
	v_fma_f32 v121, v121, v208, v205
	v_fma_f32 v122, v122, v208, v206
	v_fma_f32 v123, v123, v208, v207
	v_fma_f32 v108, v108, v208, v216
	v_fma_f32 v109, v109, v208, v217
	v_fma_f32 v110, v110, v208, v218
	v_fma_f32 v111, v111, v208, v219
	v_fma_f32 v104, v104, v208, v220
	v_fma_f32 v105, v105, v208, v221
	v_fma_f32 v106, v106, v208, v222
	v_fma_f32 v107, v107, v208, v223
	v_fma_f32 v116, v116, v209, v200
	v_fma_f32 v117, v117, v209, v201
	v_fma_f32 v118, v118, v209, v202
	v_fma_f32 v119, v119, v209, v203
	v_fma_f32 v112, v112, v209, v204
	v_fma_f32 v113, v113, v209, v205
	v_fma_f32 v114, v114, v209, v206
	v_fma_f32 v115, v115, v209, v207
	v_fma_f32 v100, v100, v209, v216
	v_fma_f32 v101, v101, v209, v217
	v_fma_f32 v102, v102, v209, v218
	v_fma_f32 v103, v103, v209, v219
	v_fma_f32 v92, v92, v209, v220
	v_fma_f32 v93, v93, v209, v221
	v_fma_f32 v94, v94, v209, v222
	v_fma_f32 v95, v95, v209, v223
	v_fma_f32 v96, v96, v210, v200
	v_fma_f32 v97, v97, v210, v201
	v_fma_f32 v98, v98, v210, v202
	v_fma_f32 v99, v99, v210, v203
	v_fma_f32 v88, v88, v210, v204
	v_fma_f32 v89, v89, v210, v205
	v_fma_f32 v90, v90, v210, v206
	v_fma_f32 v91, v91, v210, v207
	v_fma_f32 v84, v84, v210, v216
	v_fma_f32 v85, v85, v210, v217
	v_fma_f32 v86, v86, v210, v218
	v_fma_f32 v87, v87, v210, v219
	v_fma_f32 v76, v76, v210, v220
	v_fma_f32 v77, v77, v210, v221
	v_fma_f32 v78, v78, v210, v222
	v_fma_f32 v79, v79, v210, v223
	v_fma_f32 v80, v80, v211, v200
	v_fma_f32 v81, v81, v211, v201
	v_fma_f32 v82, v82, v211, v202
	v_fma_f32 v83, v83, v211, v203
	v_fma_f32 v72, v72, v211, v204
	v_fma_f32 v73, v73, v211, v205
	v_fma_f32 v74, v74, v211, v206
	v_fma_f32 v75, v75, v211, v207
	v_fma_f32 v68, v68, v211, v216
	v_fma_f32 v69, v69, v211, v217
	v_fma_f32 v70, v70, v211, v218
	v_fma_f32 v71, v71, v211, v219
	v_fma_f32 v64, v64, v211, v220
	v_fma_f32 v65, v65, v211, v221
	v_fma_f32 v66, v66, v211, v222
	v_fma_f32 v67, v67, v211, v223
	v_fma_f32 v60, v60, v212, v200
	v_fma_f32 v61, v61, v212, v201
	v_fma_f32 v62, v62, v212, v202
	v_fma_f32 v63, v63, v212, v203
	v_fma_f32 v56, v56, v212, v204
	v_fma_f32 v57, v57, v212, v205
	v_fma_f32 v58, v58, v212, v206
	v_fma_f32 v59, v59, v212, v207
	v_fma_f32 v52, v52, v212, v216
	v_fma_f32 v53, v53, v212, v217
	v_fma_f32 v54, v54, v212, v218
	v_fma_f32 v55, v55, v212, v219
	v_fma_f32 v44, v44, v212, v220
	v_fma_f32 v45, v45, v212, v221
	v_fma_f32 v46, v46, v212, v222
	v_fma_f32 v47, v47, v212, v223
	v_fma_f32 v48, v48, v213, v200
	v_fma_f32 v49, v49, v213, v201
	v_fma_f32 v50, v50, v213, v202
	v_fma_f32 v51, v51, v213, v203
	v_fma_f32 v40, v40, v213, v204
	v_fma_f32 v41, v41, v213, v205
	v_fma_f32 v42, v42, v213, v206
	v_fma_f32 v43, v43, v213, v207
	v_fma_f32 v36, v36, v213, v216
	v_fma_f32 v37, v37, v213, v217
	v_fma_f32 v38, v38, v213, v218
	v_fma_f32 v39, v39, v213, v219
	v_fma_f32 v28, v28, v213, v220
	v_fma_f32 v29, v29, v213, v221
	v_fma_f32 v30, v30, v213, v222
	v_fma_f32 v31, v31, v213, v223
	v_fma_f32 v32, v32, v214, v200
	v_fma_f32 v33, v33, v214, v201
	v_fma_f32 v34, v34, v214, v202
	v_fma_f32 v35, v35, v214, v203
	v_fma_f32 v24, v24, v214, v204
	v_fma_f32 v25, v25, v214, v205
	v_fma_f32 v26, v26, v214, v206
	v_fma_f32 v27, v27, v214, v207
	v_fma_f32 v20, v20, v214, v216
	v_fma_f32 v21, v21, v214, v217
	v_fma_f32 v22, v22, v214, v218
	v_fma_f32 v23, v23, v214, v219
	v_fma_f32 v12, v12, v214, v220
	v_fma_f32 v13, v13, v214, v221
	v_fma_f32 v14, v14, v214, v222
	v_fma_f32 v15, v15, v214, v223
	v_fma_f32 v16, v16, v215, v200
	v_fma_f32 v17, v17, v215, v201
	v_fma_f32 v18, v18, v215, v202
	v_fma_f32 v19, v19, v215, v203
	v_fma_f32 v8, v8, v215, v204
	v_fma_f32 v9, v9, v215, v205
	v_fma_f32 v10, v10, v215, v206
	v_fma_f32 v11, v11, v215, v207
	v_fma_f32 v4, v4, v215, v216
	v_fma_f32 v5, v5, v215, v217
	v_fma_f32 v6, v6, v215, v218
	v_fma_f32 v7, v7, v215, v219
	v_fma_f32 v0, v0, v215, v220
	v_fma_f32 v1, v1, v215, v221
	v_fma_f32 v2, v2, v215, v222
	v_fma_f32 v3, v3, v215, v223
	v_mov_b32_e32 v212, 0
	v_mov_b32_e32 v213, 0
	v_mov_b32_e32 v214, 0
	v_mov_b32_e32 v215, 0
	s_lshl_b32 s96, s23, 12
	s_sub_i32 s96, 0x2000, s96
	s_mul_i32 s94, s23, 0x1400
	s_add_i32 s94, s94, 0xc00
	s_lshl_b32 s79, s23, 10
	s_add_i32 s95, s79, 5120
	s_add_i32 s92, s79, 1024
	s_mov_b64 s[58:59], exec
	s_mov_b64 exec, s[54:55]
	v_add_u32_e32 v250, s96, v228
	ds_write_b128 v250, v[124:127] offset:0
	ds_write_b128 v250, v[120:123] offset:16
	ds_write_b128 v250, v[108:111] offset:512
	ds_write_b128 v250, v[104:107] offset:528
	v_add_u32_e32 v250, s95, v228
	ds_write_b128 v250, v[60:63] offset:0
	ds_write_b128 v250, v[56:59] offset:16
	ds_write_b128 v250, v[52:55] offset:512
	ds_write_b128 v250, v[44:47] offset:528
	ds_write_b128 v228, v[212:215] offset:0
	ds_write_b128 v228, v[212:215] offset:16
	ds_write_b128 v228, v[212:215] offset:512
	ds_write_b128 v228, v[212:215] offset:528
	s_mov_b64 exec, s[56:57]
	v_add_u32_e32 v251, s92, v228
	ds_write_b128 v251, v[80:83] offset:0
	ds_write_b128 v251, v[72:75] offset:16
	ds_write_b128 v251, v[68:71] offset:512
	ds_write_b128 v251, v[64:67] offset:528
	v_add_u32_e32 v251, s94, v228
	ds_write_b128 v251, v[16:19] offset:0
	ds_write_b128 v251, v[8:11] offset:16
	ds_write_b128 v251, v[4:7] offset:512
	ds_write_b128 v251, v[0:3] offset:528
	ds_write_b128 v228, v[212:215] offset:7168
	ds_write_b128 v228, v[212:215] offset:7184
	ds_write_b128 v228, v[212:215] offset:7680
	ds_write_b128 v228, v[212:215] offset:7696
	s_mov_b64 exec, s[58:59]
	s_cmp_eq_u32 s23, 0
	s_cselect_b64 s[60:61], s[54:55], 0
	s_cselect_b64 s[62:63], 0, s[56:57]
	s_mul_i32 s64, s6, 0x16000
	s_add_u32 s64, s64, 0x5b00000
	s_add_u32 s64, s64, s70
	s_addc_u32 s65, s71, 0
	s_mov_b64 exec, s[60:61]
	global_store_dwordx4 v229, v[124:127], s[64:65]
	global_store_dwordx4 v229, v[120:123], s[64:65] offset:16
	v_add_u32_e32 v250, 0x2c00, v229
	global_store_dwordx4 v250, v[108:111], s[64:65]
	global_store_dwordx4 v250, v[104:107], s[64:65] offset:16
	s_mov_b64 exec, s[62:63]
	v_add_u32_e32 v250, 0xb000, v229
	global_store_dwordx4 v250, v[16:19], s[64:65]
	global_store_dwordx4 v250, v[8:11], s[64:65] offset:16
	v_add_u32_e32 v250, 0xdc00, v229
	global_store_dwordx4 v250, v[4:7], s[64:65]
	global_store_dwordx4 v250, v[0:3], s[64:65] offset:16
	s_mov_b64 exec, s[58:59]
	s_waitcnt lgkmcnt(0)
	s_barrier
	ds_read_b128 v[184:187], v231 offset:0
	ds_read_b128 v[188:191], v231 offset:512
	ds_read_b128 v[192:195], v231 offset:2048
	ds_read_b128 v[196:199], v231 offset:2560
	s_waitcnt vmcnt(0)
	v_cndmask_b32_e64 v216, 0, v128, s[54:55]
	v_cndmask_b32_e64 v220, 0, v136, s[56:57]
	v_cndmask_b32_e64 v217, 0, v129, s[54:55]
	v_cndmask_b32_e64 v221, 0, v137, s[56:57]
	v_cndmask_b32_e64 v218, 0, v130, s[54:55]
	v_cndmask_b32_e64 v222, 0, v138, s[56:57]
	v_cndmask_b32_e64 v219, 0, v131, s[54:55]
	v_cndmask_b32_e64 v223, 0, v139, s[56:57]
	v_cndmask_b32_e64 v224, 0, v160, s[54:55]
	v_cndmask_b32_e64 v232, 0, v176, s[56:57]
	v_cndmask_b32_e64 v225, 0, v161, s[54:55]
	v_cndmask_b32_e64 v233, 0, v177, s[56:57]
	v_cndmask_b32_e64 v226, 0, v162, s[54:55]
	v_cndmask_b32_e64 v234, 0, v178, s[56:57]
	v_cndmask_b32_e64 v227, 0, v163, s[54:55]
	v_cndmask_b32_e64 v235, 0, v179, s[56:57]
	s_waitcnt lgkmcnt(0)
	s_nop 1
	v_fma_f32 v200, v132, v124, v140
	v_fma_f32 v201, v133, v125, v141
	v_fma_f32 v202, v134, v126, v142
	v_fma_f32 v203, v135, v127, v143
	v_fmac_f32_dpp v200, v80, v128 row_shr:1 row_mask:0xf bank_mask:0xf
	v_fmac_f32_dpp v201, v81, v129 row_shr:1 row_mask:0xf bank_mask:0xf
	v_fmac_f32_dpp v202, v82, v130 row_shr:1 row_mask:0xf bank_mask:0xf
	v_fmac_f32_dpp v203, v83, v131 row_shr:1 row_mask:0xf bank_mask:0xf
	v_fmac_f32_e32 v200, v184, v216
	v_fmac_f32_e32 v201, v185, v217
	v_fmac_f32_e32 v202, v186, v218
	v_fmac_f32_e32 v203, v187, v219
	v_fmac_f32_e32 v200, v116, v136
	v_fmac_f32_e32 v201, v117, v137
	v_fmac_f32_e32 v202, v118, v138
	v_fmac_f32_e32 v203, v119, v139
	v_fma_f32 v204, v172, v108, v180
	v_fma_f32 v205, v173, v109, v181
	v_fma_f32 v206, v174, v110, v182
	v_fma_f32 v207, v175, v111, v183
	v_fmac_f32_dpp v204, v68, v160 row_shr:1 row_mask:0xf bank_mask:0xf
	v_fmac_f32_dpp v205, v69, v161 row_shr:1 row_mask:0xf bank_mask:0xf
	v_fmac_f32_dpp v206, v70, v162 row_shr:1 row_mask:0xf bank_mask:0xf
	v_fmac_f32_dpp v207, v71, v163 row_shr:1 row_mask:0xf bank_mask:0xf
	v_fmac_f32_e32 v204, v188, v224
	v_fmac_f32_e32 v205, v189, v225
	v_fmac_f32_e32 v206, v190, v226
	v_fmac_f32_e32 v207, v191, v227
	v_fmac_f32_e32 v204, v100, v176
	v_fmac_f32_e32 v205, v101, v177
	v_fmac_f32_e32 v206, v102, v178
	v_fmac_f32_e32 v207, v103, v179
	s_mov_b64 exec, s[60:61]
	v_add_u32_e32 v250, 0x5800, v229
	global_store_dwordx4 v250, v[200:203], s[64:65]
	v_add_u32_e32 v250, 0x8400, v229
	global_store_dwordx4 v250, v[204:207], s[64:65]
	s_mov_b64 exec, s[58:59]
	s_nop 4
	v_mul_f32_e32 v208, 0xbfb8aa3b, v200
	v_mul_f32_e32 v209, 0xbfb8aa3b, v201
	v_mul_f32_e32 v210, 0xbfb8aa3b, v202
	v_mul_f32_e32 v211, 0xbfb8aa3b, v203
	v_exp_f32_e32 v208, v208
	v_exp_f32_e32 v209, v209
	v_exp_f32_e32 v210, v210
	v_exp_f32_e32 v211, v211
	v_add_f32_e32 v208, 1.0, v208
	v_add_f32_e32 v209, 1.0, v209
	v_add_f32_e32 v210, 1.0, v210
	v_add_f32_e32 v211, 1.0, v211
	v_rcp_f32_e32 v208, v208
	v_rcp_f32_e32 v209, v209
	v_rcp_f32_e32 v210, v210
	v_rcp_f32_e32 v211, v211
	v_mul_f32_e32 v200, v200, v208
	v_mul_f32_e32 v201, v201, v209
	v_mul_f32_e32 v202, v202, v210
	v_mul_f32_e32 v203, v203, v211
	v_mul_f32_e32 v200, v200, v204
	v_mul_f32_e32 v201, v201, v205
	v_mul_f32_e32 v202, v202, v206
	v_mul_f32_e32 v203, v203, v207
	v_cvt_pk_bf16_f32 v236, v200, v201
	v_cvt_pk_bf16_f32 v237, v202, v203
	v_fma_f32 v200, v132, v116, v140
	v_fma_f32 v201, v133, v117, v141
	v_fma_f32 v202, v134, v118, v142
	v_fma_f32 v203, v135, v119, v143
	v_fmac_f32_e32 v200, v124, v128
	v_fmac_f32_e32 v201, v125, v129
	v_fmac_f32_e32 v202, v126, v130
	v_fmac_f32_e32 v203, v127, v131
	v_fmac_f32_e32 v200, v96, v136
	v_fmac_f32_e32 v201, v97, v137
	v_fmac_f32_e32 v202, v98, v138
	v_fmac_f32_e32 v203, v99, v139
	v_fma_f32 v204, v172, v100, v180
	v_fma_f32 v205, v173, v101, v181
	v_fma_f32 v206, v174, v102, v182
	v_fma_f32 v207, v175, v103, v183
	v_fmac_f32_e32 v204, v108, v160
	v_fmac_f32_e32 v205, v109, v161
	v_fmac_f32_e32 v206, v110, v162
	v_fmac_f32_e32 v207, v111, v163
	v_fmac_f32_e32 v204, v84, v176
	v_fmac_f32_e32 v205, v85, v177
	v_fmac_f32_e32 v206, v86, v178
	v_fmac_f32_e32 v207, v87, v179
	v_mul_f32_e32 v208, 0xbfb8aa3b, v200
	v_mul_f32_e32 v209, 0xbfb8aa3b, v201
	v_mul_f32_e32 v210, 0xbfb8aa3b, v202
	v_mul_f32_e32 v211, 0xbfb8aa3b, v203
	v_exp_f32_e32 v208, v208
	v_exp_f32_e32 v209, v209
	v_exp_f32_e32 v210, v210
	v_exp_f32_e32 v211, v211
	v_add_f32_e32 v208, 1.0, v208
	v_add_f32_e32 v209, 1.0, v209
	v_add_f32_e32 v210, 1.0, v210
	v_add_f32_e32 v211, 1.0, v211
	v_rcp_f32_e32 v208, v208
	v_rcp_f32_e32 v209, v209
	v_rcp_f32_e32 v210, v210
	v_rcp_f32_e32 v211, v211
	v_mul_f32_e32 v200, v200, v208
	v_mul_f32_e32 v201, v201, v209
	v_mul_f32_e32 v202, v202, v210
	v_mul_f32_e32 v203, v203, v211
	v_mul_f32_e32 v200, v200, v204
	v_mul_f32_e32 v201, v201, v205
	v_mul_f32_e32 v202, v202, v206
	v_mul_f32_e32 v203, v203, v207
	v_cvt_pk_bf16_f32 v238, v200, v201
	v_cvt_pk_bf16_f32 v239, v202, v203
	v_fma_f32 v200, v132, v96, v140
	v_fma_f32 v201, v133, v97, v141
	v_fma_f32 v202, v134, v98, v142
	v_fma_f32 v203, v135, v99, v143
	v_fmac_f32_e32 v200, v116, v128
	v_fmac_f32_e32 v201, v117, v129
	v_fmac_f32_e32 v202, v118, v130
	v_fmac_f32_e32 v203, v119, v131
	v_fmac_f32_e32 v200, v80, v136
	v_fmac_f32_e32 v201, v81, v137
	v_fmac_f32_e32 v202, v82, v138
	v_fmac_f32_e32 v203, v83, v139
	v_fma_f32 v204, v172, v84, v180
	v_fma_f32 v205, v173, v85, v181
	v_fma_f32 v206, v174, v86, v182
	v_fma_f32 v207, v175, v87, v183
	v_fmac_f32_e32 v204, v100, v160
	v_fmac_f32_e32 v205, v101, v161
	v_fmac_f32_e32 v206, v102, v162
	v_fmac_f32_e32 v207, v103, v163
	v_fmac_f32_e32 v204, v68, v176
	v_fmac_f32_e32 v205, v69, v177
	v_fmac_f32_e32 v206, v70, v178
	v_fmac_f32_e32 v207, v71, v179
	v_mul_f32_e32 v208, 0xbfb8aa3b, v200
	v_mul_f32_e32 v209, 0xbfb8aa3b, v201
	v_mul_f32_e32 v210, 0xbfb8aa3b, v202
	v_mul_f32_e32 v211, 0xbfb8aa3b, v203
	v_exp_f32_e32 v208, v208
	v_exp_f32_e32 v209, v209
	v_exp_f32_e32 v210, v210
	v_exp_f32_e32 v211, v211
	v_add_f32_e32 v208, 1.0, v208
	v_add_f32_e32 v209, 1.0, v209
	v_add_f32_e32 v210, 1.0, v210
	v_add_f32_e32 v211, 1.0, v211
	v_rcp_f32_e32 v208, v208
	v_rcp_f32_e32 v209, v209
	v_rcp_f32_e32 v210, v210
	v_rcp_f32_e32 v211, v211
	v_mul_f32_e32 v200, v200, v208
	v_mul_f32_e32 v201, v201, v209
	v_mul_f32_e32 v202, v202, v210
	v_mul_f32_e32 v203, v203, v211
	v_mul_f32_e32 v200, v200, v204
	v_mul_f32_e32 v201, v201, v205
	v_mul_f32_e32 v202, v202, v206
	v_mul_f32_e32 v203, v203, v207
	v_cvt_pk_bf16_f32 v240, v200, v201
	v_cvt_pk_bf16_f32 v241, v202, v203
	v_fma_f32 v200, v132, v80, v140
	v_fma_f32 v201, v133, v81, v141
	v_fma_f32 v202, v134, v82, v142
	v_fma_f32 v203, v135, v83, v143
	v_fmac_f32_e32 v200, v96, v128
	v_fmac_f32_e32 v201, v97, v129
	v_fmac_f32_e32 v202, v98, v130
	v_fmac_f32_e32 v203, v99, v131
	v_fmac_f32_dpp v200, v124, v136 row_shl:1 row_mask:0xf bank_mask:0xf
	v_fmac_f32_dpp v201, v125, v137 row_shl:1 row_mask:0xf bank_mask:0xf
	v_fmac_f32_dpp v202, v126, v138 row_shl:1 row_mask:0xf bank_mask:0xf
	v_fmac_f32_dpp v203, v127, v139 row_shl:1 row_mask:0xf bank_mask:0xf
	v_fmac_f32_e32 v200, v184, v220
	v_fmac_f32_e32 v201, v185, v221
	v_fmac_f32_e32 v202, v186, v222
	v_fmac_f32_e32 v203, v187, v223
	v_fma_f32 v204, v172, v68, v180
	v_fma_f32 v205, v173, v69, v181
	v_fma_f32 v206, v174, v70, v182
	v_fma_f32 v207, v175, v71, v183
	v_fmac_f32_e32 v204, v84, v160
	v_fmac_f32_e32 v205, v85, v161
	v_fmac_f32_e32 v206, v86, v162
	v_fmac_f32_e32 v207, v87, v163
	v_fmac_f32_dpp v204, v108, v176 row_shl:1 row_mask:0xf bank_mask:0xf
	v_fmac_f32_dpp v205, v109, v177 row_shl:1 row_mask:0xf bank_mask:0xf
	v_fmac_f32_dpp v206, v110, v178 row_shl:1 row_mask:0xf bank_mask:0xf
	v_fmac_f32_dpp v207, v111, v179 row_shl:1 row_mask:0xf bank_mask:0xf
	v_fmac_f32_e32 v204, v188, v232
	v_fmac_f32_e32 v205, v189, v233
	v_fmac_f32_e32 v206, v190, v234
	v_fmac_f32_e32 v207, v191, v235
	v_mul_f32_e32 v208, 0xbfb8aa3b, v200
	v_mul_f32_e32 v209, 0xbfb8aa3b, v201
	v_mul_f32_e32 v210, 0xbfb8aa3b, v202
	v_mul_f32_e32 v211, 0xbfb8aa3b, v203
	v_exp_f32_e32 v208, v208
	v_exp_f32_e32 v209, v209
	v_exp_f32_e32 v210, v210
	v_exp_f32_e32 v211, v211
	v_add_f32_e32 v208, 1.0, v208
	v_add_f32_e32 v209, 1.0, v209
	v_add_f32_e32 v210, 1.0, v210
	v_add_f32_e32 v211, 1.0, v211
	v_rcp_f32_e32 v208, v208
	v_rcp_f32_e32 v209, v209
	v_rcp_f32_e32 v210, v210
	v_rcp_f32_e32 v211, v211
	v_mul_f32_e32 v200, v200, v208
	v_mul_f32_e32 v201, v201, v209
	v_mul_f32_e32 v202, v202, v210
	v_mul_f32_e32 v203, v203, v211
	v_mul_f32_e32 v200, v200, v204
	v_mul_f32_e32 v201, v201, v205
	v_mul_f32_e32 v202, v202, v206
	v_mul_f32_e32 v203, v203, v207
	v_cvt_pk_bf16_f32 v242, v200, v201
	v_cvt_pk_bf16_f32 v243, v202, v203
	v_fma_f32 v200, v132, v60, v140
	v_fma_f32 v201, v133, v61, v141
	v_fma_f32 v202, v134, v62, v142
	v_fma_f32 v203, v135, v63, v143
	v_fmac_f32_dpp v200, v16, v128 row_shr:1 row_mask:0xf bank_mask:0xf
	v_fmac_f32_dpp v201, v17, v129 row_shr:1 row_mask:0xf bank_mask:0xf
	v_fmac_f32_dpp v202, v18, v130 row_shr:1 row_mask:0xf bank_mask:0xf
	v_fmac_f32_dpp v203, v19, v131 row_shr:1 row_mask:0xf bank_mask:0xf
	v_fmac_f32_e32 v200, v192, v216
	v_fmac_f32_e32 v201, v193, v217
	v_fmac_f32_e32 v202, v194, v218
	v_fmac_f32_e32 v203, v195, v219
	v_fmac_f32_e32 v200, v48, v136
	v_fmac_f32_e32 v201, v49, v137
	v_fmac_f32_e32 v202, v50, v138
	v_fmac_f32_e32 v203, v51, v139
	v_fma_f32 v204, v172, v52, v180
	v_fma_f32 v205, v173, v53, v181
	v_fma_f32 v206, v174, v54, v182
	v_fma_f32 v207, v175, v55, v183
	v_fmac_f32_dpp v204, v4, v160 row_shr:1 row_mask:0xf bank_mask:0xf
	v_fmac_f32_dpp v205, v5, v161 row_shr:1 row_mask:0xf bank_mask:0xf
	v_fmac_f32_dpp v206, v6, v162 row_shr:1 row_mask:0xf bank_mask:0xf
	v_fmac_f32_dpp v207, v7, v163 row_shr:1 row_mask:0xf bank_mask:0xf
	v_fmac_f32_e32 v204, v196, v224
	v_fmac_f32_e32 v205, v197, v225
	v_fmac_f32_e32 v206, v198, v226
	v_fmac_f32_e32 v207, v199, v227
	v_fmac_f32_e32 v204, v36, v176
	v_fmac_f32_e32 v205, v37, v177
	v_fmac_f32_e32 v206, v38, v178
	v_fmac_f32_e32 v207, v39, v179
	v_mul_f32_e32 v208, 0xbfb8aa3b, v200
	v_mul_f32_e32 v209, 0xbfb8aa3b, v201
	v_mul_f32_e32 v210, 0xbfb8aa3b, v202
	v_mul_f32_e32 v211, 0xbfb8aa3b, v203
	v_exp_f32_e32 v208, v208
	v_exp_f32_e32 v209, v209
	v_exp_f32_e32 v210, v210
	v_exp_f32_e32 v211, v211
	v_add_f32_e32 v208, 1.0, v208
	v_add_f32_e32 v209, 1.0, v209
	v_add_f32_e32 v210, 1.0, v210
	v_add_f32_e32 v211, 1.0, v211
	v_rcp_f32_e32 v208, v208
	v_rcp_f32_e32 v209, v209
	v_rcp_f32_e32 v210, v210
	v_rcp_f32_e32 v211, v211
	v_mul_f32_e32 v200, v200, v208
	v_mul_f32_e32 v201, v201, v209
	v_mul_f32_e32 v202, v202, v210
	v_mul_f32_e32 v203, v203, v211
	v_mul_f32_e32 v200, v200, v204
	v_mul_f32_e32 v201, v201, v205
	v_mul_f32_e32 v202, v202, v206
	v_mul_f32_e32 v203, v203, v207
	v_cvt_pk_bf16_f32 v244, v200, v201
	v_cvt_pk_bf16_f32 v245, v202, v203
	v_fma_f32 v200, v132, v48, v140
	v_fma_f32 v201, v133, v49, v141
	v_fma_f32 v202, v134, v50, v142
	v_fma_f32 v203, v135, v51, v143
	v_fmac_f32_e32 v200, v60, v128
	v_fmac_f32_e32 v201, v61, v129
	v_fmac_f32_e32 v202, v62, v130
	v_fmac_f32_e32 v203, v63, v131
	v_fmac_f32_e32 v200, v32, v136
	v_fmac_f32_e32 v201, v33, v137
	v_fmac_f32_e32 v202, v34, v138
	v_fmac_f32_e32 v203, v35, v139
	v_fma_f32 v204, v172, v36, v180
	v_fma_f32 v205, v173, v37, v181
	v_fma_f32 v206, v174, v38, v182
	v_fma_f32 v207, v175, v39, v183
	v_fmac_f32_e32 v204, v52, v160
	v_fmac_f32_e32 v205, v53, v161
	v_fmac_f32_e32 v206, v54, v162
	v_fmac_f32_e32 v207, v55, v163
	v_fmac_f32_e32 v204, v20, v176
	v_fmac_f32_e32 v205, v21, v177
	v_fmac_f32_e32 v206, v22, v178
	v_fmac_f32_e32 v207, v23, v179
	v_mul_f32_e32 v208, 0xbfb8aa3b, v200
	v_mul_f32_e32 v209, 0xbfb8aa3b, v201
	v_mul_f32_e32 v210, 0xbfb8aa3b, v202
	v_mul_f32_e32 v211, 0xbfb8aa3b, v203
	v_exp_f32_e32 v208, v208
	v_exp_f32_e32 v209, v209
	v_exp_f32_e32 v210, v210
	v_exp_f32_e32 v211, v211
	v_add_f32_e32 v208, 1.0, v208
	v_add_f32_e32 v209, 1.0, v209
	v_add_f32_e32 v210, 1.0, v210
	v_add_f32_e32 v211, 1.0, v211
	v_rcp_f32_e32 v208, v208
	v_rcp_f32_e32 v209, v209
	v_rcp_f32_e32 v210, v210
	v_rcp_f32_e32 v211, v211
	v_mul_f32_e32 v200, v200, v208
	v_mul_f32_e32 v201, v201, v209
	v_mul_f32_e32 v202, v202, v210
	v_mul_f32_e32 v203, v203, v211
	v_mul_f32_e32 v200, v200, v204
	v_mul_f32_e32 v201, v201, v205
	v_mul_f32_e32 v202, v202, v206
	v_mul_f32_e32 v203, v203, v207
	v_cvt_pk_bf16_f32 v246, v200, v201
	v_cvt_pk_bf16_f32 v247, v202, v203
	v_fma_f32 v200, v132, v32, v140
	v_fma_f32 v201, v133, v33, v141
	v_fma_f32 v202, v134, v34, v142
	v_fma_f32 v203, v135, v35, v143
	v_fmac_f32_e32 v200, v48, v128
	v_fmac_f32_e32 v201, v49, v129
	v_fmac_f32_e32 v202, v50, v130
	v_fmac_f32_e32 v203, v51, v131
	v_fmac_f32_e32 v200, v16, v136
	v_fmac_f32_e32 v201, v17, v137
	v_fmac_f32_e32 v202, v18, v138
	v_fmac_f32_e32 v203, v19, v139
	v_fma_f32 v204, v172, v20, v180
	v_fma_f32 v205, v173, v21, v181
	v_fma_f32 v206, v174, v22, v182
	v_fma_f32 v207, v175, v23, v183
	v_fmac_f32_e32 v204, v36, v160
	v_fmac_f32_e32 v205, v37, v161
	v_fmac_f32_e32 v206, v38, v162
	v_fmac_f32_e32 v207, v39, v163
	v_fmac_f32_e32 v204, v4, v176
	v_fmac_f32_e32 v205, v5, v177
	v_fmac_f32_e32 v206, v6, v178
	v_fmac_f32_e32 v207, v7, v179
	v_mul_f32_e32 v208, 0xbfb8aa3b, v200
	v_mul_f32_e32 v209, 0xbfb8aa3b, v201
	v_mul_f32_e32 v210, 0xbfb8aa3b, v202
	v_mul_f32_e32 v211, 0xbfb8aa3b, v203
	v_exp_f32_e32 v208, v208
	v_exp_f32_e32 v209, v209
	v_exp_f32_e32 v210, v210
	v_exp_f32_e32 v211, v211
	v_add_f32_e32 v208, 1.0, v208
	v_add_f32_e32 v209, 1.0, v209
	v_add_f32_e32 v210, 1.0, v210
	v_add_f32_e32 v211, 1.0, v211
	v_rcp_f32_e32 v208, v208
	v_rcp_f32_e32 v209, v209
	v_rcp_f32_e32 v210, v210
	v_rcp_f32_e32 v211, v211
	v_mul_f32_e32 v200, v200, v208
	v_mul_f32_e32 v201, v201, v209
	v_mul_f32_e32 v202, v202, v210
	v_mul_f32_e32 v203, v203, v211
	v_mul_f32_e32 v200, v200, v204
	v_mul_f32_e32 v201, v201, v205
	v_mul_f32_e32 v202, v202, v206
	v_mul_f32_e32 v203, v203, v207
	v_cvt_pk_bf16_f32 v248, v200, v201
	v_cvt_pk_bf16_f32 v249, v202, v203
	v_fma_f32 v200, v132, v16, v140
	v_fma_f32 v201, v133, v17, v141
	v_fma_f32 v202, v134, v18, v142
	v_fma_f32 v203, v135, v19, v143
	v_fmac_f32_e32 v200, v32, v128
	v_fmac_f32_e32 v201, v33, v129
	v_fmac_f32_e32 v202, v34, v130
	v_fmac_f32_e32 v203, v35, v131
	v_fmac_f32_dpp v200, v60, v136 row_shl:1 row_mask:0xf bank_mask:0xf
	v_fmac_f32_dpp v201, v61, v137 row_shl:1 row_mask:0xf bank_mask:0xf
	v_fmac_f32_dpp v202, v62, v138 row_shl:1 row_mask:0xf bank_mask:0xf
	v_fmac_f32_dpp v203, v63, v139 row_shl:1 row_mask:0xf bank_mask:0xf
	v_fmac_f32_e32 v200, v192, v220
	v_fmac_f32_e32 v201, v193, v221
	v_fmac_f32_e32 v202, v194, v222
	v_fmac_f32_e32 v203, v195, v223
	v_fma_f32 v204, v172, v4, v180
	v_fma_f32 v205, v173, v5, v181
	v_fma_f32 v206, v174, v6, v182
	v_fma_f32 v207, v175, v7, v183
	v_fmac_f32_e32 v204, v20, v160
	v_fmac_f32_e32 v205, v21, v161
	v_fmac_f32_e32 v206, v22, v162
	v_fmac_f32_e32 v207, v23, v163
	v_fmac_f32_dpp v204, v52, v176 row_shl:1 row_mask:0xf bank_mask:0xf
	v_fmac_f32_dpp v205, v53, v177 row_shl:1 row_mask:0xf bank_mask:0xf
	v_fmac_f32_dpp v206, v54, v178 row_shl:1 row_mask:0xf bank_mask:0xf
	v_fmac_f32_dpp v207, v55, v179 row_shl:1 row_mask:0xf bank_mask:0xf
	v_fmac_f32_e32 v204, v196, v232
	v_fmac_f32_e32 v205, v197, v233
	v_fmac_f32_e32 v206, v198, v234
	v_fmac_f32_e32 v207, v199, v235
	s_mov_b64 exec, s[62:63]
	v_add_u32_e32 v250, 0x10800, v229
	global_store_dwordx4 v250, v[200:203], s[64:65]
	v_add_u32_e32 v250, 0x13400, v229
	global_store_dwordx4 v250, v[204:207], s[64:65]
	s_mov_b64 exec, s[58:59]
	s_nop 4
	v_mul_f32_e32 v208, 0xbfb8aa3b, v200
	v_mul_f32_e32 v209, 0xbfb8aa3b, v201
	v_mul_f32_e32 v210, 0xbfb8aa3b, v202
	v_mul_f32_e32 v211, 0xbfb8aa3b, v203
	v_exp_f32_e32 v208, v208
	v_exp_f32_e32 v209, v209
	v_exp_f32_e32 v210, v210
	v_exp_f32_e32 v211, v211
	v_add_f32_e32 v208, 1.0, v208
	v_add_f32_e32 v209, 1.0, v209
	v_add_f32_e32 v210, 1.0, v210
	v_add_f32_e32 v211, 1.0, v211
	v_rcp_f32_e32 v208, v208
	v_rcp_f32_e32 v209, v209
	v_rcp_f32_e32 v210, v210
	v_rcp_f32_e32 v211, v211
	v_mul_f32_e32 v200, v200, v208
	v_mul_f32_e32 v201, v201, v209
	v_mul_f32_e32 v202, v202, v210
	v_mul_f32_e32 v203, v203, v211
	v_mul_f32_e32 v200, v200, v204
	v_mul_f32_e32 v201, v201, v205
	v_mul_f32_e32 v202, v202, v206
	v_mul_f32_e32 v203, v203, v207
	v_cvt_pk_bf16_f32 v250, v200, v201
	v_cvt_pk_bf16_f32 v251, v202, v203
	global_load_dwordx4 v[128:131], v229, s[34:35] offset:16
	v_add_u32_e32 v211, 0x5800, v229
	global_load_dwordx4 v[132:135], v211, s[34:35] offset:16
	v_add_u32_e32 v210, 0xb000, v229
	global_load_dwordx4 v[136:139], v210, s[34:35] offset:16
	global_load_dwordx4 v[140:143], v229, s[36:37] offset:16
	v_add_u32_e32 v210, 0x2c00, v229
	global_load_dwordx4 v[160:163], v210, s[34:35] offset:16
	v_add_u32_e32 v211, 0x8400, v229
	global_load_dwordx4 v[172:175], v211, s[34:35] offset:16
	v_add_u32_e32 v210, 0xdc00, v229
	global_load_dwordx4 v[176:179], v210, s[34:35] offset:16
	v_add_u32_e32 v211, 0x2c00, v229
	global_load_dwordx4 v[180:183], v211, s[36:37] offset:16
	v_mov_b32_e32 v124, v236
	v_mov_b32_e32 v125, v237
	v_mov_b32_e32 v116, v238
	v_mov_b32_e32 v117, v239
	v_mov_b32_e32 v96, v240
	v_mov_b32_e32 v97, v241
	v_mov_b32_e32 v80, v242
	v_mov_b32_e32 v81, v243
	v_mov_b32_e32 v60, v244
	v_mov_b32_e32 v61, v245
	v_mov_b32_e32 v48, v246
	v_mov_b32_e32 v49, v247
	v_mov_b32_e32 v32, v248
	v_mov_b32_e32 v33, v249
	v_mov_b32_e32 v16, v250
	v_mov_b32_e32 v17, v251
	ds_read_b128 v[184:187], v231 offset:16
	ds_read_b128 v[188:191], v231 offset:528
	ds_read_b128 v[192:195], v231 offset:2064
	ds_read_b128 v[196:199], v231 offset:2576
	s_waitcnt vmcnt(0)
	v_cndmask_b32_e64 v216, 0, v128, s[54:55]
	v_cndmask_b32_e64 v220, 0, v136, s[56:57]
	v_cndmask_b32_e64 v217, 0, v129, s[54:55]
	v_cndmask_b32_e64 v221, 0, v137, s[56:57]
	v_cndmask_b32_e64 v218, 0, v130, s[54:55]
	v_cndmask_b32_e64 v222, 0, v138, s[56:57]
	v_cndmask_b32_e64 v219, 0, v131, s[54:55]
	v_cndmask_b32_e64 v223, 0, v139, s[56:57]
	v_cndmask_b32_e64 v224, 0, v160, s[54:55]
	v_cndmask_b32_e64 v232, 0, v176, s[56:57]
	v_cndmask_b32_e64 v225, 0, v161, s[54:55]
	v_cndmask_b32_e64 v233, 0, v177, s[56:57]
	v_cndmask_b32_e64 v226, 0, v162, s[54:55]
	v_cndmask_b32_e64 v234, 0, v178, s[56:57]
	v_cndmask_b32_e64 v227, 0, v163, s[54:55]
	v_cndmask_b32_e64 v235, 0, v179, s[56:57]
	s_waitcnt lgkmcnt(0)
	s_nop 1
	v_fma_f32 v200, v132, v120, v140
	v_fma_f32 v201, v133, v121, v141
	v_fma_f32 v202, v134, v122, v142
	v_fma_f32 v203, v135, v123, v143
	v_fmac_f32_dpp v200, v72, v128 row_shr:1 row_mask:0xf bank_mask:0xf
	v_fmac_f32_dpp v201, v73, v129 row_shr:1 row_mask:0xf bank_mask:0xf
	v_fmac_f32_dpp v202, v74, v130 row_shr:1 row_mask:0xf bank_mask:0xf
	v_fmac_f32_dpp v203, v75, v131 row_shr:1 row_mask:0xf bank_mask:0xf
	v_fmac_f32_e32 v200, v184, v216
	v_fmac_f32_e32 v201, v185, v217
	v_fmac_f32_e32 v202, v186, v218
	v_fmac_f32_e32 v203, v187, v219
	v_fmac_f32_e32 v200, v112, v136
	v_fmac_f32_e32 v201, v113, v137
	v_fmac_f32_e32 v202, v114, v138
	v_fmac_f32_e32 v203, v115, v139
	v_fma_f32 v204, v172, v104, v180
	v_fma_f32 v205, v173, v105, v181
	v_fma_f32 v206, v174, v106, v182
	v_fma_f32 v207, v175, v107, v183
	v_fmac_f32_dpp v204, v64, v160 row_shr:1 row_mask:0xf bank_mask:0xf
	v_fmac_f32_dpp v205, v65, v161 row_shr:1 row_mask:0xf bank_mask:0xf
	v_fmac_f32_dpp v206, v66, v162 row_shr:1 row_mask:0xf bank_mask:0xf
	v_fmac_f32_dpp v207, v67, v163 row_shr:1 row_mask:0xf bank_mask:0xf
	v_fmac_f32_e32 v204, v188, v224
	v_fmac_f32_e32 v205, v189, v225
	v_fmac_f32_e32 v206, v190, v226
	v_fmac_f32_e32 v207, v191, v227
	v_fmac_f32_e32 v204, v92, v176
	v_fmac_f32_e32 v205, v93, v177
	v_fmac_f32_e32 v206, v94, v178
	v_fmac_f32_e32 v207, v95, v179
	s_mov_b64 exec, s[60:61]
	v_add_u32_e32 v250, 0x5800, v229
	global_store_dwordx4 v250, v[200:203], s[64:65] offset:16
	v_add_u32_e32 v250, 0x8400, v229
	global_store_dwordx4 v250, v[204:207], s[64:65] offset:16
	s_mov_b64 exec, s[58:59]
	s_nop 4
	v_mul_f32_e32 v208, 0xbfb8aa3b, v200
	v_mul_f32_e32 v209, 0xbfb8aa3b, v201
	v_mul_f32_e32 v210, 0xbfb8aa3b, v202
	v_mul_f32_e32 v211, 0xbfb8aa3b, v203
	v_exp_f32_e32 v208, v208
	v_exp_f32_e32 v209, v209
	v_exp_f32_e32 v210, v210
	v_exp_f32_e32 v211, v211
	v_add_f32_e32 v208, 1.0, v208
	v_add_f32_e32 v209, 1.0, v209
	v_add_f32_e32 v210, 1.0, v210
	v_add_f32_e32 v211, 1.0, v211
	v_rcp_f32_e32 v208, v208
	v_rcp_f32_e32 v209, v209
	v_rcp_f32_e32 v210, v210
	v_rcp_f32_e32 v211, v211
	v_mul_f32_e32 v200, v200, v208
	v_mul_f32_e32 v201, v201, v209
	v_mul_f32_e32 v202, v202, v210
	v_mul_f32_e32 v203, v203, v211
	v_mul_f32_e32 v200, v200, v204
	v_mul_f32_e32 v201, v201, v205
	v_mul_f32_e32 v202, v202, v206
	v_mul_f32_e32 v203, v203, v207
	v_cvt_pk_bf16_f32 v126, v200, v201
	v_cvt_pk_bf16_f32 v127, v202, v203
	v_fma_f32 v200, v132, v112, v140
	v_fma_f32 v201, v133, v113, v141
	v_fma_f32 v202, v134, v114, v142
	v_fma_f32 v203, v135, v115, v143
	v_fmac_f32_e32 v200, v120, v128
	v_fmac_f32_e32 v201, v121, v129
	v_fmac_f32_e32 v202, v122, v130
	v_fmac_f32_e32 v203, v123, v131
	v_fmac_f32_e32 v200, v88, v136
	v_fmac_f32_e32 v201, v89, v137
	v_fmac_f32_e32 v202, v90, v138
	v_fmac_f32_e32 v203, v91, v139
	v_fma_f32 v204, v172, v92, v180
	v_fma_f32 v205, v173, v93, v181
	v_fma_f32 v206, v174, v94, v182
	v_fma_f32 v207, v175, v95, v183
	v_fmac_f32_e32 v204, v104, v160
	v_fmac_f32_e32 v205, v105, v161
	v_fmac_f32_e32 v206, v106, v162
	v_fmac_f32_e32 v207, v107, v163
	v_fmac_f32_e32 v204, v76, v176
	v_fmac_f32_e32 v205, v77, v177
	v_fmac_f32_e32 v206, v78, v178
	v_fmac_f32_e32 v207, v79, v179
	v_mul_f32_e32 v208, 0xbfb8aa3b, v200
	v_mul_f32_e32 v209, 0xbfb8aa3b, v201
	v_mul_f32_e32 v210, 0xbfb8aa3b, v202
	v_mul_f32_e32 v211, 0xbfb8aa3b, v203
	v_exp_f32_e32 v208, v208
	v_exp_f32_e32 v209, v209
	v_exp_f32_e32 v210, v210
	v_exp_f32_e32 v211, v211
	v_add_f32_e32 v208, 1.0, v208
	v_add_f32_e32 v209, 1.0, v209
	v_add_f32_e32 v210, 1.0, v210
	v_add_f32_e32 v211, 1.0, v211
	v_rcp_f32_e32 v208, v208
	v_rcp_f32_e32 v209, v209
	v_rcp_f32_e32 v210, v210
	v_rcp_f32_e32 v211, v211
	v_mul_f32_e32 v200, v200, v208
	v_mul_f32_e32 v201, v201, v209
	v_mul_f32_e32 v202, v202, v210
	v_mul_f32_e32 v203, v203, v211
	v_mul_f32_e32 v200, v200, v204
	v_mul_f32_e32 v201, v201, v205
	v_mul_f32_e32 v202, v202, v206
	v_mul_f32_e32 v203, v203, v207
	v_cvt_pk_bf16_f32 v118, v200, v201
	v_cvt_pk_bf16_f32 v119, v202, v203
	v_fma_f32 v200, v132, v88, v140
	v_fma_f32 v201, v133, v89, v141
	v_fma_f32 v202, v134, v90, v142
	v_fma_f32 v203, v135, v91, v143
	v_fmac_f32_e32 v200, v112, v128
	v_fmac_f32_e32 v201, v113, v129
	v_fmac_f32_e32 v202, v114, v130
	v_fmac_f32_e32 v203, v115, v131
	v_fmac_f32_e32 v200, v72, v136
	v_fmac_f32_e32 v201, v73, v137
	v_fmac_f32_e32 v202, v74, v138
	v_fmac_f32_e32 v203, v75, v139
	v_fma_f32 v204, v172, v76, v180
	v_fma_f32 v205, v173, v77, v181
	v_fma_f32 v206, v174, v78, v182
	v_fma_f32 v207, v175, v79, v183
	v_fmac_f32_e32 v204, v92, v160
	v_fmac_f32_e32 v205, v93, v161
	v_fmac_f32_e32 v206, v94, v162
	v_fmac_f32_e32 v207, v95, v163
	v_fmac_f32_e32 v204, v64, v176
	v_fmac_f32_e32 v205, v65, v177
	v_fmac_f32_e32 v206, v66, v178
	v_fmac_f32_e32 v207, v67, v179
	v_mul_f32_e32 v208, 0xbfb8aa3b, v200
	v_mul_f32_e32 v209, 0xbfb8aa3b, v201
	v_mul_f32_e32 v210, 0xbfb8aa3b, v202
	v_mul_f32_e32 v211, 0xbfb8aa3b, v203
	v_exp_f32_e32 v208, v208
	v_exp_f32_e32 v209, v209
	v_exp_f32_e32 v210, v210
	v_exp_f32_e32 v211, v211
	v_add_f32_e32 v208, 1.0, v208
	v_add_f32_e32 v209, 1.0, v209
	v_add_f32_e32 v210, 1.0, v210
	v_add_f32_e32 v211, 1.0, v211
	v_rcp_f32_e32 v208, v208
	v_rcp_f32_e32 v209, v209
	v_rcp_f32_e32 v210, v210
	v_rcp_f32_e32 v211, v211
	v_mul_f32_e32 v200, v200, v208
	v_mul_f32_e32 v201, v201, v209
	v_mul_f32_e32 v202, v202, v210
	v_mul_f32_e32 v203, v203, v211
	v_mul_f32_e32 v200, v200, v204
	v_mul_f32_e32 v201, v201, v205
	v_mul_f32_e32 v202, v202, v206
	v_mul_f32_e32 v203, v203, v207
	v_cvt_pk_bf16_f32 v98, v200, v201
	v_cvt_pk_bf16_f32 v99, v202, v203
	v_fma_f32 v200, v132, v72, v140
	v_fma_f32 v201, v133, v73, v141
	v_fma_f32 v202, v134, v74, v142
	v_fma_f32 v203, v135, v75, v143
	v_fmac_f32_e32 v200, v88, v128
	v_fmac_f32_e32 v201, v89, v129
	v_fmac_f32_e32 v202, v90, v130
	v_fmac_f32_e32 v203, v91, v131
	v_fmac_f32_dpp v200, v120, v136 row_shl:1 row_mask:0xf bank_mask:0xf
	v_fmac_f32_dpp v201, v121, v137 row_shl:1 row_mask:0xf bank_mask:0xf
	v_fmac_f32_dpp v202, v122, v138 row_shl:1 row_mask:0xf bank_mask:0xf
	v_fmac_f32_dpp v203, v123, v139 row_shl:1 row_mask:0xf bank_mask:0xf
	v_fmac_f32_e32 v200, v184, v220
	v_fmac_f32_e32 v201, v185, v221
	v_fmac_f32_e32 v202, v186, v222
	v_fmac_f32_e32 v203, v187, v223
	v_fma_f32 v204, v172, v64, v180
	v_fma_f32 v205, v173, v65, v181
	v_fma_f32 v206, v174, v66, v182
	v_fma_f32 v207, v175, v67, v183
	v_fmac_f32_e32 v204, v76, v160
	v_fmac_f32_e32 v205, v77, v161
	v_fmac_f32_e32 v206, v78, v162
	v_fmac_f32_e32 v207, v79, v163
	v_fmac_f32_dpp v204, v104, v176 row_shl:1 row_mask:0xf bank_mask:0xf
	v_fmac_f32_dpp v205, v105, v177 row_shl:1 row_mask:0xf bank_mask:0xf
	v_fmac_f32_dpp v206, v106, v178 row_shl:1 row_mask:0xf bank_mask:0xf
	v_fmac_f32_dpp v207, v107, v179 row_shl:1 row_mask:0xf bank_mask:0xf
	v_fmac_f32_e32 v204, v188, v232
	v_fmac_f32_e32 v205, v189, v233
	v_fmac_f32_e32 v206, v190, v234
	v_fmac_f32_e32 v207, v191, v235
	v_mul_f32_e32 v208, 0xbfb8aa3b, v200
	v_mul_f32_e32 v209, 0xbfb8aa3b, v201
	v_mul_f32_e32 v210, 0xbfb8aa3b, v202
	v_mul_f32_e32 v211, 0xbfb8aa3b, v203
	v_exp_f32_e32 v208, v208
	v_exp_f32_e32 v209, v209
	v_exp_f32_e32 v210, v210
	v_exp_f32_e32 v211, v211
	v_add_f32_e32 v208, 1.0, v208
	v_add_f32_e32 v209, 1.0, v209
	v_add_f32_e32 v210, 1.0, v210
	v_add_f32_e32 v211, 1.0, v211
	v_rcp_f32_e32 v208, v208
	v_rcp_f32_e32 v209, v209
	v_rcp_f32_e32 v210, v210
	v_rcp_f32_e32 v211, v211
	v_mul_f32_e32 v200, v200, v208
	v_mul_f32_e32 v201, v201, v209
	v_mul_f32_e32 v202, v202, v210
	v_mul_f32_e32 v203, v203, v211
	v_mul_f32_e32 v200, v200, v204
	v_mul_f32_e32 v201, v201, v205
	v_mul_f32_e32 v202, v202, v206
	v_mul_f32_e32 v203, v203, v207
	v_cvt_pk_bf16_f32 v82, v200, v201
	v_cvt_pk_bf16_f32 v83, v202, v203
	v_fma_f32 v200, v132, v56, v140
	v_fma_f32 v201, v133, v57, v141
	v_fma_f32 v202, v134, v58, v142
	v_fma_f32 v203, v135, v59, v143
	v_fmac_f32_dpp v200, v8, v128 row_shr:1 row_mask:0xf bank_mask:0xf
	v_fmac_f32_dpp v201, v9, v129 row_shr:1 row_mask:0xf bank_mask:0xf
	v_fmac_f32_dpp v202, v10, v130 row_shr:1 row_mask:0xf bank_mask:0xf
	v_fmac_f32_dpp v203, v11, v131 row_shr:1 row_mask:0xf bank_mask:0xf
	v_fmac_f32_e32 v200, v192, v216
	v_fmac_f32_e32 v201, v193, v217
	v_fmac_f32_e32 v202, v194, v218
	v_fmac_f32_e32 v203, v195, v219
	v_fmac_f32_e32 v200, v40, v136
	v_fmac_f32_e32 v201, v41, v137
	v_fmac_f32_e32 v202, v42, v138
	v_fmac_f32_e32 v203, v43, v139
	v_fma_f32 v204, v172, v44, v180
	v_fma_f32 v205, v173, v45, v181
	v_fma_f32 v206, v174, v46, v182
	v_fma_f32 v207, v175, v47, v183
	v_fmac_f32_dpp v204, v0, v160 row_shr:1 row_mask:0xf bank_mask:0xf
	v_fmac_f32_dpp v205, v1, v161 row_shr:1 row_mask:0xf bank_mask:0xf
	v_fmac_f32_dpp v206, v2, v162 row_shr:1 row_mask:0xf bank_mask:0xf
	v_fmac_f32_dpp v207, v3, v163 row_shr:1 row_mask:0xf bank_mask:0xf
	v_fmac_f32_e32 v204, v196, v224
	v_fmac_f32_e32 v205, v197, v225
	v_fmac_f32_e32 v206, v198, v226
	v_fmac_f32_e32 v207, v199, v227
	v_fmac_f32_e32 v204, v28, v176
	v_fmac_f32_e32 v205, v29, v177
	v_fmac_f32_e32 v206, v30, v178
	v_fmac_f32_e32 v207, v31, v179
	v_mul_f32_e32 v208, 0xbfb8aa3b, v200
	v_mul_f32_e32 v209, 0xbfb8aa3b, v201
	v_mul_f32_e32 v210, 0xbfb8aa3b, v202
	v_mul_f32_e32 v211, 0xbfb8aa3b, v203
	v_exp_f32_e32 v208, v208
	v_exp_f32_e32 v209, v209
	v_exp_f32_e32 v210, v210
	v_exp_f32_e32 v211, v211
	v_add_f32_e32 v208, 1.0, v208
	v_add_f32_e32 v209, 1.0, v209
	v_add_f32_e32 v210, 1.0, v210
	v_add_f32_e32 v211, 1.0, v211
	v_rcp_f32_e32 v208, v208
	v_rcp_f32_e32 v209, v209
	v_rcp_f32_e32 v210, v210
	v_rcp_f32_e32 v211, v211
	v_mul_f32_e32 v200, v200, v208
	v_mul_f32_e32 v201, v201, v209
	v_mul_f32_e32 v202, v202, v210
	v_mul_f32_e32 v203, v203, v211
	v_mul_f32_e32 v200, v200, v204
	v_mul_f32_e32 v201, v201, v205
	v_mul_f32_e32 v202, v202, v206
	v_mul_f32_e32 v203, v203, v207
	v_cvt_pk_bf16_f32 v62, v200, v201
	v_cvt_pk_bf16_f32 v63, v202, v203
	v_fma_f32 v200, v132, v40, v140
	v_fma_f32 v201, v133, v41, v141
	v_fma_f32 v202, v134, v42, v142
	v_fma_f32 v203, v135, v43, v143
	v_fmac_f32_e32 v200, v56, v128
	v_fmac_f32_e32 v201, v57, v129
	v_fmac_f32_e32 v202, v58, v130
	v_fmac_f32_e32 v203, v59, v131
	v_fmac_f32_e32 v200, v24, v136
	v_fmac_f32_e32 v201, v25, v137
	v_fmac_f32_e32 v202, v26, v138
	v_fmac_f32_e32 v203, v27, v139
	v_fma_f32 v204, v172, v28, v180
	v_fma_f32 v205, v173, v29, v181
	v_fma_f32 v206, v174, v30, v182
	v_fma_f32 v207, v175, v31, v183
	v_fmac_f32_e32 v204, v44, v160
	v_fmac_f32_e32 v205, v45, v161
	v_fmac_f32_e32 v206, v46, v162
	v_fmac_f32_e32 v207, v47, v163
	v_fmac_f32_e32 v204, v12, v176
	v_fmac_f32_e32 v205, v13, v177
	v_fmac_f32_e32 v206, v14, v178
	v_fmac_f32_e32 v207, v15, v179
	v_mul_f32_e32 v208, 0xbfb8aa3b, v200
	v_mul_f32_e32 v209, 0xbfb8aa3b, v201
	v_mul_f32_e32 v210, 0xbfb8aa3b, v202
	v_mul_f32_e32 v211, 0xbfb8aa3b, v203
	v_exp_f32_e32 v208, v208
	v_exp_f32_e32 v209, v209
	v_exp_f32_e32 v210, v210
	v_exp_f32_e32 v211, v211
	v_add_f32_e32 v208, 1.0, v208
	v_add_f32_e32 v209, 1.0, v209
	v_add_f32_e32 v210, 1.0, v210
	v_add_f32_e32 v211, 1.0, v211
	v_rcp_f32_e32 v208, v208
	v_rcp_f32_e32 v209, v209
	v_rcp_f32_e32 v210, v210
	v_rcp_f32_e32 v211, v211
	v_mul_f32_e32 v200, v200, v208
	v_mul_f32_e32 v201, v201, v209
	v_mul_f32_e32 v202, v202, v210
	v_mul_f32_e32 v203, v203, v211
	v_mul_f32_e32 v200, v200, v204
	v_mul_f32_e32 v201, v201, v205
	v_mul_f32_e32 v202, v202, v206
	v_mul_f32_e32 v203, v203, v207
	v_cvt_pk_bf16_f32 v50, v200, v201
	v_cvt_pk_bf16_f32 v51, v202, v203
	v_fma_f32 v200, v132, v24, v140
	v_fma_f32 v201, v133, v25, v141
	v_fma_f32 v202, v134, v26, v142
	v_fma_f32 v203, v135, v27, v143
	v_fmac_f32_e32 v200, v40, v128
	v_fmac_f32_e32 v201, v41, v129
	v_fmac_f32_e32 v202, v42, v130
	v_fmac_f32_e32 v203, v43, v131
	v_fmac_f32_e32 v200, v8, v136
	v_fmac_f32_e32 v201, v9, v137
	v_fmac_f32_e32 v202, v10, v138
	v_fmac_f32_e32 v203, v11, v139
	v_fma_f32 v204, v172, v12, v180
	v_fma_f32 v205, v173, v13, v181
	v_fma_f32 v206, v174, v14, v182
	v_fma_f32 v207, v175, v15, v183
	v_fmac_f32_e32 v204, v28, v160
	v_fmac_f32_e32 v205, v29, v161
	v_fmac_f32_e32 v206, v30, v162
	v_fmac_f32_e32 v207, v31, v163
	v_fmac_f32_e32 v204, v0, v176
	v_fmac_f32_e32 v205, v1, v177
	v_fmac_f32_e32 v206, v2, v178
	v_fmac_f32_e32 v207, v3, v179
	v_mul_f32_e32 v208, 0xbfb8aa3b, v200
	v_mul_f32_e32 v209, 0xbfb8aa3b, v201
	v_mul_f32_e32 v210, 0xbfb8aa3b, v202
	v_mul_f32_e32 v211, 0xbfb8aa3b, v203
	v_exp_f32_e32 v208, v208
	v_exp_f32_e32 v209, v209
	v_exp_f32_e32 v210, v210
	v_exp_f32_e32 v211, v211
	v_add_f32_e32 v208, 1.0, v208
	v_add_f32_e32 v209, 1.0, v209
	v_add_f32_e32 v210, 1.0, v210
	v_add_f32_e32 v211, 1.0, v211
	v_rcp_f32_e32 v208, v208
	v_rcp_f32_e32 v209, v209
	v_rcp_f32_e32 v210, v210
	v_rcp_f32_e32 v211, v211
	v_mul_f32_e32 v200, v200, v208
	v_mul_f32_e32 v201, v201, v209
	v_mul_f32_e32 v202, v202, v210
	v_mul_f32_e32 v203, v203, v211
	v_mul_f32_e32 v200, v200, v204
	v_mul_f32_e32 v201, v201, v205
	v_mul_f32_e32 v202, v202, v206
	v_mul_f32_e32 v203, v203, v207
	v_cvt_pk_bf16_f32 v34, v200, v201
	v_cvt_pk_bf16_f32 v35, v202, v203
	v_fma_f32 v200, v132, v8, v140
	v_fma_f32 v201, v133, v9, v141
	v_fma_f32 v202, v134, v10, v142
	v_fma_f32 v203, v135, v11, v143
	v_fmac_f32_e32 v200, v24, v128
	v_fmac_f32_e32 v201, v25, v129
	v_fmac_f32_e32 v202, v26, v130
	v_fmac_f32_e32 v203, v27, v131
	v_fmac_f32_dpp v200, v56, v136 row_shl:1 row_mask:0xf bank_mask:0xf
	v_fmac_f32_dpp v201, v57, v137 row_shl:1 row_mask:0xf bank_mask:0xf
	v_fmac_f32_dpp v202, v58, v138 row_shl:1 row_mask:0xf bank_mask:0xf
	v_fmac_f32_dpp v203, v59, v139 row_shl:1 row_mask:0xf bank_mask:0xf
	v_fmac_f32_e32 v200, v192, v220
	v_fmac_f32_e32 v201, v193, v221
	v_fmac_f32_e32 v202, v194, v222
	v_fmac_f32_e32 v203, v195, v223
	v_fma_f32 v204, v172, v0, v180
	v_fma_f32 v205, v173, v1, v181
	v_fma_f32 v206, v174, v2, v182
	v_fma_f32 v207, v175, v3, v183
	v_fmac_f32_e32 v204, v12, v160
	v_fmac_f32_e32 v205, v13, v161
	v_fmac_f32_e32 v206, v14, v162
	v_fmac_f32_e32 v207, v15, v163
	v_fmac_f32_dpp v204, v44, v176 row_shl:1 row_mask:0xf bank_mask:0xf
	v_fmac_f32_dpp v205, v45, v177 row_shl:1 row_mask:0xf bank_mask:0xf
	v_fmac_f32_dpp v206, v46, v178 row_shl:1 row_mask:0xf bank_mask:0xf
	v_fmac_f32_dpp v207, v47, v179 row_shl:1 row_mask:0xf bank_mask:0xf
	v_fmac_f32_e32 v204, v196, v232
	v_fmac_f32_e32 v205, v197, v233
	v_fmac_f32_e32 v206, v198, v234
	v_fmac_f32_e32 v207, v199, v235
	s_mov_b64 exec, s[62:63]
	v_add_u32_e32 v250, 0x10800, v229
	global_store_dwordx4 v250, v[200:203], s[64:65] offset:16
	v_add_u32_e32 v250, 0x13400, v229
	global_store_dwordx4 v250, v[204:207], s[64:65] offset:16
	s_mov_b64 exec, s[58:59]
	s_nop 4
	v_mul_f32_e32 v208, 0xbfb8aa3b, v200
	v_mul_f32_e32 v209, 0xbfb8aa3b, v201
	v_mul_f32_e32 v210, 0xbfb8aa3b, v202
	v_mul_f32_e32 v211, 0xbfb8aa3b, v203
	v_exp_f32_e32 v208, v208
	v_exp_f32_e32 v209, v209
	v_exp_f32_e32 v210, v210
	v_exp_f32_e32 v211, v211
	v_add_f32_e32 v208, 1.0, v208
	v_add_f32_e32 v209, 1.0, v209
	v_add_f32_e32 v210, 1.0, v210
	v_add_f32_e32 v211, 1.0, v211
	v_rcp_f32_e32 v208, v208
	v_rcp_f32_e32 v209, v209
	v_rcp_f32_e32 v210, v210
	v_rcp_f32_e32 v211, v211
	v_mul_f32_e32 v200, v200, v208
	v_mul_f32_e32 v201, v201, v209
	v_mul_f32_e32 v202, v202, v210
	v_mul_f32_e32 v203, v203, v211
	v_mul_f32_e32 v200, v200, v204
	v_mul_f32_e32 v201, v201, v205
	v_mul_f32_e32 v202, v202, v206
	v_mul_f32_e32 v203, v203, v207
	v_cvt_pk_bf16_f32 v18, v200, v201
	v_cvt_pk_bf16_f32 v19, v202, v203
	global_store_dwordx4 v171, v[124:127], s[52:53]
	v_add_u32_e32 v250, 0x1600, v171
	global_store_dwordx4 v250, v[116:119], s[52:53]
	s_nop 0
	v_add_u32_e32 v250, 0x2c00, v171
	global_store_dwordx4 v250, v[96:99], s[52:53]
	s_nop 0
	v_add_u32_e32 v250, 0x4200, v171
	global_store_dwordx4 v250, v[80:83], s[52:53]
	s_nop 0
	v_add_u32_e32 v250, 0xb0000, v171
	global_store_dwordx4 v250, v[60:63], s[52:53]
	s_nop 0
	v_add_u32_e32 v250, 0xb1600, v171
	global_store_dwordx4 v250, v[48:51], s[52:53]
	s_nop 0
	v_add_u32_e32 v250, 0xb2c00, v171
	global_store_dwordx4 v250, v[32:35], s[52:53]
	s_nop 0
	v_add_u32_e32 v250, 0xb4200, v171
	global_store_dwordx4 v250, v[16:19], s[52:53]
	s_nop 0
	s_mov_b64 s[6:7], -1
	s_and_b64 vcc, exec, s[4:5]
	s_cbranch_vccz .LBB0_1873
	s_andn2_b64 vcc, exec, s[8:9]
	s_cbranch_vccnz .LBB0_1872
	s_barrier
	s_branch .LBB0_1872
